# speedup vs baseline: 1.0096x; 1.0018x over previous
;   #define LDA(dst,b,h) for(int m=0;m<4;++m)for(int k=0;k<2;++k) \
;     dst[m][k]=*reinterpret_cast<const bf16x8*>((char*)SA(b,h)+lds_byte(wr*64+m*16+fr,k*32+fq*8))
;   #define LDB(dst,b,h) for(int n=0;n<2;++n)for(int k=0;k<2;++k) \
;     dst[n][k]=*reinterpret_cast<const bf16x8*>((char*)SB(b,h)+lds_byte(wc*32+n*16+fr,k*32+fq*8))
;   #define MMA(ai,bj,At,Bt_) do{__builtin_amdgcn_s_setprio(1); \
;     for(int m=0;m<4;++m)for(int n=0;n<2;++n)for(int k=0;k<2;++k) \
;       acc[ai][bj][m][n]=__builtin_amdgcn_mfma_f32_16x16x32_bf16(Bt_[n][k],At[m][k],acc[ai][bj][m][n],0,0,0); \
;     __builtin_amdgcn_s_setprio(0);}while(0)
;   #define WAIT_V(n) asm volatile("s_waitcnt vmcnt(" #n ")":::"memory")
;   #define WAIT_L(n) asm volatile("s_waitcnt lgkmcnt(" #n ")":::"memory")
;   #define BAR __builtin_amdgcn_s_barrier()
;   #define SCHED __builtin_amdgcn_sched_barrier(0)
; template <bool TWO, class MID> ...
;     ...
;   for(int t=0;t<nt-2;t+=2){
;     if (TWO && t == nt1) mid();
;     LDB(B0,0,0); SCHED; LDA(At,0,0); STAGE_A(SA(1,1),1,t+1);
;     WAIT_L(8); BAR; WAIT_L(0); MMA(0,0,At,B0); BAR; SCHED;
;     LDB(B1,0,1); STAGE_B(SB(0,0),0,t+2);
;     BAR; WAIT_L(0); MMA(0,1,At,B1); BAR;
;     LDA(At,0,1); STAGE_A(SA(0,0),0,t+2);
;     BAR; WAIT_L(0); MMA(1,0,At,B0); BAR; SCHED;
;     STAGE_B(SB(0,1),1,t+2);
;     WAIT_V(6); BAR; MMA(1,1,At,B1); BAR;
;     LDB(B0,1,0); SCHED; LDA(At,1,0); STAGE_A(SA(0,1),1,t+2);
;     WAIT_L(8); BAR; WAIT_L(0); MMA(0,0,At,B0); BAR; SCHED;
.LBB0_169:
	ds_read_b128 v[170:173], v143
	ds_read_b128 v[174:177], v143 offset:1024
	ds_read_b128 v[178:181], v143 offset:2048
	ds_read_b128 v[182:185], v143 offset:3072
	ds_read_b128 v[186:189], v168
	ds_read_b128 v[190:193], v168 offset:1024
	ds_read_b128 v[196:199], v167
	ds_read_b128 v[200:203], v167 offset:1024
	ds_read_b128 v[204:207], v166
	ds_read_b128 v[208:211], v166 offset:1024
	ds_read_b128 v[212:215], v147
	ds_read_b128 v[216:219], v147 offset:1024
	s_add_u32 s17, s0, s12
	s_addc_u32 s18, s1, s13
	s_add_u32 s20, s17, 0x8080080
	s_addc_u32 s21, s18, 0
	v_lshl_add_u64 v[220:221], s[20:21], 0, v[132:133]
	v_readfirstlane_b32 s19, v148
	s_mov_b32 m0, s19
	global_load_lds_dwordx4 v[220:221], off
	v_lshl_add_u64 v[220:221], s[20:21], 0, v[130:131]
	v_readfirstlane_b32 s19, v156
	s_mov_b32 m0, s19
	global_load_lds_dwordx4 v[220:221], off
	s_waitcnt lgkmcnt(8)
	s_setprio 1
	s_barrier
	s_waitcnt lgkmcnt(0)
	v_mfma_f32_16x16x32_bf16 v[126:129], v[170:173], v[186:189], v[126:129]
	v_mfma_f32_16x16x32_bf16 v[122:125], v[178:181], v[186:189], v[122:125]
	v_mfma_f32_16x16x32_bf16 v[118:121], v[170:173], v[196:199], v[118:121]
	v_mfma_f32_16x16x32_bf16 v[114:117], v[178:181], v[196:199], v[114:117]
	v_mfma_f32_16x16x32_bf16 v[110:113], v[170:173], v[204:207], v[110:113]
	v_mfma_f32_16x16x32_bf16 v[106:109], v[178:181], v[204:207], v[106:109]
	v_mfma_f32_16x16x32_bf16 v[102:105], v[170:173], v[212:215], v[102:105]
	v_mfma_f32_16x16x32_bf16 v[98:101], v[178:181], v[212:215], v[98:101]
	v_mfma_f32_16x16x32_bf16 v[126:129], v[174:177], v[190:193], v[126:129]
	v_mfma_f32_16x16x32_bf16 v[122:125], v[182:185], v[190:193], v[122:125]
	v_mfma_f32_16x16x32_bf16 v[118:121], v[174:177], v[200:203], v[118:121]
	v_mfma_f32_16x16x32_bf16 v[114:117], v[182:185], v[200:203], v[114:117]
	v_mfma_f32_16x16x32_bf16 v[110:113], v[174:177], v[208:211], v[110:113]
	v_mfma_f32_16x16x32_bf16 v[106:109], v[182:185], v[208:211], v[106:109]
	v_mfma_f32_16x16x32_bf16 v[102:105], v[174:177], v[216:219], v[102:105]
	v_mfma_f32_16x16x32_bf16 v[98:101], v[182:185], v[216:219], v[98:101]
	s_barrier
	s_setprio 0
	s_add_u32 s19, s0, s14
	ds_read_b128 v[220:223], v141
	ds_read_b128 v[224:227], v141 offset:1024
	ds_read_b128 v[228:231], v141 offset:2048
	ds_read_b128 v[232:235], v141 offset:3072
	s_addc_u32 s20, s1, s15
	s_add_u32 s26, s19, 0x100
	s_addc_u32 s27, s20, 0
	v_lshl_add_u64 v[236:237], s[26:27], 0, v[132:133]
	v_readfirstlane_b32 s21, v150
	s_mov_b32 m0, s21
	global_load_lds_dwordx4 v[236:237], off
	v_lshl_add_u64 v[236:237], s[26:27], 0, v[130:131]
	v_readfirstlane_b32 s21, v158
	s_mov_b32 m0, s21
	global_load_lds_dwordx4 v[236:237], off
	s_setprio 1
	s_barrier
	s_waitcnt lgkmcnt(0)
	v_mfma_f32_16x16x32_bf16 v[94:97], v[220:223], v[186:189], v[94:97]
	v_mfma_f32_16x16x32_bf16 v[90:93], v[228:231], v[186:189], v[90:93]
	v_mfma_f32_16x16x32_bf16 v[86:89], v[220:223], v[196:199], v[86:89]
	v_mfma_f32_16x16x32_bf16 v[82:85], v[228:231], v[196:199], v[82:85]
	v_mfma_f32_16x16x32_bf16 v[78:81], v[220:223], v[204:207], v[78:81]
	v_mfma_f32_16x16x32_bf16 v[74:77], v[228:231], v[204:207], v[74:77]
	v_mfma_f32_16x16x32_bf16 v[70:73], v[220:223], v[212:215], v[70:73]
	v_mfma_f32_16x16x32_bf16 v[66:69], v[228:231], v[212:215], v[66:69]
	v_mfma_f32_16x16x32_bf16 v[94:97], v[224:227], v[190:193], v[94:97]
	v_mfma_f32_16x16x32_bf16 v[90:93], v[232:235], v[190:193], v[90:93]
	v_mfma_f32_16x16x32_bf16 v[86:89], v[224:227], v[200:203], v[86:89]
	v_mfma_f32_16x16x32_bf16 v[82:85], v[232:235], v[200:203], v[82:85]
	v_mfma_f32_16x16x32_bf16 v[78:81], v[224:227], v[208:211], v[78:81]
	v_mfma_f32_16x16x32_bf16 v[74:77], v[232:235], v[208:211], v[74:77]
	v_mfma_f32_16x16x32_bf16 v[70:73], v[224:227], v[216:219], v[70:73]
	v_mfma_f32_16x16x32_bf16 v[66:69], v[232:235], v[216:219], v[66:69]
	s_barrier
	s_setprio 0
	ds_read_b128 v[186:189], v168 offset:16384
	ds_read_b128 v[190:193], v168 offset:17408
	ds_read_b128 v[196:199], v167 offset:16384
	ds_read_b128 v[200:203], v167 offset:17408
	ds_read_b128 v[204:207], v166 offset:16384
	ds_read_b128 v[208:211], v166 offset:17408
	ds_read_b128 v[212:215], v147 offset:16384
	ds_read_b128 v[216:219], v147 offset:17408
	s_add_u32 s26, s17, 0x8000100
	s_addc_u32 s27, s18, 0
	v_lshl_add_u64 v[236:237], s[26:27], 0, v[132:133]
	v_readfirstlane_b32 s21, v138
	s_mov_b32 m0, s21
	global_load_lds_dwordx4 v[236:237], off
	v_lshl_add_u64 v[236:237], s[26:27], 0, v[130:131]
	v_readfirstlane_b32 s21, v160
	s_mov_b32 m0, s21
	global_load_lds_dwordx4 v[236:237], off
	s_setprio 1
	s_barrier
	s_waitcnt lgkmcnt(0)
	v_mfma_f32_16x16x32_bf16 v[62:65], v[170:173], v[186:189], v[62:65]
	v_mfma_f32_16x16x32_bf16 v[58:61], v[178:181], v[186:189], v[58:61]
	v_mfma_f32_16x16x32_bf16 v[54:57], v[170:173], v[196:199], v[54:57]
	v_mfma_f32_16x16x32_bf16 v[50:53], v[178:181], v[196:199], v[50:53]
	v_mfma_f32_16x16x32_bf16 v[46:49], v[170:173], v[204:207], v[46:49]
	v_mfma_f32_16x16x32_bf16 v[42:45], v[178:181], v[204:207], v[42:45]
	v_mfma_f32_16x16x32_bf16 v[38:41], v[170:173], v[212:215], v[38:41]
	v_mfma_f32_16x16x32_bf16 v[34:37], v[178:181], v[212:215], v[34:37]
	v_mfma_f32_16x16x32_bf16 v[62:65], v[174:177], v[190:193], v[62:65]
	v_mfma_f32_16x16x32_bf16 v[58:61], v[182:185], v[190:193], v[58:61]
	v_mfma_f32_16x16x32_bf16 v[54:57], v[174:177], v[200:203], v[54:57]
	v_mfma_f32_16x16x32_bf16 v[50:53], v[182:185], v[200:203], v[50:53]
	v_mfma_f32_16x16x32_bf16 v[46:49], v[174:177], v[208:211], v[46:49]
	v_mfma_f32_16x16x32_bf16 v[42:45], v[182:185], v[208:211], v[42:45]
	v_mfma_f32_16x16x32_bf16 v[38:41], v[174:177], v[216:219], v[38:41]
	v_mfma_f32_16x16x32_bf16 v[34:37], v[182:185], v[216:219], v[34:37]
	s_barrier
;   #define LDA(dst,b,h) for(int m=0;m<4;++m)for(int k=0;k<2;++k) \
;     dst[m][k]=*reinterpret_cast<const bf16x8*>((char*)SA(b,h)+lds_byte(wr*64+m*16+fr,k*32+fq*8))
;   #define LDB(dst,b,h) for(int n=0;n<2;++n)for(int k=0;k<2;++k) \
;     dst[n][k]=*reinterpret_cast<const bf16x8*>((char*)SB(b,h)+lds_byte(wc*32+n*16+fr,k*32+fq*8))
;   #define MMA(ai,bj,At,Bt_) do{__builtin_amdgcn_s_setprio(1); \
;     for(int m=0;m<4;++m)for(int n=0;n<2;++n)for(int k=0;k<2;++k) \
;       acc[ai][bj][m][n]=__builtin_amdgcn_mfma_f32_16x16x32_bf16(Bt_[n][k],At[m][k],acc[ai][bj][m][n],0,0,0); \
;     __builtin_amdgcn_s_setprio(0);}while(0)
;   #define WAIT_V(n) asm volatile("s_waitcnt vmcnt(" #n ")":::"memory")
;   #define WAIT_L(n) asm volatile("s_waitcnt lgkmcnt(" #n ")":::"memory")
;   #define BAR __builtin_amdgcn_s_barrier()
;   #define SCHED __builtin_amdgcn_sched_barrier(0)
; template <bool TWO, class MID> ...
;     ...
;     WAIT_V(6); BAR; MMA(1,1,At,B1); BAR;
;     LDB(B0,1,0); SCHED; LDA(At,1,0); STAGE_A(SA(0,1),1,t+2);
;     WAIT_L(8); BAR; WAIT_L(0); MMA(0,0,At,B0); BAR; SCHED;
;     LDB(B1,1,1); STAGE_B(SB(1,0),0,t+3);
;     BAR; WAIT_L(0); MMA(0,1,At,B1); BAR;
;     LDA(At,1,1); STAGE_A(SA(1,0),0,t+3);
;     BAR; WAIT_L(0); MMA(1,0,At,B0); BAR; SCHED;
	s_setprio 0
	s_add_u32 s26, s19, 0x80100
	s_addc_u32 s27, s20, 0
	v_lshl_add_u64 v[170:171], s[26:27], 0, v[132:133]
	v_readfirstlane_b32 s21, v152
	s_mov_b32 m0, s21
	global_load_lds_dwordx4 v[170:171], off
	v_lshl_add_u64 v[170:171], s[26:27], 0, v[130:131]
	v_readfirstlane_b32 s21, v162
	s_mov_b32 m0, s21
	global_load_lds_dwordx4 v[170:171], off
	s_waitcnt vmcnt(6)
	s_setprio 1
	s_barrier
	v_mfma_f32_16x16x32_bf16 v[30:33], v[220:223], v[186:189], v[30:33]
	v_mfma_f32_16x16x32_bf16 v[26:29], v[228:231], v[186:189], v[26:29]
	v_mfma_f32_16x16x32_bf16 v[22:25], v[220:223], v[196:199], v[22:25]
	v_mfma_f32_16x16x32_bf16 v[18:21], v[228:231], v[196:199], v[18:21]
	v_mfma_f32_16x16x32_bf16 v[14:17], v[220:223], v[204:207], v[14:17]
	v_mfma_f32_16x16x32_bf16 v[10:13], v[228:231], v[204:207], v[10:13]
	v_mfma_f32_16x16x32_bf16 v[6:9], v[220:223], v[212:215], v[6:9]
	v_mfma_f32_16x16x32_bf16 v[2:5], v[228:231], v[212:215], v[2:5]
	v_mfma_f32_16x16x32_bf16 v[30:33], v[224:227], v[190:193], v[30:33]
	v_mfma_f32_16x16x32_bf16 v[26:29], v[232:235], v[190:193], v[26:29]
	v_mfma_f32_16x16x32_bf16 v[22:25], v[224:227], v[200:203], v[22:25]
	v_mfma_f32_16x16x32_bf16 v[18:21], v[232:235], v[200:203], v[18:21]
	v_mfma_f32_16x16x32_bf16 v[14:17], v[224:227], v[208:211], v[14:17]
	v_mfma_f32_16x16x32_bf16 v[10:13], v[232:235], v[208:211], v[10:13]
	v_mfma_f32_16x16x32_bf16 v[6:9], v[224:227], v[216:219], v[6:9]
	v_mfma_f32_16x16x32_bf16 v[2:5], v[232:235], v[216:219], v[2:5]
	s_barrier
	s_setprio 0
	ds_read_b128 v[170:173], v137
	ds_read_b128 v[174:177], v137 offset:1024
	ds_read_b128 v[178:181], v137 offset:2048
	ds_read_b128 v[182:185], v137 offset:3072
	ds_read_b128 v[186:189], v168 offset:32768
	ds_read_b128 v[190:193], v168 offset:33792
	ds_read_b128 v[196:199], v167 offset:32768
	ds_read_b128 v[200:203], v167 offset:33792
	ds_read_b128 v[204:207], v166 offset:32768
	ds_read_b128 v[208:211], v166 offset:33792
	ds_read_b128 v[212:215], v147 offset:32768
	ds_read_b128 v[216:219], v147 offset:33792
	s_add_u32 s26, s17, 0x8080100
	s_addc_u32 s27, s18, 0
	v_lshl_add_u64 v[220:221], s[26:27], 0, v[132:133]
	v_readfirstlane_b32 s21, v154
	s_mov_b32 m0, s21
	global_load_lds_dwordx4 v[220:221], off
	v_lshl_add_u64 v[220:221], s[26:27], 0, v[130:131]
	v_readfirstlane_b32 s21, v164
	s_mov_b32 m0, s21
	global_load_lds_dwordx4 v[220:221], off
	s_waitcnt lgkmcnt(8)
	s_setprio 1
	s_barrier
	s_waitcnt lgkmcnt(0)
	v_mfma_f32_16x16x32_bf16 v[126:129], v[170:173], v[186:189], v[126:129]
	v_mfma_f32_16x16x32_bf16 v[122:125], v[178:181], v[186:189], v[122:125]
	v_mfma_f32_16x16x32_bf16 v[118:121], v[170:173], v[196:199], v[118:121]
	v_mfma_f32_16x16x32_bf16 v[114:117], v[178:181], v[196:199], v[114:117]
	v_mfma_f32_16x16x32_bf16 v[110:113], v[170:173], v[204:207], v[110:113]
	v_mfma_f32_16x16x32_bf16 v[106:109], v[178:181], v[204:207], v[106:109]
	v_mfma_f32_16x16x32_bf16 v[102:105], v[170:173], v[212:215], v[102:105]
	v_mfma_f32_16x16x32_bf16 v[98:101], v[178:181], v[212:215], v[98:101]
	v_mfma_f32_16x16x32_bf16 v[126:129], v[174:177], v[190:193], v[126:129]
	v_mfma_f32_16x16x32_bf16 v[122:125], v[182:185], v[190:193], v[122:125]
	v_mfma_f32_16x16x32_bf16 v[118:121], v[174:177], v[200:203], v[118:121]
	v_mfma_f32_16x16x32_bf16 v[114:117], v[182:185], v[200:203], v[114:117]
	v_mfma_f32_16x16x32_bf16 v[110:113], v[174:177], v[208:211], v[110:113]
	v_mfma_f32_16x16x32_bf16 v[106:109], v[182:185], v[208:211], v[106:109]
	v_mfma_f32_16x16x32_bf16 v[102:105], v[174:177], v[216:219], v[102:105]
	v_mfma_f32_16x16x32_bf16 v[98:101], v[182:185], v[216:219], v[98:101]
	s_barrier
	s_setprio 0
	ds_read_b128 v[220:223], v135
	ds_read_b128 v[224:227], v135 offset:1024
	ds_read_b128 v[228:231], v135 offset:2048
	ds_read_b128 v[232:235], v135 offset:3072
	s_add_u32 s26, s19, 0x180
	s_addc_u32 s27, s20, 0
	v_lshl_add_u64 v[236:237], s[26:27], 0, v[132:133]
	v_readfirstlane_b32 s21, v134
	s_mov_b32 m0, s21
	global_load_lds_dwordx4 v[236:237], off
	v_lshl_add_u64 v[236:237], s[26:27], 0, v[130:131]
	v_readfirstlane_b32 s21, v136
	s_mov_b32 m0, s21
	global_load_lds_dwordx4 v[236:237], off
	s_setprio 1
	s_barrier
	s_waitcnt lgkmcnt(0)
	v_mfma_f32_16x16x32_bf16 v[94:97], v[220:223], v[186:189], v[94:97]
	v_mfma_f32_16x16x32_bf16 v[90:93], v[228:231], v[186:189], v[90:93]
	v_mfma_f32_16x16x32_bf16 v[86:89], v[220:223], v[196:199], v[86:89]
	v_mfma_f32_16x16x32_bf16 v[82:85], v[228:231], v[196:199], v[82:85]
	v_mfma_f32_16x16x32_bf16 v[78:81], v[220:223], v[204:207], v[78:81]
	v_mfma_f32_16x16x32_bf16 v[74:77], v[228:231], v[204:207], v[74:77]
	v_mfma_f32_16x16x32_bf16 v[70:73], v[220:223], v[212:215], v[70:73]
	v_mfma_f32_16x16x32_bf16 v[66:69], v[228:231], v[212:215], v[66:69]
	v_mfma_f32_16x16x32_bf16 v[94:97], v[224:227], v[190:193], v[94:97]
	v_mfma_f32_16x16x32_bf16 v[90:93], v[232:235], v[190:193], v[90:93]
	v_mfma_f32_16x16x32_bf16 v[86:89], v[224:227], v[200:203], v[86:89]
	v_mfma_f32_16x16x32_bf16 v[82:85], v[232:235], v[200:203], v[82:85]
	v_mfma_f32_16x16x32_bf16 v[78:81], v[224:227], v[208:211], v[78:81]
	v_mfma_f32_16x16x32_bf16 v[74:77], v[232:235], v[208:211], v[74:77]
	v_mfma_f32_16x16x32_bf16 v[70:73], v[224:227], v[216:219], v[70:73]
	v_mfma_f32_16x16x32_bf16 v[66:69], v[232:235], v[216:219], v[66:69]
	s_barrier
;   #define LDA(dst,b,h) for(int m=0;m<4;++m)for(int k=0;k<2;++k) \
;     dst[m][k]=*reinterpret_cast<const bf16x8*>((char*)SA(b,h)+lds_byte(wr*64+m*16+fr,k*32+fq*8))
;   #define LDB(dst,b,h) for(int n=0;n<2;++n)for(int k=0;k<2;++k) \
;     dst[n][k]=*reinterpret_cast<const bf16x8*>((char*)SB(b,h)+lds_byte(wc*32+n*16+fr,k*32+fq*8))
;   #define MMA(ai,bj,At,Bt_) do{__builtin_amdgcn_s_setprio(1); \
;     for(int m=0;m<4;++m)for(int n=0;n<2;++n)for(int k=0;k<2;++k) \
;       acc[ai][bj][m][n]=__builtin_amdgcn_mfma_f32_16x16x32_bf16(Bt_[n][k],At[m][k],acc[ai][bj][m][n],0,0,0); \
;     __builtin_amdgcn_s_setprio(0);}while(0)
;   #define WAIT_V(n) asm volatile("s_waitcnt vmcnt(" #n ")":::"memory")
;   #define WAIT_L(n) asm volatile("s_waitcnt lgkmcnt(" #n ")":::"memory")
;   #define BAR __builtin_amdgcn_s_barrier()
; template <bool TWO, class MID> ...
;     ...
;     STAGE_B(SB(1,1),1,t+3);
;     WAIT_V(6); BAR; MMA(1,1,At,B1); BAR;
;   }
;   { LDB(B0,0,0); LDA(At,0,0); STAGE_A(SA(1,1),1,nt-1);
;     BAR; WAIT_L(0); MMA(0,0,At,B0); BAR;
;     LDB(B1,0,1); BAR; WAIT_L(0); MMA(0,1,At,B1); BAR;
;     LDA(At,0,1); WAIT_V(4); BAR; WAIT_L(0); MMA(1,0,At,B0); MMA(1,1,At,B1); BAR; }
;   { LDB(B0,1,0); LDA(At,1,0); WAIT_V(2); BAR; WAIT_L(0); MMA(0,0,At,B0); BAR;
	s_setprio 0
	ds_read_b128 v[186:189], v168 offset:49152
	ds_read_b128 v[190:193], v168 offset:50176
	ds_read_b128 v[196:199], v167 offset:49152
	ds_read_b128 v[200:203], v167 offset:50176
	ds_read_b128 v[204:207], v166 offset:49152
	ds_read_b128 v[208:211], v166 offset:50176
	ds_read_b128 v[212:215], v147 offset:49152
	ds_read_b128 v[216:219], v147 offset:50176
	s_add_u32 s26, s17, 0x8000180
	s_addc_u32 s27, s18, 0
	v_lshl_add_u64 v[236:237], s[26:27], 0, v[132:133]
	v_readfirstlane_b32 s17, v140
	s_mov_b32 m0, s17
	global_load_lds_dwordx4 v[236:237], off
	v_lshl_add_u64 v[236:237], s[26:27], 0, v[130:131]
	v_readfirstlane_b32 s17, v142
	s_mov_b32 m0, s17
	global_load_lds_dwordx4 v[236:237], off
	s_setprio 1
	s_barrier
	s_waitcnt lgkmcnt(0)
	v_mfma_f32_16x16x32_bf16 v[62:65], v[170:173], v[186:189], v[62:65]
	v_mfma_f32_16x16x32_bf16 v[58:61], v[178:181], v[186:189], v[58:61]
	v_mfma_f32_16x16x32_bf16 v[54:57], v[170:173], v[196:199], v[54:57]
	v_mfma_f32_16x16x32_bf16 v[50:53], v[178:181], v[196:199], v[50:53]
	v_mfma_f32_16x16x32_bf16 v[46:49], v[170:173], v[204:207], v[46:49]
	v_mfma_f32_16x16x32_bf16 v[42:45], v[178:181], v[204:207], v[42:45]
	v_mfma_f32_16x16x32_bf16 v[38:41], v[170:173], v[212:215], v[38:41]
	v_mfma_f32_16x16x32_bf16 v[34:37], v[178:181], v[212:215], v[34:37]
	v_mfma_f32_16x16x32_bf16 v[62:65], v[174:177], v[190:193], v[62:65]
	v_mfma_f32_16x16x32_bf16 v[58:61], v[182:185], v[190:193], v[58:61]
	v_mfma_f32_16x16x32_bf16 v[54:57], v[174:177], v[200:203], v[54:57]
	v_mfma_f32_16x16x32_bf16 v[50:53], v[182:185], v[200:203], v[50:53]
	v_mfma_f32_16x16x32_bf16 v[46:49], v[174:177], v[208:211], v[46:49]
	v_mfma_f32_16x16x32_bf16 v[42:45], v[182:185], v[208:211], v[42:45]
	v_mfma_f32_16x16x32_bf16 v[38:41], v[174:177], v[216:219], v[38:41]
	v_mfma_f32_16x16x32_bf16 v[34:37], v[182:185], v[216:219], v[34:37]
	s_barrier
	s_setprio 0
	s_add_u32 s18, s19, 0x80180
	s_addc_u32 s19, s20, 0
	v_lshl_add_u64 v[170:171], s[18:19], 0, v[132:133]
	v_readfirstlane_b32 s17, v144
	s_mov_b32 m0, s17
	global_load_lds_dwordx4 v[170:171], off
	v_lshl_add_u64 v[170:171], s[18:19], 0, v[130:131]
	v_readfirstlane_b32 s17, v146
	s_mov_b32 m0, s17
	global_load_lds_dwordx4 v[170:171], off
	s_waitcnt vmcnt(6)
	s_setprio 1
	s_barrier
	v_mfma_f32_16x16x32_bf16 v[30:33], v[220:223], v[186:189], v[30:33]
	v_mfma_f32_16x16x32_bf16 v[26:29], v[228:231], v[186:189], v[26:29]
	v_mfma_f32_16x16x32_bf16 v[22:25], v[220:223], v[196:199], v[22:25]
	v_mfma_f32_16x16x32_bf16 v[18:21], v[228:231], v[196:199], v[18:21]
	v_mfma_f32_16x16x32_bf16 v[14:17], v[220:223], v[204:207], v[14:17]
	v_mfma_f32_16x16x32_bf16 v[10:13], v[228:231], v[204:207], v[10:13]
	v_mfma_f32_16x16x32_bf16 v[6:9], v[220:223], v[212:215], v[6:9]
	v_mfma_f32_16x16x32_bf16 v[2:5], v[228:231], v[212:215], v[2:5]
	v_mfma_f32_16x16x32_bf16 v[30:33], v[224:227], v[190:193], v[30:33]
	v_mfma_f32_16x16x32_bf16 v[26:29], v[232:235], v[190:193], v[26:29]
	v_mfma_f32_16x16x32_bf16 v[22:25], v[224:227], v[200:203], v[22:25]
	v_mfma_f32_16x16x32_bf16 v[18:21], v[232:235], v[200:203], v[18:21]
	v_mfma_f32_16x16x32_bf16 v[14:17], v[224:227], v[208:211], v[14:17]
	v_mfma_f32_16x16x32_bf16 v[10:13], v[232:235], v[208:211], v[10:13]
	v_mfma_f32_16x16x32_bf16 v[6:9], v[224:227], v[216:219], v[6:9]
	v_mfma_f32_16x16x32_bf16 v[2:5], v[232:235], v[216:219], v[2:5]
	s_setprio 0
	s_add_i32 s9, s9, 2
	s_add_u32 s0, s0, 0x100
	s_addc_u32 s1, s1, 0
	s_cmp_lt_u32 s9, 28
	s_barrier
	s_cbranch_scc1 .LBB0_169
	ds_read_b128 v[150:153], v143
	ds_read_b128 v[158:161], v143 offset:1024
	ds_read_b128 v[162:165], v143 offset:2048
	ds_read_b128 v[142:145], v143 offset:3072
	ds_read_b128 v[170:173], v168
	ds_read_b128 v[174:177], v168 offset:1024
	ds_read_b128 v[178:181], v167
	ds_read_b128 v[182:185], v167 offset:1024
	ds_read_b128 v[186:189], v166
	ds_read_b128 v[190:193], v166 offset:1024
	ds_read_b128 v[196:199], v147
	ds_read_b128 v[200:203], v147 offset:1024
	s_add_u32 s0, s11, 0x80f80
	s_addc_u32 s1, s16, 0
	v_lshl_add_u64 v[132:133], s[0:1], 0, v[132:133]
	v_readfirstlane_b32 s9, v148
	s_mov_b32 m0, s9
	global_load_lds_dwordx4 v[132:133], off
	v_lshl_add_u64 v[130:131], s[0:1], 0, v[130:131]
	v_readfirstlane_b32 s0, v156
	s_mov_b32 m0, s0
	global_load_lds_dwordx4 v[130:131], off
	s_setprio 1
	s_barrier
	s_waitcnt lgkmcnt(0)
	v_mfma_f32_16x16x32_bf16 v[126:129], v[150:153], v[170:173], v[126:129]
	v_mfma_f32_16x16x32_bf16 v[122:125], v[162:165], v[170:173], v[122:125]
	v_mfma_f32_16x16x32_bf16 v[114:117], v[162:165], v[178:181], v[114:117]
	v_mfma_f32_16x16x32_bf16 v[106:109], v[162:165], v[186:189], v[106:109]
	v_mfma_f32_16x16x32_bf16 v[98:101], v[162:165], v[196:199], v[98:101]
	v_mfma_f32_16x16x32_bf16 v[126:129], v[158:161], v[174:177], v[126:129]
	v_mfma_f32_16x16x32_bf16 v[122:125], v[142:145], v[174:177], v[122:125]
	v_mfma_f32_16x16x32_bf16 v[118:121], v[150:153], v[178:181], v[118:121]
	v_mfma_f32_16x16x32_bf16 v[114:117], v[142:145], v[182:185], v[114:117]
	v_mfma_f32_16x16x32_bf16 v[110:113], v[150:153], v[186:189], v[110:113]
	v_mfma_f32_16x16x32_bf16 v[106:109], v[142:145], v[190:193], v[106:109]
	v_mfma_f32_16x16x32_bf16 v[102:105], v[150:153], v[196:199], v[102:105]
	v_mfma_f32_16x16x32_bf16 v[130:133], v[142:145], v[200:203], v[98:101]
	v_mfma_f32_16x16x32_bf16 v[118:121], v[158:161], v[182:185], v[118:121]
	v_mfma_f32_16x16x32_bf16 v[110:113], v[158:161], v[190:193], v[110:113]
	v_mfma_f32_16x16x32_bf16 v[102:105], v[158:161], v[200:203], v[102:105]
	s_barrier
	s_setprio 0
	ds_read_b128 v[98:101], v141
	ds_read_b128 v[154:157], v141 offset:1024
	ds_read_b128 v[204:207], v141 offset:2048
	ds_read_b128 v[138:141], v141 offset:3072
	s_setprio 1
	s_barrier
;   #define LDA(dst,b,h) for(int m=0;m<4;++m)for(int k=0;k<2;++k) \
;     dst[m][k]=*reinterpret_cast<const bf16x8*>((char*)SA(b,h)+lds_byte(wr*64+m*16+fr,k*32+fq*8))
;   #define LDB(dst,b,h) for(int n=0;n<2;++n)for(int k=0;k<2;++k) \
;     dst[n][k]=*reinterpret_cast<const bf16x8*>((char*)SB(b,h)+lds_byte(wc*32+n*16+fr,k*32+fq*8))
;   #define MMA(ai,bj,At,Bt_) do{__builtin_amdgcn_s_setprio(1); \
;     for(int m=0;m<4;++m)for(int n=0;n<2;++n)for(int k=0;k<2;++k) \
;       acc[ai][bj][m][n]=__builtin_amdgcn_mfma_f32_16x16x32_bf16(Bt_[n][k],At[m][k],acc[ai][bj][m][n],0,0,0); \
;     __builtin_amdgcn_s_setprio(0);}while(0)
;   #define WAIT_V(n) asm volatile("s_waitcnt vmcnt(" #n ")":::"memory")
;   #define WAIT_L(n) asm volatile("s_waitcnt lgkmcnt(" #n ")":::"memory")
;   #define BAR __builtin_amdgcn_s_barrier()
; template <bool TWO, class MID> ...
;     ...
;   { LDB(B0,0,0); LDA(At,0,0); STAGE_A(SA(1,1),1,nt-1);
;     BAR; WAIT_L(0); MMA(0,0,At,B0); BAR;
;     LDB(B1,0,1); BAR; WAIT_L(0); MMA(0,1,At,B1); BAR;
;     LDA(At,0,1); WAIT_V(4); BAR; WAIT_L(0); MMA(1,0,At,B0); MMA(1,1,At,B1); BAR; }
;   { LDB(B0,1,0); LDA(At,1,0); WAIT_V(2); BAR; WAIT_L(0); MMA(0,0,At,B0); BAR;
	s_waitcnt lgkmcnt(0)
	v_mfma_f32_16x16x32_bf16 v[86:89], v[98:101], v[178:181], v[86:89]
	v_mfma_f32_16x16x32_bf16 v[82:85], v[204:207], v[178:181], v[82:85]
	v_mfma_f32_16x16x32_bf16 v[70:73], v[98:101], v[196:199], v[70:73]
	v_mfma_f32_16x16x32_bf16 v[66:69], v[204:207], v[196:199], v[66:69]
	v_mfma_f32_16x16x32_bf16 v[94:97], v[98:101], v[170:173], v[94:97]
	v_mfma_f32_16x16x32_bf16 v[90:93], v[204:207], v[170:173], v[90:93]
	v_mfma_f32_16x16x32_bf16 v[86:89], v[154:157], v[182:185], v[86:89]
	v_mfma_f32_16x16x32_bf16 v[82:85], v[138:141], v[182:185], v[82:85]
	v_mfma_f32_16x16x32_bf16 v[78:81], v[98:101], v[186:189], v[78:81]
	v_mfma_f32_16x16x32_bf16 v[74:77], v[204:207], v[186:189], v[74:77]
	v_mfma_f32_16x16x32_bf16 v[70:73], v[154:157], v[200:203], v[70:73]
	v_mfma_f32_16x16x32_bf16 v[66:69], v[138:141], v[200:203], v[66:69]
	v_mfma_f32_16x16x32_bf16 v[94:97], v[154:157], v[174:177], v[94:97]
	v_mfma_f32_16x16x32_bf16 v[170:173], v[138:141], v[174:177], v[90:93]
	v_mfma_f32_16x16x32_bf16 v[174:177], v[154:157], v[190:193], v[78:81]
	v_mfma_f32_16x16x32_bf16 v[178:181], v[138:141], v[190:193], v[74:77]
	s_barrier
	s_setprio 0
	s_nop 0
	ds_read_b128 v[74:77], v168 offset:16384
	ds_read_b128 v[78:81], v168 offset:17408
	ds_read_b128 v[90:93], v167 offset:16384
	ds_read_b128 v[182:185], v167 offset:17408
	ds_read_b128 v[186:189], v166 offset:16384
	ds_read_b128 v[190:193], v166 offset:17408
	ds_read_b128 v[196:199], v147 offset:16384
	ds_read_b128 v[200:203], v147 offset:17408
	s_waitcnt vmcnt(4)
	s_setprio 1
	s_barrier
	s_waitcnt lgkmcnt(0)
	v_mfma_f32_16x16x32_bf16 v[62:65], v[150:153], v[74:77], v[62:65]
	v_mfma_f32_16x16x32_bf16 v[58:61], v[162:165], v[74:77], v[58:61]
	v_mfma_f32_16x16x32_bf16 v[54:57], v[150:153], v[90:93], v[54:57]
	v_mfma_f32_16x16x32_bf16 v[50:53], v[162:165], v[90:93], v[50:53]
	v_mfma_f32_16x16x32_bf16 v[38:41], v[150:153], v[196:199], v[38:41]
	v_mfma_f32_16x16x32_bf16 v[34:37], v[162:165], v[196:199], v[34:37]
	v_mfma_f32_16x16x32_bf16 v[62:65], v[158:161], v[78:81], v[62:65]
	v_mfma_f32_16x16x32_bf16 v[58:61], v[142:145], v[78:81], v[58:61]
	v_mfma_f32_16x16x32_bf16 v[54:57], v[158:161], v[182:185], v[54:57]
	v_mfma_f32_16x16x32_bf16 v[50:53], v[142:145], v[182:185], v[50:53]
	v_mfma_f32_16x16x32_bf16 v[46:49], v[150:153], v[186:189], v[46:49]
	v_mfma_f32_16x16x32_bf16 v[42:45], v[162:165], v[186:189], v[42:45]
	v_mfma_f32_16x16x32_bf16 v[38:41], v[158:161], v[200:203], v[38:41]
	v_mfma_f32_16x16x32_bf16 v[34:37], v[142:145], v[200:203], v[34:37]
	v_mfma_f32_16x16x32_bf16 v[208:211], v[158:161], v[190:193], v[46:49]
	v_mfma_f32_16x16x32_bf16 v[212:215], v[142:145], v[190:193], v[42:45]
	s_setprio 0
	s_setprio 1
	v_mfma_f32_16x16x32_bf16 v[22:25], v[98:101], v[90:93], v[22:25]
	v_mfma_f32_16x16x32_bf16 v[18:21], v[204:207], v[90:93], v[18:21]
	v_mfma_f32_16x16x32_bf16 v[6:9], v[98:101], v[196:199], v[6:9]
	v_mfma_f32_16x16x32_bf16 v[2:5], v[204:207], v[196:199], v[2:5]
	v_mfma_f32_16x16x32_bf16 v[30:33], v[98:101], v[74:77], v[30:33]
	v_mfma_f32_16x16x32_bf16 v[26:29], v[204:207], v[74:77], v[26:29]
	v_mfma_f32_16x16x32_bf16 v[22:25], v[154:157], v[182:185], v[22:25]
	v_mfma_f32_16x16x32_bf16 v[18:21], v[138:141], v[182:185], v[18:21]
	v_mfma_f32_16x16x32_bf16 v[14:17], v[98:101], v[186:189], v[14:17]
	v_mfma_f32_16x16x32_bf16 v[10:13], v[204:207], v[186:189], v[10:13]
	v_mfma_f32_16x16x32_bf16 v[6:9], v[154:157], v[200:203], v[6:9]
	v_mfma_f32_16x16x32_bf16 v[2:5], v[138:141], v[200:203], v[2:5]
	v_mfma_f32_16x16x32_bf16 v[148:151], v[154:157], v[78:81], v[30:33]
	v_mfma_f32_16x16x32_bf16 v[158:161], v[138:141], v[78:81], v[26:29]
	v_mfma_f32_16x16x32_bf16 v[162:165], v[154:157], v[190:193], v[14:17]
	v_mfma_f32_16x16x32_bf16 v[182:185], v[138:141], v[190:193], v[10:13]
	s_barrier
	s_setprio 0
	s_nop 0
	ds_read_b128 v[10:13], v137
	ds_read_b128 v[14:17], v137 offset:1024
	ds_read_b128 v[152:155], v137 offset:2048
	ds_read_b128 v[186:189], v137 offset:3072
	ds_read_b128 v[26:29], v168 offset:32768
	ds_read_b128 v[30:33], v168 offset:33792
	ds_read_b128 v[42:45], v167 offset:32768
	ds_read_b128 v[46:49], v167 offset:33792
	ds_read_b128 v[190:193], v166 offset:32768
	ds_read_b128 v[196:199], v166 offset:33792
	ds_read_b128 v[200:203], v147 offset:32768
	ds_read_b128 v[204:207], v147 offset:33792
	s_waitcnt vmcnt(2)
	s_setprio 1
	s_barrier
;   #define LDA(dst,b,h) for(int m=0;m<4;++m)for(int k=0;k<2;++k) \
;     dst[m][k]=*reinterpret_cast<const bf16x8*>((char*)SA(b,h)+lds_byte(wr*64+m*16+fr,k*32+fq*8))
;   #define LDB(dst,b,h) for(int n=0;n<2;++n)for(int k=0;k<2;++k) \
;     dst[n][k]=*reinterpret_cast<const bf16x8*>((char*)SB(b,h)+lds_byte(wc*32+n*16+fr,k*32+fq*8))
;   #define MMA(ai,bj,At,Bt_) do{__builtin_amdgcn_s_setprio(1); \
;     for(int m=0;m<4;++m)for(int n=0;n<2;++n)for(int k=0;k<2;++k) \
;       acc[ai][bj][m][n]=__builtin_amdgcn_mfma_f32_16x16x32_bf16(Bt_[n][k],At[m][k],acc[ai][bj][m][n],0,0,0); \
;     __builtin_amdgcn_s_setprio(0);}while(0)
;   #define WAIT_V(n) asm volatile("s_waitcnt vmcnt(" #n ")":::"memory")
;   #define WAIT_L(n) asm volatile("s_waitcnt lgkmcnt(" #n ")":::"memory")
;   #define BAR __builtin_amdgcn_s_barrier()
; template <bool TWO, class MID> ...
;     ...
;   { LDB(B0,1,0); LDA(At,1,0); WAIT_V(2); BAR; WAIT_L(0); MMA(0,0,At,B0); BAR;
;     LDB(B1,1,1); WAIT_V(0); BAR; WAIT_L(0); MMA(0,1,At,B1); BAR;
;     LDA(At,1,1); BAR; WAIT_L(0); MMA(1,0,At,B0); MMA(1,1,At,B1); BAR; }
;   if(wr==0)BAR;
	s_waitcnt lgkmcnt(0)
	v_mfma_f32_16x16x32_bf16 v[74:77], v[10:13], v[26:29], v[126:129]
	v_mfma_f32_16x16x32_bf16 v[142:145], v[14:17], v[30:33], v[74:77]
	v_mfma_f32_16x16x32_bf16 v[74:77], v[152:155], v[26:29], v[122:125]
	v_mfma_f32_16x16x32_bf16 v[138:141], v[186:189], v[30:33], v[74:77]
	v_mfma_f32_16x16x32_bf16 v[74:77], v[10:13], v[42:45], v[118:121]
	v_mfma_f32_16x16x32_bf16 v[126:129], v[14:17], v[46:49], v[74:77]
	v_mfma_f32_16x16x32_bf16 v[74:77], v[152:155], v[42:45], v[114:117]
	v_mfma_f32_16x16x32_bf16 v[122:125], v[186:189], v[46:49], v[74:77]
	v_mfma_f32_16x16x32_bf16 v[74:77], v[10:13], v[190:193], v[110:113]
	v_mfma_f32_16x16x32_bf16 v[98:101], v[14:17], v[196:199], v[74:77]
	v_mfma_f32_16x16x32_bf16 v[74:77], v[152:155], v[190:193], v[106:109]
	v_mfma_f32_16x16x32_bf16 v[90:93], v[186:189], v[196:199], v[74:77]
	v_mfma_f32_16x16x32_bf16 v[74:77], v[10:13], v[200:203], v[102:105]
	v_mfma_f32_16x16x32_bf16 v[78:81], v[14:17], v[204:207], v[74:77]
	v_mfma_f32_16x16x32_bf16 v[74:77], v[152:155], v[200:203], v[130:133]
	v_mfma_f32_16x16x32_bf16 v[74:77], v[186:189], v[204:207], v[74:77]
	s_barrier
	s_setprio 0
	ds_read_b128 v[102:105], v135
	ds_read_b128 v[110:113], v135 offset:1024
	ds_read_b128 v[118:121], v135 offset:2048
	ds_read_b128 v[216:219], v135 offset:3072
	s_waitcnt vmcnt(0)
	s_setprio 1
	s_barrier
	s_waitcnt lgkmcnt(0)
	v_mfma_f32_16x16x32_bf16 v[94:97], v[102:105], v[26:29], v[94:97]
	v_mfma_f32_16x16x32_bf16 v[26:29], v[118:121], v[26:29], v[170:173]
	v_mfma_f32_16x16x32_bf16 v[130:133], v[216:219], v[30:33], v[26:29]
	v_mfma_f32_16x16x32_bf16 v[26:29], v[102:105], v[42:45], v[86:89]
	v_mfma_f32_16x16x32_bf16 v[114:117], v[110:113], v[46:49], v[26:29]
	v_mfma_f32_16x16x32_bf16 v[26:29], v[118:121], v[42:45], v[82:85]
	v_mfma_f32_16x16x32_bf16 v[106:109], v[216:219], v[46:49], v[26:29]
	v_mfma_f32_16x16x32_bf16 v[26:29], v[102:105], v[190:193], v[174:177]
	v_mfma_f32_16x16x32_bf16 v[86:89], v[110:113], v[196:199], v[26:29]
	v_mfma_f32_16x16x32_bf16 v[26:29], v[118:121], v[190:193], v[178:181]
	v_mfma_f32_16x16x32_bf16 v[82:85], v[216:219], v[196:199], v[26:29]
	v_mfma_f32_16x16x32_bf16 v[26:29], v[102:105], v[200:203], v[70:73]
	v_mfma_f32_16x16x32_bf16 v[70:73], v[110:113], v[204:207], v[26:29]
	v_mfma_f32_16x16x32_bf16 v[26:29], v[118:121], v[200:203], v[66:69]
	v_mfma_f32_16x16x32_bf16 v[134:137], v[110:113], v[30:33], v[94:97]
	v_mfma_f32_16x16x32_bf16 v[66:69], v[216:219], v[204:207], v[26:29]
	s_barrier
	s_setprio 0
	ds_read_b128 v[94:97], v168 offset:49152
	ds_read_b128 v[168:171], v168 offset:50176
	ds_read_b128 v[172:175], v167 offset:49152
	ds_read_b128 v[176:179], v167 offset:50176
	ds_read_b128 v[190:193], v166 offset:49152
	ds_read_b128 v[196:199], v166 offset:50176
	ds_read_b128 v[200:203], v147 offset:49152
	ds_read_b128 v[204:207], v147 offset:50176
	s_setprio 1
	s_barrier
	s_waitcnt lgkmcnt(0)
	v_mfma_f32_16x16x32_bf16 v[26:29], v[10:13], v[94:97], v[62:65]
	v_mfma_f32_16x16x32_bf16 v[62:65], v[14:17], v[168:171], v[26:29]
	v_mfma_f32_16x16x32_bf16 v[26:29], v[152:155], v[94:97], v[58:61]
	v_mfma_f32_16x16x32_bf16 v[58:61], v[186:189], v[168:171], v[26:29]
	v_mfma_f32_16x16x32_bf16 v[26:29], v[10:13], v[172:175], v[54:57]
	v_mfma_f32_16x16x32_bf16 v[46:49], v[14:17], v[176:179], v[26:29]
	v_mfma_f32_16x16x32_bf16 v[26:29], v[152:155], v[172:175], v[50:53]
	v_mfma_f32_16x16x32_bf16 v[42:45], v[186:189], v[176:179], v[26:29]
	v_mfma_f32_16x16x32_bf16 v[26:29], v[10:13], v[190:193], v[208:211]
	v_mfma_f32_16x16x32_bf16 v[10:13], v[10:13], v[200:203], v[38:41]
	v_mfma_f32_16x16x32_bf16 v[30:33], v[14:17], v[196:199], v[26:29]
	v_mfma_f32_16x16x32_bf16 v[26:29], v[152:155], v[190:193], v[212:215]
	v_mfma_f32_16x16x32_bf16 v[14:17], v[14:17], v[204:207], v[10:13]
	v_mfma_f32_16x16x32_bf16 v[10:13], v[152:155], v[200:203], v[34:37]
	v_mfma_f32_16x16x32_bf16 v[26:29], v[186:189], v[196:199], v[26:29]
	v_mfma_f32_16x16x32_bf16 v[10:13], v[186:189], v[204:207], v[10:13]
	s_setprio 0
	s_setprio 1
	v_mfma_f32_16x16x32_bf16 v[34:37], v[102:105], v[94:97], v[148:151]
	v_mfma_f32_16x16x32_bf16 v[54:57], v[110:113], v[168:171], v[34:37]
	v_mfma_f32_16x16x32_bf16 v[34:37], v[118:121], v[94:97], v[158:161]
	v_mfma_f32_16x16x32_bf16 v[18:21], v[118:121], v[172:175], v[18:21]
	v_mfma_f32_16x16x32_bf16 v[50:53], v[216:219], v[168:171], v[34:37]
	v_mfma_f32_16x16x32_bf16 v[22:25], v[102:105], v[172:175], v[22:25]
	v_mfma_f32_16x16x32_bf16 v[34:37], v[216:219], v[176:179], v[18:21]
	v_mfma_f32_16x16x32_bf16 v[18:21], v[102:105], v[190:193], v[162:165]
	v_mfma_f32_16x16x32_bf16 v[38:41], v[110:113], v[176:179], v[22:25]
	v_mfma_f32_16x16x32_bf16 v[22:25], v[110:113], v[196:199], v[18:21]
	v_mfma_f32_16x16x32_bf16 v[18:21], v[118:121], v[190:193], v[182:185]
	v_mfma_f32_16x16x32_bf16 v[6:9], v[102:105], v[200:203], v[6:9]
	v_mfma_f32_16x16x32_bf16 v[2:5], v[118:121], v[200:203], v[2:5]
	v_mfma_f32_16x16x32_bf16 v[18:21], v[216:219], v[196:199], v[18:21]
	v_mfma_f32_16x16x32_bf16 v[6:9], v[110:113], v[204:207], v[6:9]
	v_mfma_f32_16x16x32_bf16 v[2:5], v[216:219], v[204:207], v[2:5]
	s_setprio 0
	v_cmp_gt_u32_e32 vcc, s30, v1
	s_barrier
	s_and_saveexec_b64 s[0:1], vcc
	s_cbranch_execz .LBB0_172
	s_barrier

;   #define LDA(dst,b,h) for(int m=0;m<4;++m)for(int k=0;k<2;++k) \
;     dst[m][k]=*reinterpret_cast<const bf16x8*>((char*)SA(b,h)+lds_byte(wr*64+m*16+fr,k*32+fq*8))
;   #define LDB(dst,b,h) for(int n=0;n<2;++n)for(int k=0;k<2;++k) \
;     dst[n][k]=*reinterpret_cast<const bf16x8*>((char*)SB(b,h)+lds_byte(wc*32+n*16+fr,k*32+fq*8))
;   #define MMA(ai,bj,At,Bt_) do{__builtin_amdgcn_s_setprio(1); \
;     for(int m=0;m<4;++m)for(int n=0;n<2;++n)for(int k=0;k<2;++k) \
;       acc[ai][bj][m][n]=__builtin_amdgcn_mfma_f32_16x16x32_bf16(Bt_[n][k],At[m][k],acc[ai][bj][m][n],0,0,0); \
;     __builtin_amdgcn_s_setprio(0);}while(0)
;   #define WAIT_L(n) asm volatile("s_waitcnt lgkmcnt(" #n ")":::"memory")
;   #define BAR __builtin_amdgcn_s_barrier()
;   #define SCHED __builtin_amdgcn_sched_barrier(0)
; template <bool TWO, class MID> ...
;     ...
;   for(int t=0;t<nt-2;t+=2){
;     if (TWO && t == nt1) mid();
;     LDB(B0,0,0); SCHED; LDA(At,0,0); STAGE_A(SA(1,1),1,t+1);
;     WAIT_L(8); BAR; WAIT_L(0); MMA(0,0,At,B0); BAR; SCHED;
;     LDB(B1,0,1); STAGE_B(SB(0,0),0,t+2);
.LBB0_409:
	s_waitcnt lgkmcnt(8)
	s_setprio 1
	s_barrier
	s_waitcnt lgkmcnt(0)
	v_mfma_f32_16x16x32_bf16 v[126:129], v[130:133], v[186:189], v[126:129]
	v_mfma_f32_16x16x32_bf16 v[122:125], v[138:141], v[186:189], v[122:125]
	v_mfma_f32_16x16x32_bf16 v[118:121], v[130:133], v[178:181], v[118:121]
	v_mfma_f32_16x16x32_bf16 v[114:117], v[138:141], v[178:181], v[114:117]
	v_mfma_f32_16x16x32_bf16 v[110:113], v[130:133], v[170:173], v[110:113]
	v_mfma_f32_16x16x32_bf16 v[106:109], v[138:141], v[170:173], v[106:109]
	v_mfma_f32_16x16x32_bf16 v[102:105], v[130:133], v[162:165], v[102:105]
	v_mfma_f32_16x16x32_bf16 v[98:101], v[138:141], v[162:165], v[98:101]
	v_mfma_f32_16x16x32_bf16 v[126:129], v[134:137], v[190:193], v[126:129]
	v_mfma_f32_16x16x32_bf16 v[122:125], v[142:145], v[190:193], v[122:125]
	v_mfma_f32_16x16x32_bf16 v[118:121], v[134:137], v[182:185], v[118:121]
	v_mfma_f32_16x16x32_bf16 v[114:117], v[142:145], v[182:185], v[114:117]
	v_mfma_f32_16x16x32_bf16 v[110:113], v[134:137], v[174:177], v[110:113]
	v_mfma_f32_16x16x32_bf16 v[106:109], v[142:145], v[174:177], v[106:109]
	v_mfma_f32_16x16x32_bf16 v[102:105], v[134:137], v[166:169], v[102:105]
	v_mfma_f32_16x16x32_bf16 v[98:101], v[142:145], v[166:169], v[98:101]
	s_barrier
	s_setprio 0
	ds_read_b128 v[146:149], v217
	ds_read_b128 v[150:153], v217 offset:1024
	ds_read_b128 v[154:157], v217 offset:2048
	ds_read_b128 v[158:161], v217 offset:3072
	s_cmp_lt_u32 s26, 6
	s_cselect_b64 s[14:15], -1, 0
	s_mov_b64 s[16:17], -1
	s_and_b64 vcc, exec, s[14:15]
	s_cbranch_vccz .LBB0_411
	s_add_u32 s16, s24, s12
	s_addc_u32 s17, s25, s13
	s_add_u32 s16, s16, 0x2e00100
	s_addc_u32 s17, s17, 0
	v_lshl_add_u64 v[250:251], s[16:17], 0, v[200:201]
	v_readfirstlane_b32 s27, v228
	s_mov_b32 m0, s27
	global_load_lds_dwordx4 v[250:251], off
	v_lshl_add_u64 v[250:251], s[16:17], 0, v[202:203]
	v_readfirstlane_b32 s16, v230
	s_mov_b32 m0, s16
	global_load_lds_dwordx4 v[250:251], off
	s_mov_b64 s[16:17], 0

;   #define LDA(dst,b,h) for(int m=0;m<4;++m)for(int k=0;k<2;++k) \
;     dst[m][k]=*reinterpret_cast<const bf16x8*>((char*)SA(b,h)+lds_byte(wr*64+m*16+fr,k*32+fq*8))
;   #define MMA(ai,bj,At,Bt_) do{__builtin_amdgcn_s_setprio(1); \
;     for(int m=0;m<4;++m)for(int n=0;n<2;++n)for(int k=0;k<2;++k) \
;       acc[ai][bj][m][n]=__builtin_amdgcn_mfma_f32_16x16x32_bf16(Bt_[n][k],At[m][k],acc[ai][bj][m][n],0,0,0); \
;     __builtin_amdgcn_s_setprio(0);}while(0)
;   #define WAIT_L(n) asm volatile("s_waitcnt lgkmcnt(" #n ")":::"memory")
;   #define BAR __builtin_amdgcn_s_barrier()
; template <bool TWO, class MID> ...
;     ...
;     BAR; WAIT_L(0); MMA(0,1,At,B1); BAR;
;     LDA(At,0,1); STAGE_A(SA(0,0),0,t+2);
.LBB0_413:
	s_setprio 1
	s_barrier
	s_waitcnt lgkmcnt(0)
	v_mfma_f32_16x16x32_bf16 v[94:97], v[146:149], v[186:189], v[94:97]
	v_mfma_f32_16x16x32_bf16 v[90:93], v[154:157], v[186:189], v[90:93]
	v_mfma_f32_16x16x32_bf16 v[86:89], v[146:149], v[178:181], v[86:89]
	v_mfma_f32_16x16x32_bf16 v[82:85], v[154:157], v[178:181], v[82:85]
	v_mfma_f32_16x16x32_bf16 v[78:81], v[146:149], v[170:173], v[78:81]
	v_mfma_f32_16x16x32_bf16 v[74:77], v[154:157], v[170:173], v[74:77]
	v_mfma_f32_16x16x32_bf16 v[70:73], v[146:149], v[162:165], v[70:73]
	v_mfma_f32_16x16x32_bf16 v[66:69], v[154:157], v[162:165], v[66:69]
	v_mfma_f32_16x16x32_bf16 v[94:97], v[150:153], v[190:193], v[94:97]
	v_mfma_f32_16x16x32_bf16 v[90:93], v[158:161], v[190:193], v[90:93]
	v_mfma_f32_16x16x32_bf16 v[86:89], v[150:153], v[182:185], v[86:89]
	v_mfma_f32_16x16x32_bf16 v[82:85], v[158:161], v[182:185], v[82:85]
	v_mfma_f32_16x16x32_bf16 v[78:81], v[150:153], v[174:177], v[78:81]
	v_mfma_f32_16x16x32_bf16 v[74:77], v[158:161], v[174:177], v[74:77]
	v_mfma_f32_16x16x32_bf16 v[70:73], v[150:153], v[166:169], v[70:73]
	v_mfma_f32_16x16x32_bf16 v[66:69], v[158:161], v[166:169], v[66:69]
	s_barrier
	s_setprio 0
	ds_read_b128 v[186:189], v211 offset:16384
	ds_read_b128 v[190:193], v211 offset:17408
	ds_read_b128 v[178:181], v209 offset:16384
	ds_read_b128 v[182:185], v209 offset:17408
	ds_read_b128 v[170:173], v207 offset:16384
	ds_read_b128 v[174:177], v207 offset:17408
	ds_read_b128 v[162:165], v205 offset:16384
	ds_read_b128 v[166:169], v205 offset:17408
	s_mov_b64 s[16:17], -1
	s_and_b64 vcc, exec, s[14:15]
	s_cbranch_vccz .LBB0_415
	s_add_u32 s16, s1, s12
	s_addc_u32 s17, s5, s13
	s_add_u32 s16, s16, 0x10000100
	s_addc_u32 s17, s17, 0
	v_lshl_add_u64 v[250:251], s[16:17], 0, v[196:197]
	v_readfirstlane_b32 s27, v204
	s_mov_b32 m0, s27
	global_load_lds_dwordx4 v[250:251], off
	v_lshl_add_u64 v[250:251], s[16:17], 0, v[198:199]
	v_readfirstlane_b32 s16, v206
	s_mov_b32 m0, s16
	global_load_lds_dwordx4 v[250:251], off
	s_mov_b64 s[16:17], 0

;   #define MMA(ai,bj,At,Bt_) do{__builtin_amdgcn_s_setprio(1); \
;     for(int m=0;m<4;++m)for(int n=0;n<2;++n)for(int k=0;k<2;++k) \
;       acc[ai][bj][m][n]=__builtin_amdgcn_mfma_f32_16x16x32_bf16(Bt_[n][k],At[m][k],acc[ai][bj][m][n],0,0,0); \
;     __builtin_amdgcn_s_setprio(0);}while(0)
;   #define WAIT_L(n) asm volatile("s_waitcnt lgkmcnt(" #n ")":::"memory")
;   #define BAR __builtin_amdgcn_s_barrier()
;   #define SCHED __builtin_amdgcn_sched_barrier(0)
; template <bool TWO, class MID> ...
;     ...
;     BAR; WAIT_L(0); MMA(1,0,At,B0); BAR; SCHED;
;     STAGE_B(SB(0,1),1,t+2);
.LBB0_417:
	s_setprio 1
	s_barrier
	s_waitcnt lgkmcnt(0)
	v_mfma_f32_16x16x32_bf16 v[62:65], v[130:133], v[186:189], v[62:65]
	v_mfma_f32_16x16x32_bf16 v[58:61], v[138:141], v[186:189], v[58:61]
	v_mfma_f32_16x16x32_bf16 v[54:57], v[130:133], v[178:181], v[54:57]
	v_mfma_f32_16x16x32_bf16 v[50:53], v[138:141], v[178:181], v[50:53]
	v_mfma_f32_16x16x32_bf16 v[46:49], v[130:133], v[170:173], v[46:49]
	v_mfma_f32_16x16x32_bf16 v[42:45], v[138:141], v[170:173], v[42:45]
	v_mfma_f32_16x16x32_bf16 v[38:41], v[130:133], v[162:165], v[38:41]
	v_mfma_f32_16x16x32_bf16 v[34:37], v[138:141], v[162:165], v[34:37]
	v_mfma_f32_16x16x32_bf16 v[62:65], v[134:137], v[190:193], v[62:65]
	v_mfma_f32_16x16x32_bf16 v[58:61], v[142:145], v[190:193], v[58:61]
	v_mfma_f32_16x16x32_bf16 v[54:57], v[134:137], v[182:185], v[54:57]
	v_mfma_f32_16x16x32_bf16 v[50:53], v[142:145], v[182:185], v[50:53]
	v_mfma_f32_16x16x32_bf16 v[46:49], v[134:137], v[174:177], v[46:49]
	v_mfma_f32_16x16x32_bf16 v[42:45], v[142:145], v[174:177], v[42:45]
	v_mfma_f32_16x16x32_bf16 v[38:41], v[134:137], v[166:169], v[38:41]
	v_mfma_f32_16x16x32_bf16 v[34:37], v[142:145], v[166:169], v[34:37]
	s_barrier
	s_setprio 0
	s_mov_b64 s[16:17], -1
	s_and_b64 vcc, exec, s[14:15]
	s_cbranch_vccz .LBB0_419
	s_add_u32 s16, s24, s12
	s_addc_u32 s17, s25, s13
	s_add_u32 s16, s16, 0x2e20100
	s_addc_u32 s17, s17, 0
	v_lshl_add_u64 v[130:131], s[16:17], 0, v[200:201]
	v_readfirstlane_b32 s27, v236
	s_mov_b32 m0, s27
	global_load_lds_dwordx4 v[130:131], off
	v_lshl_add_u64 v[130:131], s[16:17], 0, v[202:203]
	v_readfirstlane_b32 s16, v238
	s_mov_b32 m0, s16
	global_load_lds_dwordx4 v[130:131], off
	s_mov_b64 s[16:17], 0

;   #define LDA(dst,b,h) for(int m=0;m<4;++m)for(int k=0;k<2;++k) \
;     dst[m][k]=*reinterpret_cast<const bf16x8*>((char*)SA(b,h)+lds_byte(wr*64+m*16+fr,k*32+fq*8))
;   #define LDB(dst,b,h) for(int n=0;n<2;++n)for(int k=0;k<2;++k) \
;     dst[n][k]=*reinterpret_cast<const bf16x8*>((char*)SB(b,h)+lds_byte(wc*32+n*16+fr,k*32+fq*8))
;   #define MMA(ai,bj,At,Bt_) do{__builtin_amdgcn_s_setprio(1); \
;     for(int m=0;m<4;++m)for(int n=0;n<2;++n)for(int k=0;k<2;++k) \
;       acc[ai][bj][m][n]=__builtin_amdgcn_mfma_f32_16x16x32_bf16(Bt_[n][k],At[m][k],acc[ai][bj][m][n],0,0,0); \
;     __builtin_amdgcn_s_setprio(0);}while(0)
;   #define WAIT_V(n) asm volatile("s_waitcnt vmcnt(" #n ")":::"memory")
;   #define BAR __builtin_amdgcn_s_barrier()
;   #define SCHED __builtin_amdgcn_sched_barrier(0)
; template <bool TWO, class MID> ...
;     ...
;     WAIT_V(6); BAR; MMA(1,1,At,B1); BAR;
;     LDB(B0,1,0); SCHED; LDA(At,1,0); STAGE_A(SA(0,1),1,t+2);
.LBB0_421:
	s_waitcnt vmcnt(6)
	s_setprio 1
	s_barrier
	v_mfma_f32_16x16x32_bf16 v[30:33], v[146:149], v[186:189], v[30:33]
	v_mfma_f32_16x16x32_bf16 v[26:29], v[154:157], v[186:189], v[26:29]
	v_mfma_f32_16x16x32_bf16 v[22:25], v[146:149], v[178:181], v[22:25]
	v_mfma_f32_16x16x32_bf16 v[18:21], v[154:157], v[178:181], v[18:21]
	v_mfma_f32_16x16x32_bf16 v[14:17], v[146:149], v[170:173], v[14:17]
	v_mfma_f32_16x16x32_bf16 v[10:13], v[154:157], v[170:173], v[10:13]
	v_mfma_f32_16x16x32_bf16 v[6:9], v[146:149], v[162:165], v[6:9]
	v_mfma_f32_16x16x32_bf16 v[2:5], v[154:157], v[162:165], v[2:5]
	v_mfma_f32_16x16x32_bf16 v[30:33], v[150:153], v[190:193], v[30:33]
	v_mfma_f32_16x16x32_bf16 v[26:29], v[158:161], v[190:193], v[26:29]
	v_mfma_f32_16x16x32_bf16 v[22:25], v[150:153], v[182:185], v[22:25]
	v_mfma_f32_16x16x32_bf16 v[18:21], v[158:161], v[182:185], v[18:21]
	v_mfma_f32_16x16x32_bf16 v[14:17], v[150:153], v[174:177], v[14:17]
	v_mfma_f32_16x16x32_bf16 v[10:13], v[158:161], v[174:177], v[10:13]
	v_mfma_f32_16x16x32_bf16 v[6:9], v[150:153], v[166:169], v[6:9]
	v_mfma_f32_16x16x32_bf16 v[2:5], v[158:161], v[166:169], v[2:5]
	s_barrier
	s_setprio 0
	ds_read_b128 v[130:133], v215
	ds_read_b128 v[134:137], v215 offset:1024
	ds_read_b128 v[138:141], v215 offset:2048
	ds_read_b128 v[142:145], v215 offset:3072
	ds_read_b128 v[186:189], v211 offset:32768
	ds_read_b128 v[190:193], v211 offset:33792
	ds_read_b128 v[178:181], v209 offset:32768
	ds_read_b128 v[182:185], v209 offset:33792
	ds_read_b128 v[170:173], v207 offset:32768
	ds_read_b128 v[174:177], v207 offset:33792
	ds_read_b128 v[162:165], v205 offset:32768
	ds_read_b128 v[166:169], v205 offset:33792
	s_mov_b64 s[16:17], -1
	s_and_b64 vcc, exec, s[14:15]
	s_cbranch_vccz .LBB0_423
	s_add_u32 s14, s1, s12
	s_addc_u32 s15, s5, s13
	s_add_u32 s14, s14, 0x10120100
	s_addc_u32 s15, s15, 0
	v_lshl_add_u64 v[146:147], s[14:15], 0, v[196:197]
	v_readfirstlane_b32 s16, v240
	s_mov_b32 m0, s16
	global_load_lds_dwordx4 v[146:147], off
	v_lshl_add_u64 v[146:147], s[14:15], 0, v[198:199]
	v_readfirstlane_b32 s14, v242
	s_mov_b32 m0, s14
	global_load_lds_dwordx4 v[146:147], off
	s_mov_b64 s[16:17], 0

;   #define LDB(dst,b,h) for(int n=0;n<2;++n)for(int k=0;k<2;++k) \
;     dst[n][k]=*reinterpret_cast<const bf16x8*>((char*)SB(b,h)+lds_byte(wc*32+n*16+fr,k*32+fq*8))
;   #define MMA(ai,bj,At,Bt_) do{__builtin_amdgcn_s_setprio(1); \
;     for(int m=0;m<4;++m)for(int n=0;n<2;++n)for(int k=0;k<2;++k) \
;       acc[ai][bj][m][n]=__builtin_amdgcn_mfma_f32_16x16x32_bf16(Bt_[n][k],At[m][k],acc[ai][bj][m][n],0,0,0); \
;     __builtin_amdgcn_s_setprio(0);}while(0)
;   #define WAIT_L(n) asm volatile("s_waitcnt lgkmcnt(" #n ")":::"memory")
;   #define BAR __builtin_amdgcn_s_barrier()
;   #define SCHED __builtin_amdgcn_sched_barrier(0)
; template <bool TWO, class MID> ...
;     ...
;     WAIT_L(8); BAR; WAIT_L(0); MMA(0,0,At,B0); BAR; SCHED;
;     LDB(B1,1,1); STAGE_B(SB(1,0),0,t+3);
.LBB0_425:
	s_waitcnt lgkmcnt(8)
	s_setprio 1
	s_barrier
	s_waitcnt lgkmcnt(0)
	v_mfma_f32_16x16x32_bf16 v[126:129], v[130:133], v[186:189], v[126:129]
	v_mfma_f32_16x16x32_bf16 v[122:125], v[138:141], v[186:189], v[122:125]
	v_mfma_f32_16x16x32_bf16 v[118:121], v[130:133], v[178:181], v[118:121]
	v_mfma_f32_16x16x32_bf16 v[114:117], v[138:141], v[178:181], v[114:117]
	v_mfma_f32_16x16x32_bf16 v[110:113], v[130:133], v[170:173], v[110:113]
	v_mfma_f32_16x16x32_bf16 v[106:109], v[138:141], v[170:173], v[106:109]
	v_mfma_f32_16x16x32_bf16 v[102:105], v[130:133], v[162:165], v[102:105]
	v_mfma_f32_16x16x32_bf16 v[98:101], v[138:141], v[162:165], v[98:101]
	v_mfma_f32_16x16x32_bf16 v[126:129], v[134:137], v[190:193], v[126:129]
	v_mfma_f32_16x16x32_bf16 v[122:125], v[142:145], v[190:193], v[122:125]
	v_mfma_f32_16x16x32_bf16 v[118:121], v[134:137], v[182:185], v[118:121]
	v_mfma_f32_16x16x32_bf16 v[114:117], v[142:145], v[182:185], v[114:117]
	v_mfma_f32_16x16x32_bf16 v[110:113], v[134:137], v[174:177], v[110:113]
	v_mfma_f32_16x16x32_bf16 v[106:109], v[142:145], v[174:177], v[106:109]
	v_mfma_f32_16x16x32_bf16 v[102:105], v[134:137], v[166:169], v[102:105]
	v_mfma_f32_16x16x32_bf16 v[98:101], v[142:145], v[166:169], v[98:101]
	s_barrier
	s_setprio 0
	ds_read_b128 v[146:149], v213
	ds_read_b128 v[150:153], v213 offset:1024
	ds_read_b128 v[154:157], v213 offset:2048
	ds_read_b128 v[158:161], v213 offset:3072
	s_cmp_lt_u32 s26, 5
	s_cselect_b64 s[14:15], -1, 0
	s_mov_b64 s[16:17], -1
	s_and_b64 vcc, exec, s[14:15]
	s_cbranch_vccz .LBB0_427
	s_add_u32 s16, s24, s12
	s_addc_u32 s17, s25, s13
	s_add_u32 s16, s16, 0x2e00180
	s_addc_u32 s17, s17, 0
	v_lshl_add_u64 v[250:251], s[16:17], 0, v[200:201]
	v_readfirstlane_b32 s27, v208
	s_mov_b32 m0, s27
	global_load_lds_dwordx4 v[250:251], off
	v_lshl_add_u64 v[250:251], s[16:17], 0, v[202:203]
	v_readfirstlane_b32 s16, v210
	s_mov_b32 m0, s16
	global_load_lds_dwordx4 v[250:251], off
	s_mov_b64 s[16:17], 0

;   #define LDA(dst,b,h) for(int m=0;m<4;++m)for(int k=0;k<2;++k) \
;     dst[m][k]=*reinterpret_cast<const bf16x8*>((char*)SA(b,h)+lds_byte(wr*64+m*16+fr,k*32+fq*8))
;   #define MMA(ai,bj,At,Bt_) do{__builtin_amdgcn_s_setprio(1); \
;     for(int m=0;m<4;++m)for(int n=0;n<2;++n)for(int k=0;k<2;++k) \
;       acc[ai][bj][m][n]=__builtin_amdgcn_mfma_f32_16x16x32_bf16(Bt_[n][k],At[m][k],acc[ai][bj][m][n],0,0,0); \
;     __builtin_amdgcn_s_setprio(0);}while(0)
;   #define WAIT_L(n) asm volatile("s_waitcnt lgkmcnt(" #n ")":::"memory")
;   #define BAR __builtin_amdgcn_s_barrier()
; template <bool TWO, class MID> ...
;     ...
;     BAR; WAIT_L(0); MMA(0,1,At,B1); BAR;
;     LDA(At,1,1); STAGE_A(SA(1,0),0,t+3);
.LBB0_429:
	s_setprio 1
	s_barrier
	s_waitcnt lgkmcnt(0)
	v_mfma_f32_16x16x32_bf16 v[94:97], v[146:149], v[186:189], v[94:97]
	v_mfma_f32_16x16x32_bf16 v[90:93], v[154:157], v[186:189], v[90:93]
	v_mfma_f32_16x16x32_bf16 v[86:89], v[146:149], v[178:181], v[86:89]
	v_mfma_f32_16x16x32_bf16 v[82:85], v[154:157], v[178:181], v[82:85]
	v_mfma_f32_16x16x32_bf16 v[78:81], v[146:149], v[170:173], v[78:81]
	v_mfma_f32_16x16x32_bf16 v[74:77], v[154:157], v[170:173], v[74:77]
	v_mfma_f32_16x16x32_bf16 v[70:73], v[146:149], v[162:165], v[70:73]
	v_mfma_f32_16x16x32_bf16 v[66:69], v[154:157], v[162:165], v[66:69]
	v_mfma_f32_16x16x32_bf16 v[94:97], v[150:153], v[190:193], v[94:97]
	v_mfma_f32_16x16x32_bf16 v[90:93], v[158:161], v[190:193], v[90:93]
	v_mfma_f32_16x16x32_bf16 v[86:89], v[150:153], v[182:185], v[86:89]
	v_mfma_f32_16x16x32_bf16 v[82:85], v[158:161], v[182:185], v[82:85]
	v_mfma_f32_16x16x32_bf16 v[78:81], v[150:153], v[174:177], v[78:81]
	v_mfma_f32_16x16x32_bf16 v[74:77], v[158:161], v[174:177], v[74:77]
	v_mfma_f32_16x16x32_bf16 v[70:73], v[150:153], v[166:169], v[70:73]
	v_mfma_f32_16x16x32_bf16 v[66:69], v[158:161], v[166:169], v[66:69]
	s_barrier
	s_setprio 0
	ds_read_b128 v[186:189], v211 offset:49152
	ds_read_b128 v[190:193], v211 offset:50176
	ds_read_b128 v[178:181], v209 offset:49152
	ds_read_b128 v[182:185], v209 offset:50176
	ds_read_b128 v[170:173], v207 offset:49152
	ds_read_b128 v[174:177], v207 offset:50176
	ds_read_b128 v[162:165], v205 offset:49152
	ds_read_b128 v[166:169], v205 offset:50176
	s_mov_b64 s[16:17], -1
	s_and_b64 vcc, exec, s[14:15]
	s_cbranch_vccz .LBB0_431
	s_add_u32 s16, s1, s12
	s_addc_u32 s17, s5, s13
	s_add_u32 s16, s16, 0x10000180
	s_addc_u32 s17, s17, 0
	v_lshl_add_u64 v[250:251], s[16:17], 0, v[196:197]
	v_readfirstlane_b32 s27, v212
	s_mov_b32 m0, s27
	global_load_lds_dwordx4 v[250:251], off
	v_lshl_add_u64 v[250:251], s[16:17], 0, v[198:199]
	v_readfirstlane_b32 s16, v214
	s_mov_b32 m0, s16
	global_load_lds_dwordx4 v[250:251], off
	s_mov_b64 s[16:17], 0

;   #define MMA(ai,bj,At,Bt_) do{__builtin_amdgcn_s_setprio(1); \
;     for(int m=0;m<4;++m)for(int n=0;n<2;++n)for(int k=0;k<2;++k) \
;       acc[ai][bj][m][n]=__builtin_amdgcn_mfma_f32_16x16x32_bf16(Bt_[n][k],At[m][k],acc[ai][bj][m][n],0,0,0); \
;     __builtin_amdgcn_s_setprio(0);}while(0)
;   #define WAIT_L(n) asm volatile("s_waitcnt lgkmcnt(" #n ")":::"memory")
;   #define BAR __builtin_amdgcn_s_barrier()
;   #define SCHED __builtin_amdgcn_sched_barrier(0)
; template <bool TWO, class MID> ...
;     ...
;     BAR; WAIT_L(0); MMA(1,0,At,B0); BAR; SCHED;
;     STAGE_B(SB(1,1),1,t+3);
.LBB0_433:
	s_setprio 1
	s_barrier
	s_waitcnt lgkmcnt(0)
	v_mfma_f32_16x16x32_bf16 v[62:65], v[130:133], v[186:189], v[62:65]
	v_mfma_f32_16x16x32_bf16 v[58:61], v[138:141], v[186:189], v[58:61]
	v_mfma_f32_16x16x32_bf16 v[54:57], v[130:133], v[178:181], v[54:57]
	v_mfma_f32_16x16x32_bf16 v[50:53], v[138:141], v[178:181], v[50:53]
	v_mfma_f32_16x16x32_bf16 v[46:49], v[130:133], v[170:173], v[46:49]
	v_mfma_f32_16x16x32_bf16 v[42:45], v[138:141], v[170:173], v[42:45]
	v_mfma_f32_16x16x32_bf16 v[38:41], v[130:133], v[162:165], v[38:41]
	v_mfma_f32_16x16x32_bf16 v[34:37], v[138:141], v[162:165], v[34:37]
	v_mfma_f32_16x16x32_bf16 v[62:65], v[134:137], v[190:193], v[62:65]
	v_mfma_f32_16x16x32_bf16 v[58:61], v[142:145], v[190:193], v[58:61]
	v_mfma_f32_16x16x32_bf16 v[54:57], v[134:137], v[182:185], v[54:57]
	v_mfma_f32_16x16x32_bf16 v[50:53], v[142:145], v[182:185], v[50:53]
	v_mfma_f32_16x16x32_bf16 v[46:49], v[134:137], v[174:177], v[46:49]
	v_mfma_f32_16x16x32_bf16 v[42:45], v[142:145], v[174:177], v[42:45]
	v_mfma_f32_16x16x32_bf16 v[38:41], v[134:137], v[166:169], v[38:41]
	v_mfma_f32_16x16x32_bf16 v[34:37], v[142:145], v[166:169], v[34:37]
	s_barrier
	s_setprio 0
	s_mov_b64 s[16:17], -1
	s_and_b64 vcc, exec, s[14:15]
	s_cbranch_vccz .LBB0_435
	s_add_u32 s14, s24, s12
	s_addc_u32 s15, s25, s13
	s_add_u32 s14, s14, 0x2e20180
	s_addc_u32 s15, s15, 0
	v_lshl_add_u64 v[130:131], s[14:15], 0, v[200:201]
	v_readfirstlane_b32 s16, v220
	s_mov_b32 m0, s16
	global_load_lds_dwordx4 v[130:131], off
	v_lshl_add_u64 v[130:131], s[14:15], 0, v[202:203]
	v_readfirstlane_b32 s14, v226
	s_mov_b32 m0, s14
	global_load_lds_dwordx4 v[130:131], off
	s_mov_b64 s[16:17], 0

;   #define LDA(dst,b,h) for(int m=0;m<4;++m)for(int k=0;k<2;++k) \
;     dst[m][k]=*reinterpret_cast<const bf16x8*>((char*)SA(b,h)+lds_byte(wr*64+m*16+fr,k*32+fq*8))
;   #define LDB(dst,b,h) for(int n=0;n<2;++n)for(int k=0;k<2;++k) \
;     dst[n][k]=*reinterpret_cast<const bf16x8*>((char*)SB(b,h)+lds_byte(wc*32+n*16+fr,k*32+fq*8))
;   #define MMA(ai,bj,At,Bt_) do{__builtin_amdgcn_s_setprio(1); \
;     for(int m=0;m<4;++m)for(int n=0;n<2;++n)for(int k=0;k<2;++k) \
;       acc[ai][bj][m][n]=__builtin_amdgcn_mfma_f32_16x16x32_bf16(Bt_[n][k],At[m][k],acc[ai][bj][m][n],0,0,0); \
;     __builtin_amdgcn_s_setprio(0);}while(0)
;   #define WAIT_V(n) asm volatile("s_waitcnt vmcnt(" #n ")":::"memory")
;   #define WAIT_L(n) asm volatile("s_waitcnt lgkmcnt(" #n ")":::"memory")
;   #define BAR __builtin_amdgcn_s_barrier()
; template <bool TWO, class MID> ...
;     ...
;     WAIT_V(6); BAR; MMA(1,1,At,B1); BAR;
;   }
;   { LDB(B0,0,0); LDA(At,0,0); STAGE_A(SA(1,1),1,nt-1);
;     BAR; WAIT_L(0); MMA(0,0,At,B0); BAR;
;     LDB(B1,0,1); BAR; WAIT_L(0); MMA(0,1,At,B1); BAR;
;     LDA(At,0,1); WAIT_V(4); BAR; WAIT_L(0); MMA(1,0,At,B0); MMA(1,1,At,B1); BAR; }
;   { LDB(B0,1,0); LDA(At,1,0); WAIT_V(2); BAR; WAIT_L(0); MMA(0,0,At,B0); BAR;
.LBB0_437:
	s_waitcnt vmcnt(6)
	s_add_i32 s14, s26, 2
	s_setprio 1
	s_barrier
	v_mfma_f32_16x16x32_bf16 v[30:33], v[146:149], v[186:189], v[30:33]
	v_mfma_f32_16x16x32_bf16 v[26:29], v[154:157], v[186:189], v[26:29]
	v_mfma_f32_16x16x32_bf16 v[22:25], v[146:149], v[178:181], v[22:25]
	v_mfma_f32_16x16x32_bf16 v[18:21], v[154:157], v[178:181], v[18:21]
	v_mfma_f32_16x16x32_bf16 v[14:17], v[146:149], v[170:173], v[14:17]
	v_mfma_f32_16x16x32_bf16 v[10:13], v[154:157], v[170:173], v[10:13]
	v_mfma_f32_16x16x32_bf16 v[6:9], v[146:149], v[162:165], v[6:9]
	v_mfma_f32_16x16x32_bf16 v[2:5], v[154:157], v[162:165], v[2:5]
	v_mfma_f32_16x16x32_bf16 v[30:33], v[150:153], v[190:193], v[30:33]
	v_mfma_f32_16x16x32_bf16 v[26:29], v[158:161], v[190:193], v[26:29]
	v_mfma_f32_16x16x32_bf16 v[22:25], v[150:153], v[182:185], v[22:25]
	v_mfma_f32_16x16x32_bf16 v[18:21], v[158:161], v[182:185], v[18:21]
	v_mfma_f32_16x16x32_bf16 v[14:17], v[150:153], v[174:177], v[14:17]
	v_mfma_f32_16x16x32_bf16 v[10:13], v[158:161], v[174:177], v[10:13]
	v_mfma_f32_16x16x32_bf16 v[6:9], v[150:153], v[166:169], v[6:9]
	v_mfma_f32_16x16x32_bf16 v[2:5], v[158:161], v[166:169], v[2:5]
	s_setprio 0
	s_add_u32 s12, s12, 0x100
	s_addc_u32 s13, s13, 0
	s_cmp_gt_u32 s26, 19
	s_barrier
	s_cbranch_scc1 .LBB0_439
	s_mov_b32 s26, s14
	s_cmpk_lg_i32 s12, 0x400
	s_cbranch_scc0 .LBB0_404
	s_branch .LBB0_405
.LBB0_439:
	ds_read_b128 v[130:133], v219
	ds_read_b128 v[134:137], v219 offset:1024
	ds_read_b128 v[138:141], v219 offset:2048
	ds_read_b128 v[142:145], v219 offset:3072
	ds_read_b128 v[146:149], v211
	ds_read_b128 v[150:153], v211 offset:1024
	ds_read_b128 v[154:157], v209
	ds_read_b128 v[158:161], v209 offset:1024
	ds_read_b128 v[162:165], v207
	ds_read_b128 v[166:169], v207 offset:1024
	ds_read_b128 v[170:173], v205
	ds_read_b128 v[174:177], v205 offset:1024
	s_add_u32 s12, s20, 0xc0780
	s_addc_u32 s13, s21, 0
	v_lshl_add_u64 v[178:179], s[12:13], 0, v[224:225]
	v_readfirstlane_b32 s1, v218
	s_mov_b32 m0, s1
	global_load_lds_dwordx4 v[178:179], off
	v_lshl_add_u64 v[178:179], s[12:13], 0, v[222:223]
	v_readfirstlane_b32 s1, v216
	s_mov_b32 m0, s1
	global_load_lds_dwordx4 v[178:179], off
	s_setprio 1
	s_barrier
	s_waitcnt lgkmcnt(0)
	v_mfma_f32_16x16x32_bf16 v[126:129], v[130:133], v[146:149], v[126:129]
	v_mfma_f32_16x16x32_bf16 v[122:125], v[138:141], v[146:149], v[122:125]
	v_mfma_f32_16x16x32_bf16 v[118:121], v[130:133], v[154:157], v[118:121]
	v_mfma_f32_16x16x32_bf16 v[114:117], v[138:141], v[154:157], v[114:117]
	v_mfma_f32_16x16x32_bf16 v[102:105], v[130:133], v[170:173], v[102:105]
	v_mfma_f32_16x16x32_bf16 v[98:101], v[138:141], v[170:173], v[98:101]
	v_mfma_f32_16x16x32_bf16 v[126:129], v[134:137], v[150:153], v[126:129]
	v_mfma_f32_16x16x32_bf16 v[122:125], v[142:145], v[150:153], v[122:125]
	v_mfma_f32_16x16x32_bf16 v[118:121], v[134:137], v[158:161], v[118:121]
	v_mfma_f32_16x16x32_bf16 v[114:117], v[142:145], v[158:161], v[114:117]
	v_mfma_f32_16x16x32_bf16 v[110:113], v[130:133], v[162:165], v[110:113]
	v_mfma_f32_16x16x32_bf16 v[106:109], v[138:141], v[162:165], v[106:109]
	v_mfma_f32_16x16x32_bf16 v[102:105], v[134:137], v[174:177], v[102:105]
	v_mfma_f32_16x16x32_bf16 v[98:101], v[142:145], v[174:177], v[98:101]
	v_mfma_f32_16x16x32_bf16 v[178:181], v[134:137], v[166:169], v[110:113]
	v_mfma_f32_16x16x32_bf16 v[182:185], v[142:145], v[166:169], v[106:109]
	s_barrier
	s_setprio 0
	s_nop 0
	ds_read_b128 v[106:109], v217
	ds_read_b128 v[110:113], v217 offset:1024
	ds_read_b128 v[186:189], v217 offset:2048
	ds_read_b128 v[190:193], v217 offset:3072
	s_setprio 1
	s_barrier
	s_waitcnt lgkmcnt(0)
	v_mfma_f32_16x16x32_bf16 v[86:89], v[106:109], v[154:157], v[86:89]
	v_mfma_f32_16x16x32_bf16 v[82:85], v[186:189], v[154:157], v[82:85]
	v_mfma_f32_16x16x32_bf16 v[70:73], v[106:109], v[170:173], v[70:73]
	v_mfma_f32_16x16x32_bf16 v[66:69], v[186:189], v[170:173], v[66:69]
	v_mfma_f32_16x16x32_bf16 v[94:97], v[106:109], v[146:149], v[94:97]
	v_mfma_f32_16x16x32_bf16 v[90:93], v[186:189], v[146:149], v[90:93]
	v_mfma_f32_16x16x32_bf16 v[86:89], v[110:113], v[158:161], v[86:89]
	v_mfma_f32_16x16x32_bf16 v[82:85], v[190:193], v[158:161], v[82:85]
	v_mfma_f32_16x16x32_bf16 v[78:81], v[106:109], v[162:165], v[78:81]
	v_mfma_f32_16x16x32_bf16 v[74:77], v[186:189], v[162:165], v[74:77]
	v_mfma_f32_16x16x32_bf16 v[70:73], v[110:113], v[174:177], v[70:73]
	v_mfma_f32_16x16x32_bf16 v[66:69], v[190:193], v[174:177], v[66:69]
	v_mfma_f32_16x16x32_bf16 v[196:199], v[110:113], v[150:153], v[94:97]
	v_mfma_f32_16x16x32_bf16 v[146:149], v[190:193], v[150:153], v[90:93]
	v_mfma_f32_16x16x32_bf16 v[150:153], v[110:113], v[166:169], v[78:81]
	v_mfma_f32_16x16x32_bf16 v[154:157], v[190:193], v[166:169], v[74:77]
	s_barrier
	s_setprio 0
	s_nop 0
	ds_read_b128 v[74:77], v211 offset:16384
	ds_read_b128 v[78:81], v211 offset:17408
	ds_read_b128 v[90:93], v209 offset:16384
	ds_read_b128 v[94:97], v209 offset:17408
	ds_read_b128 v[158:161], v207 offset:16384
	ds_read_b128 v[162:165], v207 offset:17408
	ds_read_b128 v[166:169], v205 offset:16384
	ds_read_b128 v[170:173], v205 offset:17408
	s_waitcnt vmcnt(4)
	s_setprio 1
	s_barrier
;   #define LDA(dst,b,h) for(int m=0;m<4;++m)for(int k=0;k<2;++k) \
;     dst[m][k]=*reinterpret_cast<const bf16x8*>((char*)SA(b,h)+lds_byte(wr*64+m*16+fr,k*32+fq*8))
;   #define LDB(dst,b,h) for(int n=0;n<2;++n)for(int k=0;k<2;++k) \
;     dst[n][k]=*reinterpret_cast<const bf16x8*>((char*)SB(b,h)+lds_byte(wc*32+n*16+fr,k*32+fq*8))
;   #define MMA(ai,bj,At,Bt_) do{__builtin_amdgcn_s_setprio(1); \
;     for(int m=0;m<4;++m)for(int n=0;n<2;++n)for(int k=0;k<2;++k) \
;       acc[ai][bj][m][n]=__builtin_amdgcn_mfma_f32_16x16x32_bf16(Bt_[n][k],At[m][k],acc[ai][bj][m][n],0,0,0); \
;     __builtin_amdgcn_s_setprio(0);}while(0)
;   #define WAIT_V(n) asm volatile("s_waitcnt vmcnt(" #n ")":::"memory")
;   #define WAIT_L(n) asm volatile("s_waitcnt lgkmcnt(" #n ")":::"memory")
;   #define BAR __builtin_amdgcn_s_barrier()
; template <bool TWO, class MID> ...
;     ...
;     LDA(At,0,1); WAIT_V(4); BAR; WAIT_L(0); MMA(1,0,At,B0); MMA(1,1,At,B1); BAR; }
;   { LDB(B0,1,0); LDA(At,1,0); WAIT_V(2); BAR; WAIT_L(0); MMA(0,0,At,B0); BAR;
;     LDB(B1,1,1); WAIT_V(0); BAR; WAIT_L(0); MMA(0,1,At,B1); BAR;
	s_waitcnt lgkmcnt(0)
	v_mfma_f32_16x16x32_bf16 v[62:65], v[130:133], v[74:77], v[62:65]
	v_mfma_f32_16x16x32_bf16 v[58:61], v[138:141], v[74:77], v[58:61]
	v_mfma_f32_16x16x32_bf16 v[54:57], v[130:133], v[90:93], v[54:57]
	v_mfma_f32_16x16x32_bf16 v[50:53], v[138:141], v[90:93], v[50:53]
	v_mfma_f32_16x16x32_bf16 v[38:41], v[130:133], v[166:169], v[38:41]
	v_mfma_f32_16x16x32_bf16 v[34:37], v[138:141], v[166:169], v[34:37]
	v_mfma_f32_16x16x32_bf16 v[62:65], v[134:137], v[78:81], v[62:65]
	v_mfma_f32_16x16x32_bf16 v[58:61], v[142:145], v[78:81], v[58:61]
	v_mfma_f32_16x16x32_bf16 v[54:57], v[134:137], v[94:97], v[54:57]
	v_mfma_f32_16x16x32_bf16 v[50:53], v[142:145], v[94:97], v[50:53]
	v_mfma_f32_16x16x32_bf16 v[46:49], v[130:133], v[158:161], v[46:49]
	v_mfma_f32_16x16x32_bf16 v[42:45], v[138:141], v[158:161], v[42:45]
	v_mfma_f32_16x16x32_bf16 v[38:41], v[134:137], v[170:173], v[38:41]
	v_mfma_f32_16x16x32_bf16 v[34:37], v[142:145], v[170:173], v[34:37]
	v_mfma_f32_16x16x32_bf16 v[174:177], v[134:137], v[162:165], v[46:49]
	v_mfma_f32_16x16x32_bf16 v[200:203], v[142:145], v[162:165], v[42:45]
	s_setprio 0
	s_setprio 1
	v_mfma_f32_16x16x32_bf16 v[22:25], v[106:109], v[90:93], v[22:25]
	v_mfma_f32_16x16x32_bf16 v[18:21], v[186:189], v[90:93], v[18:21]
	v_mfma_f32_16x16x32_bf16 v[6:9], v[106:109], v[166:169], v[6:9]
	v_mfma_f32_16x16x32_bf16 v[2:5], v[186:189], v[166:169], v[2:5]
	v_mfma_f32_16x16x32_bf16 v[30:33], v[106:109], v[74:77], v[30:33]
	v_mfma_f32_16x16x32_bf16 v[26:29], v[186:189], v[74:77], v[26:29]
	v_mfma_f32_16x16x32_bf16 v[22:25], v[110:113], v[94:97], v[22:25]
	v_mfma_f32_16x16x32_bf16 v[18:21], v[190:193], v[94:97], v[18:21]
	v_mfma_f32_16x16x32_bf16 v[14:17], v[106:109], v[158:161], v[14:17]
	v_mfma_f32_16x16x32_bf16 v[10:13], v[186:189], v[158:161], v[10:13]
	v_mfma_f32_16x16x32_bf16 v[6:9], v[110:113], v[170:173], v[6:9]
	v_mfma_f32_16x16x32_bf16 v[2:5], v[190:193], v[170:173], v[2:5]
	v_mfma_f32_16x16x32_bf16 v[130:133], v[110:113], v[78:81], v[30:33]
	v_mfma_f32_16x16x32_bf16 v[134:137], v[190:193], v[78:81], v[26:29]
	v_mfma_f32_16x16x32_bf16 v[138:141], v[110:113], v[162:165], v[14:17]
	v_mfma_f32_16x16x32_bf16 v[142:145], v[190:193], v[162:165], v[10:13]
	s_barrier
	s_setprio 0
	s_nop 0
	ds_read_b128 v[10:13], v215
	ds_read_b128 v[14:17], v215 offset:1024
	ds_read_b128 v[158:161], v215 offset:2048
	ds_read_b128 v[162:165], v215 offset:3072
	ds_read_b128 v[26:29], v211 offset:32768
	ds_read_b128 v[30:33], v211 offset:33792
	ds_read_b128 v[42:45], v209 offset:32768
	ds_read_b128 v[46:49], v209 offset:33792
	ds_read_b128 v[166:169], v207 offset:32768
	ds_read_b128 v[170:173], v207 offset:33792
	ds_read_b128 v[186:189], v205 offset:32768
	ds_read_b128 v[190:193], v205 offset:33792
	s_waitcnt vmcnt(2)
	s_setprio 1
	s_barrier
	s_waitcnt lgkmcnt(0)
	v_mfma_f32_16x16x32_bf16 v[74:77], v[10:13], v[26:29], v[126:129]
	v_mfma_f32_16x16x32_bf16 v[126:129], v[14:17], v[30:33], v[74:77]
	v_mfma_f32_16x16x32_bf16 v[74:77], v[158:161], v[26:29], v[122:125]
	v_mfma_f32_16x16x32_bf16 v[122:125], v[162:165], v[30:33], v[74:77]
	v_mfma_f32_16x16x32_bf16 v[74:77], v[10:13], v[42:45], v[118:121]
	v_mfma_f32_16x16x32_bf16 v[110:113], v[14:17], v[46:49], v[74:77]
	v_mfma_f32_16x16x32_bf16 v[74:77], v[158:161], v[42:45], v[114:117]
	v_mfma_f32_16x16x32_bf16 v[106:109], v[162:165], v[46:49], v[74:77]
	v_mfma_f32_16x16x32_bf16 v[74:77], v[10:13], v[166:169], v[178:181]
	v_mfma_f32_16x16x32_bf16 v[94:97], v[14:17], v[170:173], v[74:77]
	v_mfma_f32_16x16x32_bf16 v[74:77], v[158:161], v[166:169], v[182:185]
	v_mfma_f32_16x16x32_bf16 v[90:93], v[162:165], v[170:173], v[74:77]
	v_mfma_f32_16x16x32_bf16 v[74:77], v[10:13], v[186:189], v[102:105]
	v_mfma_f32_16x16x32_bf16 v[78:81], v[14:17], v[190:193], v[74:77]
	v_mfma_f32_16x16x32_bf16 v[74:77], v[158:161], v[186:189], v[98:101]
	v_mfma_f32_16x16x32_bf16 v[74:77], v[162:165], v[190:193], v[74:77]
	s_barrier
;   #define LDA(dst,b,h) for(int m=0;m<4;++m)for(int k=0;k<2;++k) \
;     dst[m][k]=*reinterpret_cast<const bf16x8*>((char*)SA(b,h)+lds_byte(wr*64+m*16+fr,k*32+fq*8))
;   #define LDB(dst,b,h) for(int n=0;n<2;++n)for(int k=0;k<2;++k) \
;     dst[n][k]=*reinterpret_cast<const bf16x8*>((char*)SB(b,h)+lds_byte(wc*32+n*16+fr,k*32+fq*8))
;   #define MMA(ai,bj,At,Bt_) do{__builtin_amdgcn_s_setprio(1); \
;     for(int m=0;m<4;++m)for(int n=0;n<2;++n)for(int k=0;k<2;++k) \
;       acc[ai][bj][m][n]=__builtin_amdgcn_mfma_f32_16x16x32_bf16(Bt_[n][k],At[m][k],acc[ai][bj][m][n],0,0,0); \
;     __builtin_amdgcn_s_setprio(0);}while(0)
;   #define WAIT_V(n) asm volatile("s_waitcnt vmcnt(" #n ")":::"memory")
;   #define WAIT_L(n) asm volatile("s_waitcnt lgkmcnt(" #n ")":::"memory")
;   #define BAR __builtin_amdgcn_s_barrier()
; template <bool TWO, class MID> ...
;     ...
;     LDB(B1,1,1); WAIT_V(0); BAR; WAIT_L(0); MMA(0,1,At,B1); BAR;
;     LDA(At,1,1); BAR; WAIT_L(0); MMA(1,0,At,B0); MMA(1,1,At,B1); BAR; }
;   if(wr==0)BAR;
	s_setprio 0
	ds_read_b128 v[178:181], v213
	ds_read_b128 v[182:185], v213 offset:1024
	ds_read_b128 v[214:217], v213 offset:2048
	ds_read_b128 v[218:221], v213 offset:3072
	s_waitcnt vmcnt(0)
	s_setprio 1
	s_barrier
	s_waitcnt lgkmcnt(0)
	v_mfma_f32_16x16x32_bf16 v[98:101], v[178:181], v[26:29], v[196:199]
	v_mfma_f32_16x16x32_bf16 v[26:29], v[214:217], v[26:29], v[146:149]
	v_mfma_f32_16x16x32_bf16 v[114:117], v[218:221], v[30:33], v[26:29]
	v_mfma_f32_16x16x32_bf16 v[26:29], v[178:181], v[42:45], v[86:89]
	v_mfma_f32_16x16x32_bf16 v[102:105], v[182:185], v[46:49], v[26:29]
	v_mfma_f32_16x16x32_bf16 v[26:29], v[214:217], v[42:45], v[82:85]
	v_mfma_f32_16x16x32_bf16 v[118:121], v[182:185], v[30:33], v[98:101]
	v_mfma_f32_16x16x32_bf16 v[98:101], v[218:221], v[46:49], v[26:29]
	v_mfma_f32_16x16x32_bf16 v[26:29], v[178:181], v[166:169], v[150:153]
	v_mfma_f32_16x16x32_bf16 v[86:89], v[182:185], v[170:173], v[26:29]
	v_mfma_f32_16x16x32_bf16 v[26:29], v[214:217], v[166:169], v[154:157]
	v_mfma_f32_16x16x32_bf16 v[82:85], v[218:221], v[170:173], v[26:29]
	v_mfma_f32_16x16x32_bf16 v[26:29], v[178:181], v[186:189], v[70:73]
	v_mfma_f32_16x16x32_bf16 v[70:73], v[182:185], v[190:193], v[26:29]
	v_mfma_f32_16x16x32_bf16 v[26:29], v[214:217], v[186:189], v[66:69]
	v_mfma_f32_16x16x32_bf16 v[66:69], v[218:221], v[190:193], v[26:29]
	s_barrier
	s_setprio 0
	ds_read_b128 v[146:149], v211 offset:49152
	ds_read_b128 v[150:153], v211 offset:50176
	ds_read_b128 v[154:157], v209 offset:49152
	ds_read_b128 v[166:169], v209 offset:50176
	ds_read_b128 v[170:173], v207 offset:49152
	ds_read_b128 v[186:189], v207 offset:50176
	ds_read_b128 v[190:193], v205 offset:49152
	ds_read_b128 v[196:199], v205 offset:50176
	s_setprio 1
	s_barrier
	s_waitcnt lgkmcnt(0)
	v_mfma_f32_16x16x32_bf16 v[26:29], v[10:13], v[146:149], v[62:65]
	v_mfma_f32_16x16x32_bf16 v[62:65], v[14:17], v[150:153], v[26:29]
	v_mfma_f32_16x16x32_bf16 v[26:29], v[158:161], v[146:149], v[58:61]
	v_mfma_f32_16x16x32_bf16 v[58:61], v[162:165], v[150:153], v[26:29]
	v_mfma_f32_16x16x32_bf16 v[26:29], v[10:13], v[154:157], v[54:57]
	v_mfma_f32_16x16x32_bf16 v[46:49], v[14:17], v[166:169], v[26:29]
	v_mfma_f32_16x16x32_bf16 v[26:29], v[158:161], v[154:157], v[50:53]
	v_mfma_f32_16x16x32_bf16 v[42:45], v[162:165], v[166:169], v[26:29]
	v_mfma_f32_16x16x32_bf16 v[26:29], v[10:13], v[170:173], v[174:177]
	v_mfma_f32_16x16x32_bf16 v[10:13], v[10:13], v[190:193], v[38:41]
	v_mfma_f32_16x16x32_bf16 v[30:33], v[14:17], v[186:189], v[26:29]
	v_mfma_f32_16x16x32_bf16 v[26:29], v[158:161], v[170:173], v[200:203]
	v_mfma_f32_16x16x32_bf16 v[14:17], v[14:17], v[196:199], v[10:13]
	v_mfma_f32_16x16x32_bf16 v[10:13], v[158:161], v[190:193], v[34:37]
	v_mfma_f32_16x16x32_bf16 v[26:29], v[162:165], v[186:189], v[26:29]
	v_mfma_f32_16x16x32_bf16 v[10:13], v[162:165], v[196:199], v[10:13]
	s_setprio 0
	s_setprio 1
	v_mfma_f32_16x16x32_bf16 v[34:37], v[178:181], v[146:149], v[130:133]
	v_mfma_f32_16x16x32_bf16 v[54:57], v[182:185], v[150:153], v[34:37]
	v_mfma_f32_16x16x32_bf16 v[34:37], v[214:217], v[146:149], v[134:137]
	v_mfma_f32_16x16x32_bf16 v[18:21], v[214:217], v[154:157], v[18:21]
	v_mfma_f32_16x16x32_bf16 v[50:53], v[218:221], v[150:153], v[34:37]
	v_mfma_f32_16x16x32_bf16 v[22:25], v[178:181], v[154:157], v[22:25]
	v_mfma_f32_16x16x32_bf16 v[34:37], v[218:221], v[166:169], v[18:21]
	v_mfma_f32_16x16x32_bf16 v[18:21], v[178:181], v[170:173], v[138:141]
	v_mfma_f32_16x16x32_bf16 v[38:41], v[182:185], v[166:169], v[22:25]
	v_mfma_f32_16x16x32_bf16 v[22:25], v[182:185], v[186:189], v[18:21]
	v_mfma_f32_16x16x32_bf16 v[18:21], v[214:217], v[170:173], v[142:145]
	v_mfma_f32_16x16x32_bf16 v[6:9], v[178:181], v[190:193], v[6:9]
	v_mfma_f32_16x16x32_bf16 v[2:5], v[214:217], v[190:193], v[2:5]
	v_mfma_f32_16x16x32_bf16 v[18:21], v[218:221], v[186:189], v[18:21]
	v_mfma_f32_16x16x32_bf16 v[6:9], v[182:185], v[196:199], v[6:9]
	v_mfma_f32_16x16x32_bf16 v[2:5], v[218:221], v[196:199], v[2:5]
	s_setprio 0
	v_cmp_gt_u32_e32 vcc, s30, v249
	s_barrier
	s_and_saveexec_b64 s[12:13], vcc
	s_cbranch_execz .LBB0_396
	s_barrier
	s_branch .LBB0_396

;   #define LDA(dst,b,h) for(int m=0;m<4;++m)for(int k=0;k<2;++k) \
;     dst[m][k]=*reinterpret_cast<const bf16x8*>((char*)SA(b,h)+lds_byte(wr*64+m*16+fr,k*32+fq*8))
;   #define LDB(dst,b,h) for(int n=0;n<2;++n)for(int k=0;k<2;++k) \
;     dst[n][k]=*reinterpret_cast<const bf16x8*>((char*)SB(b,h)+lds_byte(wc*32+n*16+fr,k*32+fq*8))
;   #define MMA(ai,bj,At,Bt_) do{__builtin_amdgcn_s_setprio(1); \
;     for(int m=0;m<4;++m)for(int n=0;n<2;++n)for(int k=0;k<2;++k) \
;       acc[ai][bj][m][n]=__builtin_amdgcn_mfma_f32_16x16x32_bf16(Bt_[n][k],At[m][k],acc[ai][bj][m][n],0,0,0); \
;     __builtin_amdgcn_s_setprio(0);}while(0)
;   #define WAIT_V(n) asm volatile("s_waitcnt vmcnt(" #n ")":::"memory")
;   #define WAIT_L(n) asm volatile("s_waitcnt lgkmcnt(" #n ")":::"memory")
;   #define BAR __builtin_amdgcn_s_barrier()
;   #define SCHED __builtin_amdgcn_sched_barrier(0)
; template <bool TWO, class MID> ...
;     ...
;   for(int t=0;t<nt-2;t+=2){
;     if (TWO && t == nt1) mid();
;     LDB(B0,0,0); SCHED; LDA(At,0,0); STAGE_A(SA(1,1),1,t+1);
;     WAIT_L(8); BAR; WAIT_L(0); MMA(0,0,At,B0); BAR; SCHED;
;     LDB(B1,0,1); STAGE_B(SB(0,0),0,t+2);
;     BAR; WAIT_L(0); MMA(0,1,At,B1); BAR;
;     LDA(At,0,1); STAGE_A(SA(0,0),0,t+2);
;     BAR; WAIT_L(0); MMA(1,0,At,B0); BAR; SCHED;
;     STAGE_B(SB(0,1),1,t+2);
;     WAIT_V(6); BAR; MMA(1,1,At,B1); BAR;
;     LDB(B0,1,0); SCHED; LDA(At,1,0); STAGE_A(SA(0,1),1,t+2);
;     WAIT_L(8); BAR; WAIT_L(0); MMA(0,0,At,B0); BAR; SCHED;
.LBB0_489:
	ds_read_b128 v[166:169], v149
	ds_read_b128 v[170:173], v149 offset:1024
	ds_read_b128 v[174:177], v149 offset:2048
	ds_read_b128 v[178:181], v149 offset:3072
	ds_read_b128 v[182:185], v141
	ds_read_b128 v[186:189], v141 offset:1024
	ds_read_b128 v[190:193], v139
	ds_read_b128 v[196:199], v139 offset:1024
	ds_read_b128 v[200:203], v137
	ds_read_b128 v[204:207], v137 offset:1024
	ds_read_b128 v[208:211], v135
	ds_read_b128 v[212:215], v135 offset:1024
	s_add_u32 s19, s4, s10
	s_addc_u32 s24, s5, s11
	s_add_u32 s26, s19, 0x36080080
	s_addc_u32 s27, s24, 0
	v_lshl_add_u64 v[216:217], s[26:27], 0, v[132:133]
	v_readfirstlane_b32 s25, v148
	s_mov_b32 m0, s25
	global_load_lds_dwordx4 v[216:217], off
	v_lshl_add_u64 v[216:217], s[26:27], 0, v[130:131]
	v_readfirstlane_b32 s25, v150
	s_mov_b32 m0, s25
	global_load_lds_dwordx4 v[216:217], off
	s_waitcnt lgkmcnt(8)
	s_setprio 1
	s_barrier
	s_waitcnt lgkmcnt(0)
	v_mfma_f32_16x16x32_bf16 v[126:129], v[166:169], v[182:185], v[126:129]
	v_mfma_f32_16x16x32_bf16 v[122:125], v[174:177], v[182:185], v[122:125]
	v_mfma_f32_16x16x32_bf16 v[118:121], v[166:169], v[190:193], v[118:121]
	v_mfma_f32_16x16x32_bf16 v[114:117], v[174:177], v[190:193], v[114:117]
	v_mfma_f32_16x16x32_bf16 v[110:113], v[166:169], v[200:203], v[110:113]
	v_mfma_f32_16x16x32_bf16 v[106:109], v[174:177], v[200:203], v[106:109]
	v_mfma_f32_16x16x32_bf16 v[102:105], v[166:169], v[208:211], v[102:105]
	v_mfma_f32_16x16x32_bf16 v[98:101], v[174:177], v[208:211], v[98:101]
	v_mfma_f32_16x16x32_bf16 v[126:129], v[170:173], v[186:189], v[126:129]
	v_mfma_f32_16x16x32_bf16 v[122:125], v[178:181], v[186:189], v[122:125]
	v_mfma_f32_16x16x32_bf16 v[118:121], v[170:173], v[196:199], v[118:121]
	v_mfma_f32_16x16x32_bf16 v[114:117], v[178:181], v[196:199], v[114:117]
	v_mfma_f32_16x16x32_bf16 v[110:113], v[170:173], v[204:207], v[110:113]
	v_mfma_f32_16x16x32_bf16 v[106:109], v[178:181], v[204:207], v[106:109]
	v_mfma_f32_16x16x32_bf16 v[102:105], v[170:173], v[212:215], v[102:105]
	v_mfma_f32_16x16x32_bf16 v[98:101], v[178:181], v[212:215], v[98:101]
	s_barrier
	s_setprio 0
	s_add_u32 s25, s4, s16
	ds_read_b128 v[216:219], v147
	ds_read_b128 v[220:223], v147 offset:1024
	ds_read_b128 v[224:227], v147 offset:2048
	ds_read_b128 v[228:231], v147 offset:3072
	s_addc_u32 s26, s5, s17
	s_add_u32 s28, s25, 0x3400100
	s_addc_u32 s29, s26, 0
	v_lshl_add_u64 v[232:233], s[28:29], 0, v[132:133]
	v_readfirstlane_b32 s27, v152
	s_mov_b32 m0, s27
	global_load_lds_dwordx4 v[232:233], off
	v_lshl_add_u64 v[232:233], s[28:29], 0, v[130:131]
	v_readfirstlane_b32 s27, v154
	s_mov_b32 m0, s27
	global_load_lds_dwordx4 v[232:233], off
	s_setprio 1
	s_barrier
	s_waitcnt lgkmcnt(0)
	v_mfma_f32_16x16x32_bf16 v[94:97], v[216:219], v[182:185], v[94:97]
	v_mfma_f32_16x16x32_bf16 v[90:93], v[224:227], v[182:185], v[90:93]
	v_mfma_f32_16x16x32_bf16 v[86:89], v[216:219], v[190:193], v[86:89]
	v_mfma_f32_16x16x32_bf16 v[82:85], v[224:227], v[190:193], v[82:85]
	v_mfma_f32_16x16x32_bf16 v[78:81], v[216:219], v[200:203], v[78:81]
	v_mfma_f32_16x16x32_bf16 v[74:77], v[224:227], v[200:203], v[74:77]
	v_mfma_f32_16x16x32_bf16 v[70:73], v[216:219], v[208:211], v[70:73]
	v_mfma_f32_16x16x32_bf16 v[66:69], v[224:227], v[208:211], v[66:69]
	v_mfma_f32_16x16x32_bf16 v[94:97], v[220:223], v[186:189], v[94:97]
	v_mfma_f32_16x16x32_bf16 v[90:93], v[228:231], v[186:189], v[90:93]
	v_mfma_f32_16x16x32_bf16 v[86:89], v[220:223], v[196:199], v[86:89]
	v_mfma_f32_16x16x32_bf16 v[82:85], v[228:231], v[196:199], v[82:85]
	v_mfma_f32_16x16x32_bf16 v[78:81], v[220:223], v[204:207], v[78:81]
	v_mfma_f32_16x16x32_bf16 v[74:77], v[228:231], v[204:207], v[74:77]
	v_mfma_f32_16x16x32_bf16 v[70:73], v[220:223], v[212:215], v[70:73]
	v_mfma_f32_16x16x32_bf16 v[66:69], v[228:231], v[212:215], v[66:69]
	s_barrier
	s_setprio 0
	ds_read_b128 v[182:185], v141 offset:16384
	ds_read_b128 v[186:189], v141 offset:17408
	ds_read_b128 v[190:193], v139 offset:16384
	ds_read_b128 v[196:199], v139 offset:17408
	ds_read_b128 v[200:203], v137 offset:16384
	ds_read_b128 v[204:207], v137 offset:17408
	ds_read_b128 v[208:211], v135 offset:16384
	ds_read_b128 v[212:215], v135 offset:17408
	s_add_u32 s28, s19, 0x36000100
	s_addc_u32 s29, s24, 0
	v_lshl_add_u64 v[232:233], s[28:29], 0, v[132:133]
	v_readfirstlane_b32 s27, v138
	s_mov_b32 m0, s27
	global_load_lds_dwordx4 v[232:233], off
	v_lshl_add_u64 v[232:233], s[28:29], 0, v[130:131]
	v_readfirstlane_b32 s27, v156
	s_mov_b32 m0, s27
	global_load_lds_dwordx4 v[232:233], off
	s_setprio 1
	s_barrier
	s_waitcnt lgkmcnt(0)
	v_mfma_f32_16x16x32_bf16 v[62:65], v[166:169], v[182:185], v[62:65]
	v_mfma_f32_16x16x32_bf16 v[58:61], v[174:177], v[182:185], v[58:61]
	v_mfma_f32_16x16x32_bf16 v[54:57], v[166:169], v[190:193], v[54:57]
	v_mfma_f32_16x16x32_bf16 v[50:53], v[174:177], v[190:193], v[50:53]
	v_mfma_f32_16x16x32_bf16 v[46:49], v[166:169], v[200:203], v[46:49]
	v_mfma_f32_16x16x32_bf16 v[42:45], v[174:177], v[200:203], v[42:45]
	v_mfma_f32_16x16x32_bf16 v[38:41], v[166:169], v[208:211], v[38:41]
	v_mfma_f32_16x16x32_bf16 v[34:37], v[174:177], v[208:211], v[34:37]
	v_mfma_f32_16x16x32_bf16 v[62:65], v[170:173], v[186:189], v[62:65]
	v_mfma_f32_16x16x32_bf16 v[58:61], v[178:181], v[186:189], v[58:61]
	v_mfma_f32_16x16x32_bf16 v[54:57], v[170:173], v[196:199], v[54:57]
	v_mfma_f32_16x16x32_bf16 v[50:53], v[178:181], v[196:199], v[50:53]
	v_mfma_f32_16x16x32_bf16 v[46:49], v[170:173], v[204:207], v[46:49]
	v_mfma_f32_16x16x32_bf16 v[42:45], v[178:181], v[204:207], v[42:45]
	v_mfma_f32_16x16x32_bf16 v[38:41], v[170:173], v[212:215], v[38:41]
	v_mfma_f32_16x16x32_bf16 v[34:37], v[178:181], v[212:215], v[34:37]
	s_barrier
;   #define LDA(dst,b,h) for(int m=0;m<4;++m)for(int k=0;k<2;++k) \
;     dst[m][k]=*reinterpret_cast<const bf16x8*>((char*)SA(b,h)+lds_byte(wr*64+m*16+fr,k*32+fq*8))
;   #define LDB(dst,b,h) for(int n=0;n<2;++n)for(int k=0;k<2;++k) \
;     dst[n][k]=*reinterpret_cast<const bf16x8*>((char*)SB(b,h)+lds_byte(wc*32+n*16+fr,k*32+fq*8))
;   #define MMA(ai,bj,At,Bt_) do{__builtin_amdgcn_s_setprio(1); \
;     for(int m=0;m<4;++m)for(int n=0;n<2;++n)for(int k=0;k<2;++k) \
;       acc[ai][bj][m][n]=__builtin_amdgcn_mfma_f32_16x16x32_bf16(Bt_[n][k],At[m][k],acc[ai][bj][m][n],0,0,0); \
;     __builtin_amdgcn_s_setprio(0);}while(0)
;   #define WAIT_V(n) asm volatile("s_waitcnt vmcnt(" #n ")":::"memory")
;   #define WAIT_L(n) asm volatile("s_waitcnt lgkmcnt(" #n ")":::"memory")
;   #define BAR __builtin_amdgcn_s_barrier()
;   #define SCHED __builtin_amdgcn_sched_barrier(0)
; template <bool TWO, class MID> ...
;     ...
;     WAIT_V(6); BAR; MMA(1,1,At,B1); BAR;
;     LDB(B0,1,0); SCHED; LDA(At,1,0); STAGE_A(SA(0,1),1,t+2);
;     WAIT_L(8); BAR; WAIT_L(0); MMA(0,0,At,B0); BAR; SCHED;
;     LDB(B1,1,1); STAGE_B(SB(1,0),0,t+3);
;     BAR; WAIT_L(0); MMA(0,1,At,B1); BAR;
;     LDA(At,1,1); STAGE_A(SA(1,0),0,t+3);
;     BAR; WAIT_L(0); MMA(1,0,At,B0); BAR; SCHED;
	s_setprio 0
	s_add_u32 s28, s25, 0x3480100
	s_addc_u32 s29, s26, 0
	v_lshl_add_u64 v[166:167], s[28:29], 0, v[132:133]
	v_readfirstlane_b32 s27, v158
	s_mov_b32 m0, s27
	global_load_lds_dwordx4 v[166:167], off
	v_lshl_add_u64 v[166:167], s[28:29], 0, v[130:131]
	v_readfirstlane_b32 s27, v160
	s_mov_b32 m0, s27
	global_load_lds_dwordx4 v[166:167], off
	s_waitcnt vmcnt(6)
	s_setprio 1
	s_barrier
	v_mfma_f32_16x16x32_bf16 v[30:33], v[216:219], v[182:185], v[30:33]
	v_mfma_f32_16x16x32_bf16 v[26:29], v[224:227], v[182:185], v[26:29]
	v_mfma_f32_16x16x32_bf16 v[22:25], v[216:219], v[190:193], v[22:25]
	v_mfma_f32_16x16x32_bf16 v[18:21], v[224:227], v[190:193], v[18:21]
	v_mfma_f32_16x16x32_bf16 v[14:17], v[216:219], v[200:203], v[14:17]
	v_mfma_f32_16x16x32_bf16 v[10:13], v[224:227], v[200:203], v[10:13]
	v_mfma_f32_16x16x32_bf16 v[6:9], v[216:219], v[208:211], v[6:9]
	v_mfma_f32_16x16x32_bf16 v[2:5], v[224:227], v[208:211], v[2:5]
	v_mfma_f32_16x16x32_bf16 v[30:33], v[220:223], v[186:189], v[30:33]
	v_mfma_f32_16x16x32_bf16 v[26:29], v[228:231], v[186:189], v[26:29]
	v_mfma_f32_16x16x32_bf16 v[22:25], v[220:223], v[196:199], v[22:25]
	v_mfma_f32_16x16x32_bf16 v[18:21], v[228:231], v[196:199], v[18:21]
	v_mfma_f32_16x16x32_bf16 v[14:17], v[220:223], v[204:207], v[14:17]
	v_mfma_f32_16x16x32_bf16 v[10:13], v[228:231], v[204:207], v[10:13]
	v_mfma_f32_16x16x32_bf16 v[6:9], v[220:223], v[212:215], v[6:9]
	v_mfma_f32_16x16x32_bf16 v[2:5], v[228:231], v[212:215], v[2:5]
	s_barrier
	s_setprio 0
	ds_read_b128 v[166:169], v145
	ds_read_b128 v[170:173], v145 offset:1024
	ds_read_b128 v[174:177], v145 offset:2048
	ds_read_b128 v[178:181], v145 offset:3072
	ds_read_b128 v[182:185], v141 offset:32768
	ds_read_b128 v[186:189], v141 offset:33792
	ds_read_b128 v[190:193], v139 offset:32768
	ds_read_b128 v[196:199], v139 offset:33792
	ds_read_b128 v[200:203], v137 offset:32768
	ds_read_b128 v[204:207], v137 offset:33792
	ds_read_b128 v[208:211], v135 offset:32768
	ds_read_b128 v[212:215], v135 offset:33792
	s_add_u32 s28, s19, 0x36080100
	s_addc_u32 s29, s24, 0
	v_lshl_add_u64 v[216:217], s[28:29], 0, v[132:133]
	v_readfirstlane_b32 s27, v162
	s_mov_b32 m0, s27
	global_load_lds_dwordx4 v[216:217], off
	v_lshl_add_u64 v[216:217], s[28:29], 0, v[130:131]
	v_readfirstlane_b32 s27, v164
	s_mov_b32 m0, s27
	global_load_lds_dwordx4 v[216:217], off
	s_waitcnt lgkmcnt(8)
	s_setprio 1
	s_barrier
	s_waitcnt lgkmcnt(0)
	v_mfma_f32_16x16x32_bf16 v[126:129], v[166:169], v[182:185], v[126:129]
	v_mfma_f32_16x16x32_bf16 v[122:125], v[174:177], v[182:185], v[122:125]
	v_mfma_f32_16x16x32_bf16 v[118:121], v[166:169], v[190:193], v[118:121]
	v_mfma_f32_16x16x32_bf16 v[114:117], v[174:177], v[190:193], v[114:117]
	v_mfma_f32_16x16x32_bf16 v[110:113], v[166:169], v[200:203], v[110:113]
	v_mfma_f32_16x16x32_bf16 v[106:109], v[174:177], v[200:203], v[106:109]
	v_mfma_f32_16x16x32_bf16 v[102:105], v[166:169], v[208:211], v[102:105]
	v_mfma_f32_16x16x32_bf16 v[98:101], v[174:177], v[208:211], v[98:101]
	v_mfma_f32_16x16x32_bf16 v[126:129], v[170:173], v[186:189], v[126:129]
	v_mfma_f32_16x16x32_bf16 v[122:125], v[178:181], v[186:189], v[122:125]
	v_mfma_f32_16x16x32_bf16 v[118:121], v[170:173], v[196:199], v[118:121]
	v_mfma_f32_16x16x32_bf16 v[114:117], v[178:181], v[196:199], v[114:117]
	v_mfma_f32_16x16x32_bf16 v[110:113], v[170:173], v[204:207], v[110:113]
	v_mfma_f32_16x16x32_bf16 v[106:109], v[178:181], v[204:207], v[106:109]
	v_mfma_f32_16x16x32_bf16 v[102:105], v[170:173], v[212:215], v[102:105]
	v_mfma_f32_16x16x32_bf16 v[98:101], v[178:181], v[212:215], v[98:101]
	s_barrier
	s_setprio 0
	ds_read_b128 v[216:219], v143
	ds_read_b128 v[220:223], v143 offset:1024
	ds_read_b128 v[224:227], v143 offset:2048
	ds_read_b128 v[228:231], v143 offset:3072
	s_add_u32 s28, s25, 0x3400180
	s_addc_u32 s29, s26, 0
	v_lshl_add_u64 v[232:233], s[28:29], 0, v[132:133]
	v_readfirstlane_b32 s27, v134
	s_mov_b32 m0, s27
	global_load_lds_dwordx4 v[232:233], off
	v_lshl_add_u64 v[232:233], s[28:29], 0, v[130:131]
	v_readfirstlane_b32 s27, v136
	s_mov_b32 m0, s27
	global_load_lds_dwordx4 v[232:233], off
	s_setprio 1
	s_barrier
	s_waitcnt lgkmcnt(0)
	v_mfma_f32_16x16x32_bf16 v[94:97], v[216:219], v[182:185], v[94:97]
	v_mfma_f32_16x16x32_bf16 v[90:93], v[224:227], v[182:185], v[90:93]
	v_mfma_f32_16x16x32_bf16 v[86:89], v[216:219], v[190:193], v[86:89]
	v_mfma_f32_16x16x32_bf16 v[82:85], v[224:227], v[190:193], v[82:85]
	v_mfma_f32_16x16x32_bf16 v[78:81], v[216:219], v[200:203], v[78:81]
	v_mfma_f32_16x16x32_bf16 v[74:77], v[224:227], v[200:203], v[74:77]
	v_mfma_f32_16x16x32_bf16 v[70:73], v[216:219], v[208:211], v[70:73]
	v_mfma_f32_16x16x32_bf16 v[66:69], v[224:227], v[208:211], v[66:69]
	v_mfma_f32_16x16x32_bf16 v[94:97], v[220:223], v[186:189], v[94:97]
	v_mfma_f32_16x16x32_bf16 v[90:93], v[228:231], v[186:189], v[90:93]
	v_mfma_f32_16x16x32_bf16 v[86:89], v[220:223], v[196:199], v[86:89]
	v_mfma_f32_16x16x32_bf16 v[82:85], v[228:231], v[196:199], v[82:85]
	v_mfma_f32_16x16x32_bf16 v[78:81], v[220:223], v[204:207], v[78:81]
	v_mfma_f32_16x16x32_bf16 v[74:77], v[228:231], v[204:207], v[74:77]
	v_mfma_f32_16x16x32_bf16 v[70:73], v[220:223], v[212:215], v[70:73]
	v_mfma_f32_16x16x32_bf16 v[66:69], v[228:231], v[212:215], v[66:69]
	s_barrier
;   #define LDA(dst,b,h) for(int m=0;m<4;++m)for(int k=0;k<2;++k) \
;     dst[m][k]=*reinterpret_cast<const bf16x8*>((char*)SA(b,h)+lds_byte(wr*64+m*16+fr,k*32+fq*8))
;   #define LDB(dst,b,h) for(int n=0;n<2;++n)for(int k=0;k<2;++k) \
;     dst[n][k]=*reinterpret_cast<const bf16x8*>((char*)SB(b,h)+lds_byte(wc*32+n*16+fr,k*32+fq*8))
;   #define MMA(ai,bj,At,Bt_) do{__builtin_amdgcn_s_setprio(1); \
;     for(int m=0;m<4;++m)for(int n=0;n<2;++n)for(int k=0;k<2;++k) \
;       acc[ai][bj][m][n]=__builtin_amdgcn_mfma_f32_16x16x32_bf16(Bt_[n][k],At[m][k],acc[ai][bj][m][n],0,0,0); \
;     __builtin_amdgcn_s_setprio(0);}while(0)
;   #define WAIT_V(n) asm volatile("s_waitcnt vmcnt(" #n ")":::"memory")
;   #define WAIT_L(n) asm volatile("s_waitcnt lgkmcnt(" #n ")":::"memory")
;   #define BAR __builtin_amdgcn_s_barrier()
; template <bool TWO, class MID> ...
;     ...
;     STAGE_B(SB(1,1),1,t+3);
;     WAIT_V(6); BAR; MMA(1,1,At,B1); BAR;
;   }
;   { LDB(B0,0,0); LDA(At,0,0); STAGE_A(SA(1,1),1,nt-1);
;     BAR; WAIT_L(0); MMA(0,0,At,B0); BAR;
;     LDB(B1,0,1); BAR; WAIT_L(0); MMA(0,1,At,B1); BAR;
;     LDA(At,0,1); WAIT_V(4); BAR; WAIT_L(0); MMA(1,0,At,B0); MMA(1,1,At,B1); BAR; }
;   { LDB(B0,1,0); LDA(At,1,0); WAIT_V(2); BAR; WAIT_L(0); MMA(0,0,At,B0); BAR;
	s_setprio 0
	ds_read_b128 v[182:185], v141 offset:49152
	ds_read_b128 v[186:189], v141 offset:50176
	ds_read_b128 v[190:193], v139 offset:49152
	ds_read_b128 v[196:199], v139 offset:50176
	ds_read_b128 v[200:203], v137 offset:49152
	ds_read_b128 v[204:207], v137 offset:50176
	ds_read_b128 v[208:211], v135 offset:49152
	ds_read_b128 v[212:215], v135 offset:50176
	s_add_u32 s28, s19, 0x36000180
	s_addc_u32 s29, s24, 0
	v_lshl_add_u64 v[232:233], s[28:29], 0, v[132:133]
	v_readfirstlane_b32 s19, v140
	s_mov_b32 m0, s19
	global_load_lds_dwordx4 v[232:233], off
	v_lshl_add_u64 v[232:233], s[28:29], 0, v[130:131]
	v_readfirstlane_b32 s19, v142
	s_mov_b32 m0, s19
	global_load_lds_dwordx4 v[232:233], off
	s_setprio 1
	s_barrier
	s_waitcnt lgkmcnt(0)
	v_mfma_f32_16x16x32_bf16 v[62:65], v[166:169], v[182:185], v[62:65]
	v_mfma_f32_16x16x32_bf16 v[58:61], v[174:177], v[182:185], v[58:61]
	v_mfma_f32_16x16x32_bf16 v[54:57], v[166:169], v[190:193], v[54:57]
	v_mfma_f32_16x16x32_bf16 v[50:53], v[174:177], v[190:193], v[50:53]
	v_mfma_f32_16x16x32_bf16 v[46:49], v[166:169], v[200:203], v[46:49]
	v_mfma_f32_16x16x32_bf16 v[42:45], v[174:177], v[200:203], v[42:45]
	v_mfma_f32_16x16x32_bf16 v[38:41], v[166:169], v[208:211], v[38:41]
	v_mfma_f32_16x16x32_bf16 v[34:37], v[174:177], v[208:211], v[34:37]
	v_mfma_f32_16x16x32_bf16 v[62:65], v[170:173], v[186:189], v[62:65]
	v_mfma_f32_16x16x32_bf16 v[58:61], v[178:181], v[186:189], v[58:61]
	v_mfma_f32_16x16x32_bf16 v[54:57], v[170:173], v[196:199], v[54:57]
	v_mfma_f32_16x16x32_bf16 v[50:53], v[178:181], v[196:199], v[50:53]
	v_mfma_f32_16x16x32_bf16 v[46:49], v[170:173], v[204:207], v[46:49]
	v_mfma_f32_16x16x32_bf16 v[42:45], v[178:181], v[204:207], v[42:45]
	v_mfma_f32_16x16x32_bf16 v[38:41], v[170:173], v[212:215], v[38:41]
	v_mfma_f32_16x16x32_bf16 v[34:37], v[178:181], v[212:215], v[34:37]
	s_barrier
	s_setprio 0
	s_add_u32 s24, s25, 0x3480180
	s_addc_u32 s25, s26, 0
	v_lshl_add_u64 v[166:167], s[24:25], 0, v[132:133]
	v_readfirstlane_b32 s19, v144
	s_mov_b32 m0, s19
	global_load_lds_dwordx4 v[166:167], off
	v_lshl_add_u64 v[166:167], s[24:25], 0, v[130:131]
	v_readfirstlane_b32 s19, v146
	s_mov_b32 m0, s19
	global_load_lds_dwordx4 v[166:167], off
	s_waitcnt vmcnt(6)
	s_setprio 1
	s_barrier
	v_mfma_f32_16x16x32_bf16 v[30:33], v[216:219], v[182:185], v[30:33]
	v_mfma_f32_16x16x32_bf16 v[26:29], v[224:227], v[182:185], v[26:29]
	v_mfma_f32_16x16x32_bf16 v[22:25], v[216:219], v[190:193], v[22:25]
	v_mfma_f32_16x16x32_bf16 v[18:21], v[224:227], v[190:193], v[18:21]
	v_mfma_f32_16x16x32_bf16 v[14:17], v[216:219], v[200:203], v[14:17]
	v_mfma_f32_16x16x32_bf16 v[10:13], v[224:227], v[200:203], v[10:13]
	v_mfma_f32_16x16x32_bf16 v[6:9], v[216:219], v[208:211], v[6:9]
	v_mfma_f32_16x16x32_bf16 v[2:5], v[224:227], v[208:211], v[2:5]
	v_mfma_f32_16x16x32_bf16 v[30:33], v[220:223], v[186:189], v[30:33]
	v_mfma_f32_16x16x32_bf16 v[26:29], v[228:231], v[186:189], v[26:29]
	v_mfma_f32_16x16x32_bf16 v[22:25], v[220:223], v[196:199], v[22:25]
	v_mfma_f32_16x16x32_bf16 v[18:21], v[228:231], v[196:199], v[18:21]
	v_mfma_f32_16x16x32_bf16 v[14:17], v[220:223], v[204:207], v[14:17]
	v_mfma_f32_16x16x32_bf16 v[10:13], v[228:231], v[204:207], v[10:13]
	v_mfma_f32_16x16x32_bf16 v[6:9], v[220:223], v[212:215], v[6:9]
	v_mfma_f32_16x16x32_bf16 v[2:5], v[228:231], v[212:215], v[2:5]
	s_setprio 0
	s_add_i32 s18, s18, 2
	s_add_u32 s4, s4, 0x100
	s_addc_u32 s5, s5, 0
	s_cmp_lt_u32 s18, 28
	s_barrier
	s_cbranch_scc1 .LBB0_489
	ds_read_b128 v[152:155], v149
	ds_read_b128 v[156:159], v149 offset:1024
	ds_read_b128 v[160:163], v149 offset:2048
	ds_read_b128 v[164:167], v149 offset:3072
	ds_read_b128 v[168:171], v141
	ds_read_b128 v[172:175], v141 offset:1024
	ds_read_b128 v[176:179], v139
	ds_read_b128 v[180:183], v139 offset:1024
	ds_read_b128 v[184:187], v137
	ds_read_b128 v[188:191], v137 offset:1024
	ds_read_b128 v[196:199], v135
	ds_read_b128 v[200:203], v135 offset:1024
	s_add_u32 s4, s12, 0x80f80
	s_addc_u32 s5, s13, 0
	v_lshl_add_u64 v[132:133], s[4:5], 0, v[132:133]
	v_readfirstlane_b32 s12, v148
	s_mov_b32 m0, s12
	global_load_lds_dwordx4 v[132:133], off
	v_lshl_add_u64 v[130:131], s[4:5], 0, v[130:131]
	v_readfirstlane_b32 s4, v150
	s_mov_b32 m0, s4
	global_load_lds_dwordx4 v[130:131], off
	s_setprio 1
	s_barrier
	s_waitcnt lgkmcnt(0)
	v_mfma_f32_16x16x32_bf16 v[126:129], v[152:155], v[168:171], v[126:129]
	v_mfma_f32_16x16x32_bf16 v[122:125], v[160:163], v[168:171], v[122:125]
	v_mfma_f32_16x16x32_bf16 v[118:121], v[152:155], v[176:179], v[118:121]
	v_mfma_f32_16x16x32_bf16 v[114:117], v[160:163], v[176:179], v[114:117]
	v_mfma_f32_16x16x32_bf16 v[102:105], v[152:155], v[196:199], v[102:105]
	v_mfma_f32_16x16x32_bf16 v[98:101], v[160:163], v[196:199], v[98:101]
	v_mfma_f32_16x16x32_bf16 v[126:129], v[156:159], v[172:175], v[126:129]
	v_mfma_f32_16x16x32_bf16 v[122:125], v[164:167], v[172:175], v[122:125]
	v_mfma_f32_16x16x32_bf16 v[118:121], v[156:159], v[180:183], v[118:121]
	v_mfma_f32_16x16x32_bf16 v[114:117], v[164:167], v[180:183], v[114:117]
	v_mfma_f32_16x16x32_bf16 v[110:113], v[152:155], v[184:187], v[110:113]
	v_mfma_f32_16x16x32_bf16 v[106:109], v[160:163], v[184:187], v[106:109]
	v_mfma_f32_16x16x32_bf16 v[102:105], v[156:159], v[200:203], v[102:105]
	v_mfma_f32_16x16x32_bf16 v[98:101], v[164:167], v[200:203], v[98:101]
	v_mfma_f32_16x16x32_bf16 v[130:133], v[156:159], v[188:191], v[110:113]
	v_mfma_f32_16x16x32_bf16 v[148:151], v[164:167], v[188:191], v[106:109]
	s_barrier
	s_setprio 0
	s_nop 0
	ds_read_b128 v[106:109], v147
	ds_read_b128 v[110:113], v147 offset:1024
	ds_read_b128 v[204:207], v147 offset:2048
	ds_read_b128 v[208:211], v147 offset:3072
	s_setprio 1
	s_barrier
;   #define LDA(dst,b,h) for(int m=0;m<4;++m)for(int k=0;k<2;++k) \
;     dst[m][k]=*reinterpret_cast<const bf16x8*>((char*)SA(b,h)+lds_byte(wr*64+m*16+fr,k*32+fq*8))
;   #define LDB(dst,b,h) for(int n=0;n<2;++n)for(int k=0;k<2;++k) \
;     dst[n][k]=*reinterpret_cast<const bf16x8*>((char*)SB(b,h)+lds_byte(wc*32+n*16+fr,k*32+fq*8))
;   #define MMA(ai,bj,At,Bt_) do{__builtin_amdgcn_s_setprio(1); \
;     for(int m=0;m<4;++m)for(int n=0;n<2;++n)for(int k=0;k<2;++k) \
;       acc[ai][bj][m][n]=__builtin_amdgcn_mfma_f32_16x16x32_bf16(Bt_[n][k],At[m][k],acc[ai][bj][m][n],0,0,0); \
;     __builtin_amdgcn_s_setprio(0);}while(0)
;   #define WAIT_V(n) asm volatile("s_waitcnt vmcnt(" #n ")":::"memory")
;   #define WAIT_L(n) asm volatile("s_waitcnt lgkmcnt(" #n ")":::"memory")
;   #define BAR __builtin_amdgcn_s_barrier()
; template <bool TWO, class MID> ...
;     ...
;     LDA(At,0,1); WAIT_V(4); BAR; WAIT_L(0); MMA(1,0,At,B0); MMA(1,1,At,B1); BAR; }
;   { LDB(B0,1,0); LDA(At,1,0); WAIT_V(2); BAR; WAIT_L(0); MMA(0,0,At,B0); BAR;
;     LDB(B1,1,1); WAIT_V(0); BAR; WAIT_L(0); MMA(0,1,At,B1); BAR;
	s_waitcnt lgkmcnt(0)
	v_mfma_f32_16x16x32_bf16 v[86:89], v[106:109], v[176:179], v[86:89]
	v_mfma_f32_16x16x32_bf16 v[82:85], v[204:207], v[176:179], v[82:85]
	v_mfma_f32_16x16x32_bf16 v[70:73], v[106:109], v[196:199], v[70:73]
	v_mfma_f32_16x16x32_bf16 v[66:69], v[204:207], v[196:199], v[66:69]
	v_mfma_f32_16x16x32_bf16 v[94:97], v[106:109], v[168:171], v[94:97]
	v_mfma_f32_16x16x32_bf16 v[90:93], v[204:207], v[168:171], v[90:93]
	v_mfma_f32_16x16x32_bf16 v[86:89], v[110:113], v[180:183], v[86:89]
	v_mfma_f32_16x16x32_bf16 v[82:85], v[208:211], v[180:183], v[82:85]
	v_mfma_f32_16x16x32_bf16 v[78:81], v[106:109], v[184:187], v[78:81]
	v_mfma_f32_16x16x32_bf16 v[74:77], v[204:207], v[184:187], v[74:77]
	v_mfma_f32_16x16x32_bf16 v[70:73], v[110:113], v[200:203], v[70:73]
	v_mfma_f32_16x16x32_bf16 v[66:69], v[208:211], v[200:203], v[66:69]
	v_mfma_f32_16x16x32_bf16 v[212:215], v[110:113], v[172:175], v[94:97]
	v_mfma_f32_16x16x32_bf16 v[168:171], v[208:211], v[172:175], v[90:93]
	v_mfma_f32_16x16x32_bf16 v[172:175], v[110:113], v[188:191], v[78:81]
	v_mfma_f32_16x16x32_bf16 v[176:179], v[208:211], v[188:191], v[74:77]
	s_barrier
	s_setprio 0
	s_nop 0
	ds_read_b128 v[74:77], v141 offset:16384
	ds_read_b128 v[78:81], v141 offset:17408
	ds_read_b128 v[90:93], v139 offset:16384
	ds_read_b128 v[94:97], v139 offset:17408
	ds_read_b128 v[180:183], v137 offset:16384
	ds_read_b128 v[184:187], v137 offset:17408
	ds_read_b128 v[188:191], v135 offset:16384
	ds_read_b128 v[196:199], v135 offset:17408
	s_waitcnt vmcnt(4)
	s_setprio 1
	s_barrier
	s_waitcnt lgkmcnt(0)
	v_mfma_f32_16x16x32_bf16 v[62:65], v[152:155], v[74:77], v[62:65]
	v_mfma_f32_16x16x32_bf16 v[58:61], v[160:163], v[74:77], v[58:61]
	v_mfma_f32_16x16x32_bf16 v[54:57], v[152:155], v[90:93], v[54:57]
	v_mfma_f32_16x16x32_bf16 v[50:53], v[160:163], v[90:93], v[50:53]
	v_mfma_f32_16x16x32_bf16 v[38:41], v[152:155], v[188:191], v[38:41]
	v_mfma_f32_16x16x32_bf16 v[34:37], v[160:163], v[188:191], v[34:37]
	v_mfma_f32_16x16x32_bf16 v[62:65], v[156:159], v[78:81], v[62:65]
	v_mfma_f32_16x16x32_bf16 v[58:61], v[164:167], v[78:81], v[58:61]
	v_mfma_f32_16x16x32_bf16 v[54:57], v[156:159], v[94:97], v[54:57]
	v_mfma_f32_16x16x32_bf16 v[50:53], v[164:167], v[94:97], v[50:53]
	v_mfma_f32_16x16x32_bf16 v[46:49], v[152:155], v[180:183], v[46:49]
	v_mfma_f32_16x16x32_bf16 v[42:45], v[160:163], v[180:183], v[42:45]
	v_mfma_f32_16x16x32_bf16 v[38:41], v[156:159], v[196:199], v[38:41]
	v_mfma_f32_16x16x32_bf16 v[34:37], v[164:167], v[196:199], v[34:37]
	v_mfma_f32_16x16x32_bf16 v[200:203], v[156:159], v[184:187], v[46:49]
	v_mfma_f32_16x16x32_bf16 v[216:219], v[164:167], v[184:187], v[42:45]
	s_setprio 0
	s_setprio 1
	v_mfma_f32_16x16x32_bf16 v[22:25], v[106:109], v[90:93], v[22:25]
	v_mfma_f32_16x16x32_bf16 v[18:21], v[204:207], v[90:93], v[18:21]
	v_mfma_f32_16x16x32_bf16 v[6:9], v[106:109], v[188:191], v[6:9]
	v_mfma_f32_16x16x32_bf16 v[2:5], v[204:207], v[188:191], v[2:5]
	v_mfma_f32_16x16x32_bf16 v[30:33], v[106:109], v[74:77], v[30:33]
	v_mfma_f32_16x16x32_bf16 v[26:29], v[204:207], v[74:77], v[26:29]
	v_mfma_f32_16x16x32_bf16 v[22:25], v[110:113], v[94:97], v[22:25]
	v_mfma_f32_16x16x32_bf16 v[18:21], v[208:211], v[94:97], v[18:21]
	v_mfma_f32_16x16x32_bf16 v[14:17], v[106:109], v[180:183], v[14:17]
	v_mfma_f32_16x16x32_bf16 v[10:13], v[204:207], v[180:183], v[10:13]
	v_mfma_f32_16x16x32_bf16 v[6:9], v[110:113], v[196:199], v[6:9]
	v_mfma_f32_16x16x32_bf16 v[2:5], v[208:211], v[196:199], v[2:5]
	v_mfma_f32_16x16x32_bf16 v[152:155], v[110:113], v[78:81], v[30:33]
	v_mfma_f32_16x16x32_bf16 v[156:159], v[208:211], v[78:81], v[26:29]
	v_mfma_f32_16x16x32_bf16 v[160:163], v[110:113], v[184:187], v[14:17]
	v_mfma_f32_16x16x32_bf16 v[164:167], v[208:211], v[184:187], v[10:13]
	s_barrier
	s_setprio 0
	s_nop 0
	ds_read_b128 v[10:13], v145
	ds_read_b128 v[14:17], v145 offset:1024
	ds_read_b128 v[180:183], v145 offset:2048
	ds_read_b128 v[144:147], v145 offset:3072
	ds_read_b128 v[26:29], v141 offset:32768
	ds_read_b128 v[30:33], v141 offset:33792
	ds_read_b128 v[42:45], v139 offset:32768
	ds_read_b128 v[46:49], v139 offset:33792
	ds_read_b128 v[184:187], v137 offset:32768
	ds_read_b128 v[188:191], v137 offset:33792
	ds_read_b128 v[196:199], v135 offset:32768
	ds_read_b128 v[204:207], v135 offset:33792
	s_waitcnt vmcnt(2)
	s_setprio 1
	s_barrier
;   #define LDA(dst,b,h) for(int m=0;m<4;++m)for(int k=0;k<2;++k) \
;     dst[m][k]=*reinterpret_cast<const bf16x8*>((char*)SA(b,h)+lds_byte(wr*64+m*16+fr,k*32+fq*8))
;   #define LDB(dst,b,h) for(int n=0;n<2;++n)for(int k=0;k<2;++k) \
;     dst[n][k]=*reinterpret_cast<const bf16x8*>((char*)SB(b,h)+lds_byte(wc*32+n*16+fr,k*32+fq*8))
;   #define MMA(ai,bj,At,Bt_) do{__builtin_amdgcn_s_setprio(1); \
;     for(int m=0;m<4;++m)for(int n=0;n<2;++n)for(int k=0;k<2;++k) \
;       acc[ai][bj][m][n]=__builtin_amdgcn_mfma_f32_16x16x32_bf16(Bt_[n][k],At[m][k],acc[ai][bj][m][n],0,0,0); \
;     __builtin_amdgcn_s_setprio(0);}while(0)
;   #define WAIT_V(n) asm volatile("s_waitcnt vmcnt(" #n ")":::"memory")
;   #define WAIT_L(n) asm volatile("s_waitcnt lgkmcnt(" #n ")":::"memory")
;   #define BAR __builtin_amdgcn_s_barrier()
; template <bool TWO, class MID> ...
;     ...
;   { LDB(B0,1,0); LDA(At,1,0); WAIT_V(2); BAR; WAIT_L(0); MMA(0,0,At,B0); BAR;
;     LDB(B1,1,1); WAIT_V(0); BAR; WAIT_L(0); MMA(0,1,At,B1); BAR;
;     LDA(At,1,1); BAR; WAIT_L(0); MMA(1,0,At,B0); MMA(1,1,At,B1); BAR; }
;   if(wr==0)BAR;
	s_waitcnt lgkmcnt(0)
	v_mfma_f32_16x16x32_bf16 v[74:77], v[10:13], v[26:29], v[126:129]
	v_mfma_f32_16x16x32_bf16 v[126:129], v[14:17], v[30:33], v[74:77]
	v_mfma_f32_16x16x32_bf16 v[74:77], v[180:183], v[26:29], v[122:125]
	v_mfma_f32_16x16x32_bf16 v[122:125], v[144:147], v[30:33], v[74:77]
	v_mfma_f32_16x16x32_bf16 v[74:77], v[10:13], v[42:45], v[118:121]
	v_mfma_f32_16x16x32_bf16 v[110:113], v[14:17], v[46:49], v[74:77]
	v_mfma_f32_16x16x32_bf16 v[74:77], v[180:183], v[42:45], v[114:117]
	v_mfma_f32_16x16x32_bf16 v[106:109], v[144:147], v[46:49], v[74:77]
	v_mfma_f32_16x16x32_bf16 v[74:77], v[10:13], v[184:187], v[130:133]
	v_mfma_f32_16x16x32_bf16 v[94:97], v[14:17], v[188:191], v[74:77]
	v_mfma_f32_16x16x32_bf16 v[74:77], v[180:183], v[184:187], v[148:151]
	v_mfma_f32_16x16x32_bf16 v[90:93], v[144:147], v[188:191], v[74:77]
	v_mfma_f32_16x16x32_bf16 v[74:77], v[10:13], v[196:199], v[102:105]
	v_mfma_f32_16x16x32_bf16 v[78:81], v[14:17], v[204:207], v[74:77]
	v_mfma_f32_16x16x32_bf16 v[74:77], v[180:183], v[196:199], v[98:101]
	v_mfma_f32_16x16x32_bf16 v[74:77], v[144:147], v[204:207], v[74:77]
	s_barrier
	s_setprio 0
	ds_read_b128 v[130:133], v143
	ds_read_b128 v[148:151], v143 offset:1024
	ds_read_b128 v[208:211], v143 offset:2048
	ds_read_b128 v[220:223], v143 offset:3072
	s_waitcnt vmcnt(0)
	s_setprio 1
	s_barrier
	s_waitcnt lgkmcnt(0)
	v_mfma_f32_16x16x32_bf16 v[98:101], v[130:133], v[26:29], v[212:215]
	v_mfma_f32_16x16x32_bf16 v[26:29], v[208:211], v[26:29], v[168:171]
	v_mfma_f32_16x16x32_bf16 v[114:117], v[220:223], v[30:33], v[26:29]
	v_mfma_f32_16x16x32_bf16 v[26:29], v[130:133], v[42:45], v[86:89]
	v_mfma_f32_16x16x32_bf16 v[102:105], v[148:151], v[46:49], v[26:29]
	v_mfma_f32_16x16x32_bf16 v[26:29], v[208:211], v[42:45], v[82:85]
	v_mfma_f32_16x16x32_bf16 v[118:121], v[148:151], v[30:33], v[98:101]
	v_mfma_f32_16x16x32_bf16 v[98:101], v[220:223], v[46:49], v[26:29]
	v_mfma_f32_16x16x32_bf16 v[26:29], v[130:133], v[184:187], v[172:175]
	v_mfma_f32_16x16x32_bf16 v[86:89], v[148:151], v[188:191], v[26:29]
	v_mfma_f32_16x16x32_bf16 v[26:29], v[208:211], v[184:187], v[176:179]
	v_mfma_f32_16x16x32_bf16 v[82:85], v[220:223], v[188:191], v[26:29]
	v_mfma_f32_16x16x32_bf16 v[26:29], v[130:133], v[196:199], v[70:73]
	v_mfma_f32_16x16x32_bf16 v[70:73], v[148:151], v[204:207], v[26:29]
	v_mfma_f32_16x16x32_bf16 v[26:29], v[208:211], v[196:199], v[66:69]
	v_mfma_f32_16x16x32_bf16 v[66:69], v[220:223], v[204:207], v[26:29]
	s_barrier
	s_setprio 0
	ds_read_b128 v[168:171], v141 offset:49152
	ds_read_b128 v[140:143], v141 offset:50176
	ds_read_b128 v[172:175], v139 offset:49152
	ds_read_b128 v[176:179], v139 offset:50176
	ds_read_b128 v[184:187], v137 offset:49152
	ds_read_b128 v[136:139], v137 offset:50176
	ds_read_b128 v[188:191], v135 offset:49152
	ds_read_b128 v[196:199], v135 offset:50176
	s_setprio 1
	s_barrier
	s_waitcnt lgkmcnt(0)
	v_mfma_f32_16x16x32_bf16 v[26:29], v[10:13], v[168:171], v[62:65]
	v_mfma_f32_16x16x32_bf16 v[62:65], v[14:17], v[140:143], v[26:29]
	v_mfma_f32_16x16x32_bf16 v[26:29], v[180:183], v[168:171], v[58:61]
	v_mfma_f32_16x16x32_bf16 v[58:61], v[144:147], v[140:143], v[26:29]
	v_mfma_f32_16x16x32_bf16 v[26:29], v[10:13], v[172:175], v[54:57]
	v_mfma_f32_16x16x32_bf16 v[46:49], v[14:17], v[176:179], v[26:29]
	v_mfma_f32_16x16x32_bf16 v[26:29], v[180:183], v[172:175], v[50:53]
	v_mfma_f32_16x16x32_bf16 v[42:45], v[144:147], v[176:179], v[26:29]
	v_mfma_f32_16x16x32_bf16 v[26:29], v[10:13], v[184:187], v[200:203]
	v_mfma_f32_16x16x32_bf16 v[10:13], v[10:13], v[188:191], v[38:41]
	v_mfma_f32_16x16x32_bf16 v[30:33], v[14:17], v[136:139], v[26:29]
	v_mfma_f32_16x16x32_bf16 v[26:29], v[180:183], v[184:187], v[216:219]
	v_mfma_f32_16x16x32_bf16 v[14:17], v[14:17], v[196:199], v[10:13]
	v_mfma_f32_16x16x32_bf16 v[10:13], v[180:183], v[188:191], v[34:37]
	v_mfma_f32_16x16x32_bf16 v[26:29], v[144:147], v[136:139], v[26:29]
	v_mfma_f32_16x16x32_bf16 v[10:13], v[144:147], v[196:199], v[10:13]
	s_setprio 0
	s_setprio 1
	v_mfma_f32_16x16x32_bf16 v[34:37], v[130:133], v[168:171], v[152:155]
	v_mfma_f32_16x16x32_bf16 v[54:57], v[148:151], v[140:143], v[34:37]
	v_mfma_f32_16x16x32_bf16 v[34:37], v[208:211], v[168:171], v[156:159]
	v_mfma_f32_16x16x32_bf16 v[18:21], v[208:211], v[172:175], v[18:21]
	v_mfma_f32_16x16x32_bf16 v[50:53], v[220:223], v[140:143], v[34:37]
	v_mfma_f32_16x16x32_bf16 v[22:25], v[130:133], v[172:175], v[22:25]
	v_mfma_f32_16x16x32_bf16 v[34:37], v[220:223], v[176:179], v[18:21]
	v_mfma_f32_16x16x32_bf16 v[18:21], v[130:133], v[184:187], v[160:163]
	v_mfma_f32_16x16x32_bf16 v[38:41], v[148:151], v[176:179], v[22:25]
	v_mfma_f32_16x16x32_bf16 v[22:25], v[148:151], v[136:139], v[18:21]
	v_mfma_f32_16x16x32_bf16 v[18:21], v[208:211], v[184:187], v[164:167]
	v_mfma_f32_16x16x32_bf16 v[6:9], v[130:133], v[188:191], v[6:9]
	v_mfma_f32_16x16x32_bf16 v[2:5], v[208:211], v[188:191], v[2:5]
	v_mfma_f32_16x16x32_bf16 v[18:21], v[220:223], v[136:139], v[18:21]
	v_mfma_f32_16x16x32_bf16 v[6:9], v[148:151], v[196:199], v[6:9]
	v_mfma_f32_16x16x32_bf16 v[2:5], v[220:223], v[196:199], v[2:5]
	s_setprio 0
	v_cmp_gt_u32_e32 vcc, s30, v1
	s_barrier
	s_and_saveexec_b64 s[4:5], vcc
	s_cbranch_execz .LBB0_492
	s_barrier

;   #define LDA(dst,b,h) for(int m=0;m<4;++m)for(int k=0;k<2;++k) \
;     dst[m][k]=*reinterpret_cast<const bf16x8*>((char*)SA(b,h)+lds_byte(wr*64+m*16+fr,k*32+fq*8))
;   #define LDB(dst,b,h) for(int n=0;n<2;++n)for(int k=0;k<2;++k) \
;     dst[n][k]=*reinterpret_cast<const bf16x8*>((char*)SB(b,h)+lds_byte(wc*32+n*16+fr,k*32+fq*8))
;   #define MMA(ai,bj,At,Bt_) do{__builtin_amdgcn_s_setprio(1); \
;     for(int m=0;m<4;++m)for(int n=0;n<2;++n)for(int k=0;k<2;++k) \
;       acc[ai][bj][m][n]=__builtin_amdgcn_mfma_f32_16x16x32_bf16(Bt_[n][k],At[m][k],acc[ai][bj][m][n],0,0,0); \
;     __builtin_amdgcn_s_setprio(0);}while(0)
;   #define WAIT_V(n) asm volatile("s_waitcnt vmcnt(" #n ")":::"memory")
;   #define WAIT_L(n) asm volatile("s_waitcnt lgkmcnt(" #n ")":::"memory")
;   #define BAR __builtin_amdgcn_s_barrier()
;   #define SCHED __builtin_amdgcn_sched_barrier(0)
; template <bool TWO, class MID> ...
;     ...
;   for(int t=0;t<nt-2;t+=2){
;     if (TWO && t == nt1) mid();
;     LDB(B0,0,0); SCHED; LDA(At,0,0); STAGE_A(SA(1,1),1,t+1);
;     WAIT_L(8); BAR; WAIT_L(0); MMA(0,0,At,B0); BAR; SCHED;
;     LDB(B1,0,1); STAGE_B(SB(0,0),0,t+2);
;     BAR; WAIT_L(0); MMA(0,1,At,B1); BAR;
;     LDA(At,0,1); STAGE_A(SA(0,0),0,t+2);
;     BAR; WAIT_L(0); MMA(1,0,At,B0); BAR; SCHED;
;     STAGE_B(SB(0,1),1,t+2);
;     WAIT_V(6); BAR; MMA(1,1,At,B1); BAR;
;     LDB(B0,1,0); SCHED; LDA(At,1,0); STAGE_A(SA(0,1),1,t+2);
;     WAIT_L(8); BAR; WAIT_L(0); MMA(0,0,At,B0); BAR; SCHED;
.LBB0_562:
	ds_read_b128 v[166:169], v149
	ds_read_b128 v[170:173], v149 offset:1024
	ds_read_b128 v[174:177], v149 offset:2048
	ds_read_b128 v[178:181], v149 offset:3072
	ds_read_b128 v[182:185], v141
	ds_read_b128 v[186:189], v141 offset:1024
	ds_read_b128 v[190:193], v139
	ds_read_b128 v[196:199], v139 offset:1024
	ds_read_b128 v[200:203], v137
	ds_read_b128 v[204:207], v137 offset:1024
	ds_read_b128 v[208:211], v135
	ds_read_b128 v[212:215], v135 offset:1024
	s_add_u32 s23, s4, s12
	s_addc_u32 s24, s5, s13
	s_add_u32 s26, s23, 0x8080080
	s_addc_u32 s27, s24, 0
	v_lshl_add_u64 v[216:217], s[26:27], 0, v[132:133]
	v_readfirstlane_b32 s25, v148
	s_mov_b32 m0, s25
	global_load_lds_dwordx4 v[216:217], off
	v_lshl_add_u64 v[216:217], s[26:27], 0, v[130:131]
	v_readfirstlane_b32 s25, v150
	s_mov_b32 m0, s25
	global_load_lds_dwordx4 v[216:217], off
	s_waitcnt lgkmcnt(8)
	s_setprio 1
	s_barrier
	s_waitcnt lgkmcnt(0)
	v_mfma_f32_16x16x32_bf16 v[126:129], v[166:169], v[182:185], v[126:129]
	v_mfma_f32_16x16x32_bf16 v[122:125], v[174:177], v[182:185], v[122:125]
	v_mfma_f32_16x16x32_bf16 v[118:121], v[166:169], v[190:193], v[118:121]
	v_mfma_f32_16x16x32_bf16 v[114:117], v[174:177], v[190:193], v[114:117]
	v_mfma_f32_16x16x32_bf16 v[110:113], v[166:169], v[200:203], v[110:113]
	v_mfma_f32_16x16x32_bf16 v[106:109], v[174:177], v[200:203], v[106:109]
	v_mfma_f32_16x16x32_bf16 v[102:105], v[166:169], v[208:211], v[102:105]
	v_mfma_f32_16x16x32_bf16 v[98:101], v[174:177], v[208:211], v[98:101]
	v_mfma_f32_16x16x32_bf16 v[126:129], v[170:173], v[186:189], v[126:129]
	v_mfma_f32_16x16x32_bf16 v[122:125], v[178:181], v[186:189], v[122:125]
	v_mfma_f32_16x16x32_bf16 v[118:121], v[170:173], v[196:199], v[118:121]
	v_mfma_f32_16x16x32_bf16 v[114:117], v[178:181], v[196:199], v[114:117]
	v_mfma_f32_16x16x32_bf16 v[110:113], v[170:173], v[204:207], v[110:113]
	v_mfma_f32_16x16x32_bf16 v[106:109], v[178:181], v[204:207], v[106:109]
	v_mfma_f32_16x16x32_bf16 v[102:105], v[170:173], v[212:215], v[102:105]
	v_mfma_f32_16x16x32_bf16 v[98:101], v[178:181], v[212:215], v[98:101]
	s_barrier
	s_setprio 0
	s_add_u32 s25, s4, s14
	ds_read_b128 v[216:219], v147
	ds_read_b128 v[220:223], v147 offset:1024
	ds_read_b128 v[224:227], v147 offset:2048
	ds_read_b128 v[228:231], v147 offset:3072
	s_addc_u32 s26, s5, s15
	s_add_u32 s28, s25, 0x3c00100
	s_addc_u32 s29, s26, 0
	v_lshl_add_u64 v[232:233], s[28:29], 0, v[132:133]
	v_readfirstlane_b32 s27, v152
	s_mov_b32 m0, s27
	global_load_lds_dwordx4 v[232:233], off
	v_lshl_add_u64 v[232:233], s[28:29], 0, v[130:131]
	v_readfirstlane_b32 s27, v154
	s_mov_b32 m0, s27
	global_load_lds_dwordx4 v[232:233], off
	s_setprio 1
	s_barrier
	s_waitcnt lgkmcnt(0)
	v_mfma_f32_16x16x32_bf16 v[94:97], v[216:219], v[182:185], v[94:97]
	v_mfma_f32_16x16x32_bf16 v[90:93], v[224:227], v[182:185], v[90:93]
	v_mfma_f32_16x16x32_bf16 v[86:89], v[216:219], v[190:193], v[86:89]
	v_mfma_f32_16x16x32_bf16 v[82:85], v[224:227], v[190:193], v[82:85]
	v_mfma_f32_16x16x32_bf16 v[78:81], v[216:219], v[200:203], v[78:81]
	v_mfma_f32_16x16x32_bf16 v[74:77], v[224:227], v[200:203], v[74:77]
	v_mfma_f32_16x16x32_bf16 v[70:73], v[216:219], v[208:211], v[70:73]
	v_mfma_f32_16x16x32_bf16 v[66:69], v[224:227], v[208:211], v[66:69]
	v_mfma_f32_16x16x32_bf16 v[94:97], v[220:223], v[186:189], v[94:97]
	v_mfma_f32_16x16x32_bf16 v[90:93], v[228:231], v[186:189], v[90:93]
	v_mfma_f32_16x16x32_bf16 v[86:89], v[220:223], v[196:199], v[86:89]
	v_mfma_f32_16x16x32_bf16 v[82:85], v[228:231], v[196:199], v[82:85]
	v_mfma_f32_16x16x32_bf16 v[78:81], v[220:223], v[204:207], v[78:81]
	v_mfma_f32_16x16x32_bf16 v[74:77], v[228:231], v[204:207], v[74:77]
	v_mfma_f32_16x16x32_bf16 v[70:73], v[220:223], v[212:215], v[70:73]
	v_mfma_f32_16x16x32_bf16 v[66:69], v[228:231], v[212:215], v[66:69]
	s_barrier
	s_setprio 0
	ds_read_b128 v[182:185], v141 offset:16384
	ds_read_b128 v[186:189], v141 offset:17408
	ds_read_b128 v[190:193], v139 offset:16384
	ds_read_b128 v[196:199], v139 offset:17408
	ds_read_b128 v[200:203], v137 offset:16384
	ds_read_b128 v[204:207], v137 offset:17408
	ds_read_b128 v[208:211], v135 offset:16384
	ds_read_b128 v[212:215], v135 offset:17408
	s_add_u32 s28, s23, 0x8000100
	s_addc_u32 s29, s24, 0
	v_lshl_add_u64 v[232:233], s[28:29], 0, v[132:133]
	v_readfirstlane_b32 s27, v138
	s_mov_b32 m0, s27
	global_load_lds_dwordx4 v[232:233], off
	v_lshl_add_u64 v[232:233], s[28:29], 0, v[130:131]
	v_readfirstlane_b32 s27, v156
	s_mov_b32 m0, s27
	global_load_lds_dwordx4 v[232:233], off
	s_setprio 1
	s_barrier
	s_waitcnt lgkmcnt(0)
	v_mfma_f32_16x16x32_bf16 v[62:65], v[166:169], v[182:185], v[62:65]
	v_mfma_f32_16x16x32_bf16 v[58:61], v[174:177], v[182:185], v[58:61]
	v_mfma_f32_16x16x32_bf16 v[54:57], v[166:169], v[190:193], v[54:57]
	v_mfma_f32_16x16x32_bf16 v[50:53], v[174:177], v[190:193], v[50:53]
	v_mfma_f32_16x16x32_bf16 v[46:49], v[166:169], v[200:203], v[46:49]
	v_mfma_f32_16x16x32_bf16 v[42:45], v[174:177], v[200:203], v[42:45]
	v_mfma_f32_16x16x32_bf16 v[38:41], v[166:169], v[208:211], v[38:41]
	v_mfma_f32_16x16x32_bf16 v[34:37], v[174:177], v[208:211], v[34:37]
	v_mfma_f32_16x16x32_bf16 v[62:65], v[170:173], v[186:189], v[62:65]
	v_mfma_f32_16x16x32_bf16 v[58:61], v[178:181], v[186:189], v[58:61]
	v_mfma_f32_16x16x32_bf16 v[54:57], v[170:173], v[196:199], v[54:57]
	v_mfma_f32_16x16x32_bf16 v[50:53], v[178:181], v[196:199], v[50:53]
	v_mfma_f32_16x16x32_bf16 v[46:49], v[170:173], v[204:207], v[46:49]
	v_mfma_f32_16x16x32_bf16 v[42:45], v[178:181], v[204:207], v[42:45]
	v_mfma_f32_16x16x32_bf16 v[38:41], v[170:173], v[212:215], v[38:41]
	v_mfma_f32_16x16x32_bf16 v[34:37], v[178:181], v[212:215], v[34:37]
	s_barrier
;   #define LDA(dst,b,h) for(int m=0;m<4;++m)for(int k=0;k<2;++k) \
;     dst[m][k]=*reinterpret_cast<const bf16x8*>((char*)SA(b,h)+lds_byte(wr*64+m*16+fr,k*32+fq*8))
;   #define LDB(dst,b,h) for(int n=0;n<2;++n)for(int k=0;k<2;++k) \
;     dst[n][k]=*reinterpret_cast<const bf16x8*>((char*)SB(b,h)+lds_byte(wc*32+n*16+fr,k*32+fq*8))
;   #define MMA(ai,bj,At,Bt_) do{__builtin_amdgcn_s_setprio(1); \
;     for(int m=0;m<4;++m)for(int n=0;n<2;++n)for(int k=0;k<2;++k) \
;       acc[ai][bj][m][n]=__builtin_amdgcn_mfma_f32_16x16x32_bf16(Bt_[n][k],At[m][k],acc[ai][bj][m][n],0,0,0); \
;     __builtin_amdgcn_s_setprio(0);}while(0)
;   #define WAIT_V(n) asm volatile("s_waitcnt vmcnt(" #n ")":::"memory")
;   #define WAIT_L(n) asm volatile("s_waitcnt lgkmcnt(" #n ")":::"memory")
;   #define BAR __builtin_amdgcn_s_barrier()
;   #define SCHED __builtin_amdgcn_sched_barrier(0)
; template <bool TWO, class MID> ...
;     ...
;     WAIT_V(6); BAR; MMA(1,1,At,B1); BAR;
;     LDB(B0,1,0); SCHED; LDA(At,1,0); STAGE_A(SA(0,1),1,t+2);
;     WAIT_L(8); BAR; WAIT_L(0); MMA(0,0,At,B0); BAR; SCHED;
;     LDB(B1,1,1); STAGE_B(SB(1,0),0,t+3);
;     BAR; WAIT_L(0); MMA(0,1,At,B1); BAR;
;     LDA(At,1,1); STAGE_A(SA(1,0),0,t+3);
;     BAR; WAIT_L(0); MMA(1,0,At,B0); BAR; SCHED;
	s_setprio 0
	s_add_u32 s28, s25, 0x3c80100
	s_addc_u32 s29, s26, 0
	v_lshl_add_u64 v[166:167], s[28:29], 0, v[132:133]
	v_readfirstlane_b32 s27, v158
	s_mov_b32 m0, s27
	global_load_lds_dwordx4 v[166:167], off
	v_lshl_add_u64 v[166:167], s[28:29], 0, v[130:131]
	v_readfirstlane_b32 s27, v160
	s_mov_b32 m0, s27
	global_load_lds_dwordx4 v[166:167], off
	s_waitcnt vmcnt(6)
	s_setprio 1
	s_barrier
	v_mfma_f32_16x16x32_bf16 v[30:33], v[216:219], v[182:185], v[30:33]
	v_mfma_f32_16x16x32_bf16 v[26:29], v[224:227], v[182:185], v[26:29]
	v_mfma_f32_16x16x32_bf16 v[22:25], v[216:219], v[190:193], v[22:25]
	v_mfma_f32_16x16x32_bf16 v[18:21], v[224:227], v[190:193], v[18:21]
	v_mfma_f32_16x16x32_bf16 v[14:17], v[216:219], v[200:203], v[14:17]
	v_mfma_f32_16x16x32_bf16 v[10:13], v[224:227], v[200:203], v[10:13]
	v_mfma_f32_16x16x32_bf16 v[6:9], v[216:219], v[208:211], v[6:9]
	v_mfma_f32_16x16x32_bf16 v[2:5], v[224:227], v[208:211], v[2:5]
	v_mfma_f32_16x16x32_bf16 v[30:33], v[220:223], v[186:189], v[30:33]
	v_mfma_f32_16x16x32_bf16 v[26:29], v[228:231], v[186:189], v[26:29]
	v_mfma_f32_16x16x32_bf16 v[22:25], v[220:223], v[196:199], v[22:25]
	v_mfma_f32_16x16x32_bf16 v[18:21], v[228:231], v[196:199], v[18:21]
	v_mfma_f32_16x16x32_bf16 v[14:17], v[220:223], v[204:207], v[14:17]
	v_mfma_f32_16x16x32_bf16 v[10:13], v[228:231], v[204:207], v[10:13]
	v_mfma_f32_16x16x32_bf16 v[6:9], v[220:223], v[212:215], v[6:9]
	v_mfma_f32_16x16x32_bf16 v[2:5], v[228:231], v[212:215], v[2:5]
	s_barrier
	s_setprio 0
	ds_read_b128 v[166:169], v145
	ds_read_b128 v[170:173], v145 offset:1024
	ds_read_b128 v[174:177], v145 offset:2048
	ds_read_b128 v[178:181], v145 offset:3072
	ds_read_b128 v[182:185], v141 offset:32768
	ds_read_b128 v[186:189], v141 offset:33792
	ds_read_b128 v[190:193], v139 offset:32768
	ds_read_b128 v[196:199], v139 offset:33792
	ds_read_b128 v[200:203], v137 offset:32768
	ds_read_b128 v[204:207], v137 offset:33792
	ds_read_b128 v[208:211], v135 offset:32768
	ds_read_b128 v[212:215], v135 offset:33792
	s_add_u32 s28, s23, 0x8080100
	s_addc_u32 s29, s24, 0
	v_lshl_add_u64 v[216:217], s[28:29], 0, v[132:133]
	v_readfirstlane_b32 s27, v162
	s_mov_b32 m0, s27
	global_load_lds_dwordx4 v[216:217], off
	v_lshl_add_u64 v[216:217], s[28:29], 0, v[130:131]
	v_readfirstlane_b32 s27, v164
	s_mov_b32 m0, s27
	global_load_lds_dwordx4 v[216:217], off
	s_waitcnt lgkmcnt(8)
	s_setprio 1
	s_barrier
	s_waitcnt lgkmcnt(0)
	v_mfma_f32_16x16x32_bf16 v[126:129], v[166:169], v[182:185], v[126:129]
	v_mfma_f32_16x16x32_bf16 v[122:125], v[174:177], v[182:185], v[122:125]
	v_mfma_f32_16x16x32_bf16 v[118:121], v[166:169], v[190:193], v[118:121]
	v_mfma_f32_16x16x32_bf16 v[114:117], v[174:177], v[190:193], v[114:117]
	v_mfma_f32_16x16x32_bf16 v[110:113], v[166:169], v[200:203], v[110:113]
	v_mfma_f32_16x16x32_bf16 v[106:109], v[174:177], v[200:203], v[106:109]
	v_mfma_f32_16x16x32_bf16 v[102:105], v[166:169], v[208:211], v[102:105]
	v_mfma_f32_16x16x32_bf16 v[98:101], v[174:177], v[208:211], v[98:101]
	v_mfma_f32_16x16x32_bf16 v[126:129], v[170:173], v[186:189], v[126:129]
	v_mfma_f32_16x16x32_bf16 v[122:125], v[178:181], v[186:189], v[122:125]
	v_mfma_f32_16x16x32_bf16 v[118:121], v[170:173], v[196:199], v[118:121]
	v_mfma_f32_16x16x32_bf16 v[114:117], v[178:181], v[196:199], v[114:117]
	v_mfma_f32_16x16x32_bf16 v[110:113], v[170:173], v[204:207], v[110:113]
	v_mfma_f32_16x16x32_bf16 v[106:109], v[178:181], v[204:207], v[106:109]
	v_mfma_f32_16x16x32_bf16 v[102:105], v[170:173], v[212:215], v[102:105]
	v_mfma_f32_16x16x32_bf16 v[98:101], v[178:181], v[212:215], v[98:101]
	s_barrier
	s_setprio 0
	ds_read_b128 v[216:219], v143
	ds_read_b128 v[220:223], v143 offset:1024
	ds_read_b128 v[224:227], v143 offset:2048
	ds_read_b128 v[228:231], v143 offset:3072
	s_add_u32 s28, s25, 0x3c00180
	s_addc_u32 s29, s26, 0
	v_lshl_add_u64 v[232:233], s[28:29], 0, v[132:133]
	v_readfirstlane_b32 s27, v134
	s_mov_b32 m0, s27
	global_load_lds_dwordx4 v[232:233], off
	v_lshl_add_u64 v[232:233], s[28:29], 0, v[130:131]
	v_readfirstlane_b32 s27, v136
	s_mov_b32 m0, s27
	global_load_lds_dwordx4 v[232:233], off
	s_setprio 1
	s_barrier
	s_waitcnt lgkmcnt(0)
	v_mfma_f32_16x16x32_bf16 v[94:97], v[216:219], v[182:185], v[94:97]
	v_mfma_f32_16x16x32_bf16 v[90:93], v[224:227], v[182:185], v[90:93]
	v_mfma_f32_16x16x32_bf16 v[86:89], v[216:219], v[190:193], v[86:89]
	v_mfma_f32_16x16x32_bf16 v[82:85], v[224:227], v[190:193], v[82:85]
	v_mfma_f32_16x16x32_bf16 v[78:81], v[216:219], v[200:203], v[78:81]
	v_mfma_f32_16x16x32_bf16 v[74:77], v[224:227], v[200:203], v[74:77]
	v_mfma_f32_16x16x32_bf16 v[70:73], v[216:219], v[208:211], v[70:73]
	v_mfma_f32_16x16x32_bf16 v[66:69], v[224:227], v[208:211], v[66:69]
	v_mfma_f32_16x16x32_bf16 v[94:97], v[220:223], v[186:189], v[94:97]
	v_mfma_f32_16x16x32_bf16 v[90:93], v[228:231], v[186:189], v[90:93]
	v_mfma_f32_16x16x32_bf16 v[86:89], v[220:223], v[196:199], v[86:89]
	v_mfma_f32_16x16x32_bf16 v[82:85], v[228:231], v[196:199], v[82:85]
	v_mfma_f32_16x16x32_bf16 v[78:81], v[220:223], v[204:207], v[78:81]
	v_mfma_f32_16x16x32_bf16 v[74:77], v[228:231], v[204:207], v[74:77]
	v_mfma_f32_16x16x32_bf16 v[70:73], v[220:223], v[212:215], v[70:73]
	v_mfma_f32_16x16x32_bf16 v[66:69], v[228:231], v[212:215], v[66:69]
	s_barrier
;   #define LDA(dst,b,h) for(int m=0;m<4;++m)for(int k=0;k<2;++k) \
;     dst[m][k]=*reinterpret_cast<const bf16x8*>((char*)SA(b,h)+lds_byte(wr*64+m*16+fr,k*32+fq*8))
;   #define LDB(dst,b,h) for(int n=0;n<2;++n)for(int k=0;k<2;++k) \
;     dst[n][k]=*reinterpret_cast<const bf16x8*>((char*)SB(b,h)+lds_byte(wc*32+n*16+fr,k*32+fq*8))
;   #define MMA(ai,bj,At,Bt_) do{__builtin_amdgcn_s_setprio(1); \
;     for(int m=0;m<4;++m)for(int n=0;n<2;++n)for(int k=0;k<2;++k) \
;       acc[ai][bj][m][n]=__builtin_amdgcn_mfma_f32_16x16x32_bf16(Bt_[n][k],At[m][k],acc[ai][bj][m][n],0,0,0); \
;     __builtin_amdgcn_s_setprio(0);}while(0)
;   #define WAIT_V(n) asm volatile("s_waitcnt vmcnt(" #n ")":::"memory")
;   #define WAIT_L(n) asm volatile("s_waitcnt lgkmcnt(" #n ")":::"memory")
;   #define BAR __builtin_amdgcn_s_barrier()
;   #define SCHED __builtin_amdgcn_sched_barrier(0)
; template <bool TWO, class MID> ...
;     ...
;     BAR; WAIT_L(0); MMA(0,1,At,B1); BAR;
;     LDA(At,1,1); STAGE_A(SA(1,0),0,t+3);
;     BAR; WAIT_L(0); MMA(1,0,At,B0); BAR; SCHED;
;     STAGE_B(SB(1,1),1,t+3);
;     WAIT_V(6); BAR; MMA(1,1,At,B1); BAR;
;   }
;   { LDB(B0,0,0); LDA(At,0,0); STAGE_A(SA(1,1),1,nt-1);
;     BAR; WAIT_L(0); MMA(0,0,At,B0); BAR;
;     LDB(B1,0,1); BAR; WAIT_L(0); MMA(0,1,At,B1); BAR;
	s_setprio 0
	ds_read_b128 v[182:185], v141 offset:49152
	ds_read_b128 v[186:189], v141 offset:50176
	ds_read_b128 v[190:193], v139 offset:49152
	ds_read_b128 v[196:199], v139 offset:50176
	ds_read_b128 v[200:203], v137 offset:49152
	ds_read_b128 v[204:207], v137 offset:50176
	ds_read_b128 v[208:211], v135 offset:49152
	ds_read_b128 v[212:215], v135 offset:50176
	s_add_u32 s28, s23, 0x8000180
	s_addc_u32 s29, s24, 0
	v_lshl_add_u64 v[232:233], s[28:29], 0, v[132:133]
	v_readfirstlane_b32 s23, v140
	s_mov_b32 m0, s23
	global_load_lds_dwordx4 v[232:233], off
	v_lshl_add_u64 v[232:233], s[28:29], 0, v[130:131]
	v_readfirstlane_b32 s23, v142
	s_mov_b32 m0, s23
	global_load_lds_dwordx4 v[232:233], off
	s_setprio 1
	s_barrier
	s_waitcnt lgkmcnt(0)
	v_mfma_f32_16x16x32_bf16 v[62:65], v[166:169], v[182:185], v[62:65]
	v_mfma_f32_16x16x32_bf16 v[58:61], v[174:177], v[182:185], v[58:61]
	v_mfma_f32_16x16x32_bf16 v[54:57], v[166:169], v[190:193], v[54:57]
	v_mfma_f32_16x16x32_bf16 v[50:53], v[174:177], v[190:193], v[50:53]
	v_mfma_f32_16x16x32_bf16 v[46:49], v[166:169], v[200:203], v[46:49]
	v_mfma_f32_16x16x32_bf16 v[42:45], v[174:177], v[200:203], v[42:45]
	v_mfma_f32_16x16x32_bf16 v[38:41], v[166:169], v[208:211], v[38:41]
	v_mfma_f32_16x16x32_bf16 v[34:37], v[174:177], v[208:211], v[34:37]
	v_mfma_f32_16x16x32_bf16 v[62:65], v[170:173], v[186:189], v[62:65]
	v_mfma_f32_16x16x32_bf16 v[58:61], v[178:181], v[186:189], v[58:61]
	v_mfma_f32_16x16x32_bf16 v[54:57], v[170:173], v[196:199], v[54:57]
	v_mfma_f32_16x16x32_bf16 v[50:53], v[178:181], v[196:199], v[50:53]
	v_mfma_f32_16x16x32_bf16 v[46:49], v[170:173], v[204:207], v[46:49]
	v_mfma_f32_16x16x32_bf16 v[42:45], v[178:181], v[204:207], v[42:45]
	v_mfma_f32_16x16x32_bf16 v[38:41], v[170:173], v[212:215], v[38:41]
	v_mfma_f32_16x16x32_bf16 v[34:37], v[178:181], v[212:215], v[34:37]
	s_barrier
	s_setprio 0
	s_add_u32 s24, s25, 0x3c80180
	s_addc_u32 s25, s26, 0
	v_lshl_add_u64 v[166:167], s[24:25], 0, v[132:133]
	v_readfirstlane_b32 s23, v144
	s_mov_b32 m0, s23
	global_load_lds_dwordx4 v[166:167], off
	v_lshl_add_u64 v[166:167], s[24:25], 0, v[130:131]
	v_readfirstlane_b32 s23, v146
	s_mov_b32 m0, s23
	global_load_lds_dwordx4 v[166:167], off
	s_waitcnt vmcnt(6)
	s_setprio 1
	s_barrier
	v_mfma_f32_16x16x32_bf16 v[30:33], v[216:219], v[182:185], v[30:33]
	v_mfma_f32_16x16x32_bf16 v[26:29], v[224:227], v[182:185], v[26:29]
	v_mfma_f32_16x16x32_bf16 v[22:25], v[216:219], v[190:193], v[22:25]
	v_mfma_f32_16x16x32_bf16 v[18:21], v[224:227], v[190:193], v[18:21]
	v_mfma_f32_16x16x32_bf16 v[14:17], v[216:219], v[200:203], v[14:17]
	v_mfma_f32_16x16x32_bf16 v[10:13], v[224:227], v[200:203], v[10:13]
	v_mfma_f32_16x16x32_bf16 v[6:9], v[216:219], v[208:211], v[6:9]
	v_mfma_f32_16x16x32_bf16 v[2:5], v[224:227], v[208:211], v[2:5]
	v_mfma_f32_16x16x32_bf16 v[30:33], v[220:223], v[186:189], v[30:33]
	v_mfma_f32_16x16x32_bf16 v[26:29], v[228:231], v[186:189], v[26:29]
	v_mfma_f32_16x16x32_bf16 v[22:25], v[220:223], v[196:199], v[22:25]
	v_mfma_f32_16x16x32_bf16 v[18:21], v[228:231], v[196:199], v[18:21]
	v_mfma_f32_16x16x32_bf16 v[14:17], v[220:223], v[204:207], v[14:17]
	v_mfma_f32_16x16x32_bf16 v[10:13], v[228:231], v[204:207], v[10:13]
	v_mfma_f32_16x16x32_bf16 v[6:9], v[220:223], v[212:215], v[6:9]
	v_mfma_f32_16x16x32_bf16 v[2:5], v[228:231], v[212:215], v[2:5]
	s_setprio 0
	s_add_i32 s22, s22, 2
	s_add_u32 s4, s4, 0x100
	s_addc_u32 s5, s5, 0
	s_cmp_lt_u32 s22, 28
	s_barrier
	s_cbranch_scc1 .LBB0_562
	ds_read_b128 v[152:155], v149
	ds_read_b128 v[156:159], v149 offset:1024
	ds_read_b128 v[160:163], v149 offset:2048
	ds_read_b128 v[164:167], v149 offset:3072
	ds_read_b128 v[168:171], v141
	ds_read_b128 v[172:175], v141 offset:1024
	ds_read_b128 v[176:179], v139
	ds_read_b128 v[180:183], v139 offset:1024
	ds_read_b128 v[184:187], v137
	ds_read_b128 v[188:191], v137 offset:1024
	ds_read_b128 v[196:199], v135
	ds_read_b128 v[200:203], v135 offset:1024
	s_add_u32 s4, s19, 0x80f80
	s_addc_u32 s5, s21, 0
	v_lshl_add_u64 v[132:133], s[4:5], 0, v[132:133]
	v_readfirstlane_b32 s12, v148
	s_mov_b32 m0, s12
	global_load_lds_dwordx4 v[132:133], off
	v_lshl_add_u64 v[130:131], s[4:5], 0, v[130:131]
	v_readfirstlane_b32 s4, v150
	s_mov_b32 m0, s4
	global_load_lds_dwordx4 v[130:131], off
	s_setprio 1
	s_barrier
	s_waitcnt lgkmcnt(0)
	v_mfma_f32_16x16x32_bf16 v[126:129], v[152:155], v[168:171], v[126:129]
	v_mfma_f32_16x16x32_bf16 v[122:125], v[160:163], v[168:171], v[122:125]
	v_mfma_f32_16x16x32_bf16 v[114:117], v[160:163], v[176:179], v[114:117]
	v_mfma_f32_16x16x32_bf16 v[106:109], v[160:163], v[184:187], v[106:109]
	v_mfma_f32_16x16x32_bf16 v[98:101], v[160:163], v[196:199], v[98:101]
	v_mfma_f32_16x16x32_bf16 v[126:129], v[156:159], v[172:175], v[126:129]
	v_mfma_f32_16x16x32_bf16 v[122:125], v[164:167], v[172:175], v[122:125]
	v_mfma_f32_16x16x32_bf16 v[118:121], v[152:155], v[176:179], v[118:121]
	v_mfma_f32_16x16x32_bf16 v[114:117], v[164:167], v[180:183], v[114:117]
	v_mfma_f32_16x16x32_bf16 v[110:113], v[152:155], v[184:187], v[110:113]
	v_mfma_f32_16x16x32_bf16 v[106:109], v[164:167], v[188:191], v[106:109]
	v_mfma_f32_16x16x32_bf16 v[102:105], v[152:155], v[196:199], v[102:105]
	v_mfma_f32_16x16x32_bf16 v[98:101], v[164:167], v[200:203], v[98:101]
	v_mfma_f32_16x16x32_bf16 v[130:133], v[156:159], v[180:183], v[118:121]
	v_mfma_f32_16x16x32_bf16 v[148:151], v[156:159], v[188:191], v[110:113]
	v_mfma_f32_16x16x32_bf16 v[204:207], v[156:159], v[200:203], v[102:105]
	s_barrier
	s_setprio 0
	s_nop 0
	ds_read_b128 v[102:105], v147
	ds_read_b128 v[110:113], v147 offset:1024
	ds_read_b128 v[118:121], v147 offset:2048
	ds_read_b128 v[208:211], v147 offset:3072
	s_setprio 1
	s_barrier
;   #define LDA(dst,b,h) for(int m=0;m<4;++m)for(int k=0;k<2;++k) \
;     dst[m][k]=*reinterpret_cast<const bf16x8*>((char*)SA(b,h)+lds_byte(wr*64+m*16+fr,k*32+fq*8))
;   #define LDB(dst,b,h) for(int n=0;n<2;++n)for(int k=0;k<2;++k) \
;     dst[n][k]=*reinterpret_cast<const bf16x8*>((char*)SB(b,h)+lds_byte(wc*32+n*16+fr,k*32+fq*8))
;   #define MMA(ai,bj,At,Bt_) do{__builtin_amdgcn_s_setprio(1); \
;     for(int m=0;m<4;++m)for(int n=0;n<2;++n)for(int k=0;k<2;++k) \
;       acc[ai][bj][m][n]=__builtin_amdgcn_mfma_f32_16x16x32_bf16(Bt_[n][k],At[m][k],acc[ai][bj][m][n],0,0,0); \
;     __builtin_amdgcn_s_setprio(0);}while(0)
;   #define WAIT_V(n) asm volatile("s_waitcnt vmcnt(" #n ")":::"memory")
;   #define WAIT_L(n) asm volatile("s_waitcnt lgkmcnt(" #n ")":::"memory")
;   #define BAR __builtin_amdgcn_s_barrier()
; template <bool TWO, class MID> ...
;     ...
;     LDB(B1,0,1); BAR; WAIT_L(0); MMA(0,1,At,B1); BAR;
;     LDA(At,0,1); WAIT_V(4); BAR; WAIT_L(0); MMA(1,0,At,B0); MMA(1,1,At,B1); BAR; }
;   { LDB(B0,1,0); LDA(At,1,0); WAIT_V(2); BAR; WAIT_L(0); MMA(0,0,At,B0); BAR;
	s_waitcnt lgkmcnt(0)
	v_mfma_f32_16x16x32_bf16 v[90:93], v[118:121], v[168:171], v[90:93]
	v_mfma_f32_16x16x32_bf16 v[82:85], v[118:121], v[176:179], v[82:85]
	v_mfma_f32_16x16x32_bf16 v[74:77], v[118:121], v[184:187], v[74:77]
	v_mfma_f32_16x16x32_bf16 v[66:69], v[118:121], v[196:199], v[66:69]
	v_mfma_f32_16x16x32_bf16 v[94:97], v[102:105], v[168:171], v[94:97]
	v_mfma_f32_16x16x32_bf16 v[90:93], v[208:211], v[172:175], v[90:93]
	v_mfma_f32_16x16x32_bf16 v[86:89], v[102:105], v[176:179], v[86:89]
	v_mfma_f32_16x16x32_bf16 v[82:85], v[208:211], v[180:183], v[82:85]
	v_mfma_f32_16x16x32_bf16 v[78:81], v[102:105], v[184:187], v[78:81]
	v_mfma_f32_16x16x32_bf16 v[74:77], v[208:211], v[188:191], v[74:77]
	v_mfma_f32_16x16x32_bf16 v[70:73], v[102:105], v[196:199], v[70:73]
	v_mfma_f32_16x16x32_bf16 v[66:69], v[208:211], v[200:203], v[66:69]
	v_mfma_f32_16x16x32_bf16 v[212:215], v[110:113], v[172:175], v[94:97]
	v_mfma_f32_16x16x32_bf16 v[168:171], v[110:113], v[180:183], v[86:89]
	v_mfma_f32_16x16x32_bf16 v[172:175], v[110:113], v[188:191], v[78:81]
	v_mfma_f32_16x16x32_bf16 v[176:179], v[110:113], v[200:203], v[70:73]
	s_barrier
	s_setprio 0
	s_nop 0
	ds_read_b128 v[70:73], v141 offset:16384
	ds_read_b128 v[78:81], v141 offset:17408
	ds_read_b128 v[86:89], v139 offset:16384
	ds_read_b128 v[94:97], v139 offset:17408
	ds_read_b128 v[180:183], v137 offset:16384
	ds_read_b128 v[184:187], v137 offset:17408
	ds_read_b128 v[188:191], v135 offset:16384
	ds_read_b128 v[196:199], v135 offset:17408
	s_waitcnt vmcnt(4)
	s_setprio 1
	s_barrier
	s_waitcnt lgkmcnt(0)
	v_mfma_f32_16x16x32_bf16 v[62:65], v[152:155], v[70:73], v[62:65]
	v_mfma_f32_16x16x32_bf16 v[58:61], v[160:163], v[70:73], v[58:61]
	v_mfma_f32_16x16x32_bf16 v[54:57], v[152:155], v[86:89], v[54:57]
	v_mfma_f32_16x16x32_bf16 v[50:53], v[160:163], v[86:89], v[50:53]
	v_mfma_f32_16x16x32_bf16 v[38:41], v[152:155], v[188:191], v[38:41]
	v_mfma_f32_16x16x32_bf16 v[34:37], v[160:163], v[188:191], v[34:37]
	v_mfma_f32_16x16x32_bf16 v[62:65], v[156:159], v[78:81], v[62:65]
	v_mfma_f32_16x16x32_bf16 v[58:61], v[164:167], v[78:81], v[58:61]
	v_mfma_f32_16x16x32_bf16 v[54:57], v[156:159], v[94:97], v[54:57]
	v_mfma_f32_16x16x32_bf16 v[50:53], v[164:167], v[94:97], v[50:53]
	v_mfma_f32_16x16x32_bf16 v[46:49], v[152:155], v[180:183], v[46:49]
	v_mfma_f32_16x16x32_bf16 v[42:45], v[160:163], v[180:183], v[42:45]
	v_mfma_f32_16x16x32_bf16 v[38:41], v[156:159], v[196:199], v[38:41]
	v_mfma_f32_16x16x32_bf16 v[34:37], v[164:167], v[196:199], v[34:37]
	v_mfma_f32_16x16x32_bf16 v[200:203], v[156:159], v[184:187], v[46:49]
	v_mfma_f32_16x16x32_bf16 v[216:219], v[164:167], v[184:187], v[42:45]
	s_setprio 0
	s_setprio 1
	v_mfma_f32_16x16x32_bf16 v[22:25], v[102:105], v[86:89], v[22:25]
	v_mfma_f32_16x16x32_bf16 v[18:21], v[118:121], v[86:89], v[18:21]
	v_mfma_f32_16x16x32_bf16 v[6:9], v[102:105], v[188:191], v[6:9]
	v_mfma_f32_16x16x32_bf16 v[2:5], v[118:121], v[188:191], v[2:5]
	v_mfma_f32_16x16x32_bf16 v[30:33], v[102:105], v[70:73], v[30:33]
	v_mfma_f32_16x16x32_bf16 v[26:29], v[118:121], v[70:73], v[26:29]
	v_mfma_f32_16x16x32_bf16 v[22:25], v[110:113], v[94:97], v[22:25]
	v_mfma_f32_16x16x32_bf16 v[18:21], v[208:211], v[94:97], v[18:21]
	v_mfma_f32_16x16x32_bf16 v[14:17], v[102:105], v[180:183], v[14:17]
	v_mfma_f32_16x16x32_bf16 v[10:13], v[118:121], v[180:183], v[10:13]
	v_mfma_f32_16x16x32_bf16 v[6:9], v[110:113], v[196:199], v[6:9]
	v_mfma_f32_16x16x32_bf16 v[2:5], v[208:211], v[196:199], v[2:5]
	v_mfma_f32_16x16x32_bf16 v[152:155], v[110:113], v[78:81], v[30:33]
	v_mfma_f32_16x16x32_bf16 v[156:159], v[208:211], v[78:81], v[26:29]
	v_mfma_f32_16x16x32_bf16 v[160:163], v[110:113], v[184:187], v[14:17]
	v_mfma_f32_16x16x32_bf16 v[164:167], v[208:211], v[184:187], v[10:13]
	s_barrier
	s_setprio 0
	s_nop 0
	ds_read_b128 v[10:13], v145
	ds_read_b128 v[14:17], v145 offset:1024
	ds_read_b128 v[180:183], v145 offset:2048
	ds_read_b128 v[144:147], v145 offset:3072
	ds_read_b128 v[26:29], v141 offset:32768
	ds_read_b128 v[30:33], v141 offset:33792
	ds_read_b128 v[42:45], v139 offset:32768
	ds_read_b128 v[46:49], v139 offset:33792
	ds_read_b128 v[184:187], v137 offset:32768
	ds_read_b128 v[188:191], v137 offset:33792
	ds_read_b128 v[196:199], v135 offset:32768
	ds_read_b128 v[208:211], v135 offset:33792
	s_waitcnt vmcnt(2)
	s_setprio 1
	s_barrier
;   #define LDA(dst,b,h) for(int m=0;m<4;++m)for(int k=0;k<2;++k) \
;     dst[m][k]=*reinterpret_cast<const bf16x8*>((char*)SA(b,h)+lds_byte(wr*64+m*16+fr,k*32+fq*8))
;   #define LDB(dst,b,h) for(int n=0;n<2;++n)for(int k=0;k<2;++k) \
;     dst[n][k]=*reinterpret_cast<const bf16x8*>((char*)SB(b,h)+lds_byte(wc*32+n*16+fr,k*32+fq*8))
;   #define MMA(ai,bj,At,Bt_) do{__builtin_amdgcn_s_setprio(1); \
;     for(int m=0;m<4;++m)for(int n=0;n<2;++n)for(int k=0;k<2;++k) \
;       acc[ai][bj][m][n]=__builtin_amdgcn_mfma_f32_16x16x32_bf16(Bt_[n][k],At[m][k],acc[ai][bj][m][n],0,0,0); \
;     __builtin_amdgcn_s_setprio(0);}while(0)
;   #define WAIT_V(n) asm volatile("s_waitcnt vmcnt(" #n ")":::"memory")
;   #define WAIT_L(n) asm volatile("s_waitcnt lgkmcnt(" #n ")":::"memory")
;   #define BAR __builtin_amdgcn_s_barrier()
; template <bool TWO, class MID> ...
;     ...
;   { LDB(B0,1,0); LDA(At,1,0); WAIT_V(2); BAR; WAIT_L(0); MMA(0,0,At,B0); BAR;
;     LDB(B1,1,1); WAIT_V(0); BAR; WAIT_L(0); MMA(0,1,At,B1); BAR;
;     LDA(At,1,1); BAR; WAIT_L(0); MMA(1,0,At,B0); MMA(1,1,At,B1); BAR; }
;   if(wr==0)BAR;
	s_waitcnt lgkmcnt(0)
	v_mfma_f32_16x16x32_bf16 v[70:73], v[10:13], v[26:29], v[126:129]
	v_mfma_f32_16x16x32_bf16 v[126:129], v[14:17], v[30:33], v[70:73]
	v_mfma_f32_16x16x32_bf16 v[70:73], v[180:183], v[26:29], v[122:125]
	v_mfma_f32_16x16x32_bf16 v[118:121], v[144:147], v[30:33], v[70:73]
	v_mfma_f32_16x16x32_bf16 v[70:73], v[10:13], v[42:45], v[130:133]
	v_mfma_f32_16x16x32_bf16 v[110:113], v[14:17], v[46:49], v[70:73]
	v_mfma_f32_16x16x32_bf16 v[70:73], v[180:183], v[42:45], v[114:117]
	v_mfma_f32_16x16x32_bf16 v[102:105], v[144:147], v[46:49], v[70:73]
	v_mfma_f32_16x16x32_bf16 v[70:73], v[10:13], v[184:187], v[148:151]
	v_mfma_f32_16x16x32_bf16 v[94:97], v[14:17], v[188:191], v[70:73]
	v_mfma_f32_16x16x32_bf16 v[70:73], v[180:183], v[184:187], v[106:109]
	v_mfma_f32_16x16x32_bf16 v[86:89], v[144:147], v[188:191], v[70:73]
	v_mfma_f32_16x16x32_bf16 v[70:73], v[10:13], v[196:199], v[204:207]
	v_mfma_f32_16x16x32_bf16 v[78:81], v[14:17], v[208:211], v[70:73]
	v_mfma_f32_16x16x32_bf16 v[70:73], v[180:183], v[196:199], v[98:101]
	v_mfma_f32_16x16x32_bf16 v[70:73], v[144:147], v[208:211], v[70:73]
	s_barrier
	s_setprio 0
	ds_read_b128 v[130:133], v143
	ds_read_b128 v[148:151], v143 offset:1024
	ds_read_b128 v[204:207], v143 offset:2048
	ds_read_b128 v[220:223], v143 offset:3072
	s_waitcnt vmcnt(0)
	s_setprio 1
	s_barrier
	s_waitcnt lgkmcnt(0)
	v_mfma_f32_16x16x32_bf16 v[98:101], v[130:133], v[26:29], v[212:215]
	v_mfma_f32_16x16x32_bf16 v[26:29], v[204:207], v[26:29], v[90:93]
	v_mfma_f32_16x16x32_bf16 v[114:117], v[220:223], v[30:33], v[26:29]
	v_mfma_f32_16x16x32_bf16 v[26:29], v[130:133], v[42:45], v[168:171]
	v_mfma_f32_16x16x32_bf16 v[106:109], v[148:151], v[46:49], v[26:29]
	v_mfma_f32_16x16x32_bf16 v[26:29], v[204:207], v[42:45], v[82:85]
	v_mfma_f32_16x16x32_bf16 v[122:125], v[148:151], v[30:33], v[98:101]
	v_mfma_f32_16x16x32_bf16 v[98:101], v[220:223], v[46:49], v[26:29]
	v_mfma_f32_16x16x32_bf16 v[26:29], v[130:133], v[184:187], v[172:175]
	v_mfma_f32_16x16x32_bf16 v[90:93], v[148:151], v[188:191], v[26:29]
	v_mfma_f32_16x16x32_bf16 v[26:29], v[204:207], v[184:187], v[74:77]
	v_mfma_f32_16x16x32_bf16 v[82:85], v[220:223], v[188:191], v[26:29]
	v_mfma_f32_16x16x32_bf16 v[26:29], v[130:133], v[196:199], v[176:179]
	v_mfma_f32_16x16x32_bf16 v[74:77], v[148:151], v[208:211], v[26:29]
	v_mfma_f32_16x16x32_bf16 v[26:29], v[204:207], v[196:199], v[66:69]
	v_mfma_f32_16x16x32_bf16 v[66:69], v[220:223], v[208:211], v[26:29]
	s_barrier
	s_setprio 0
	ds_read_b128 v[168:171], v141 offset:49152
	ds_read_b128 v[140:143], v141 offset:50176
	ds_read_b128 v[172:175], v139 offset:49152
	ds_read_b128 v[176:179], v139 offset:50176
	ds_read_b128 v[184:187], v137 offset:49152
	ds_read_b128 v[136:139], v137 offset:50176
	ds_read_b128 v[188:191], v135 offset:49152
	ds_read_b128 v[196:199], v135 offset:50176
	s_setprio 1
	s_barrier
	s_waitcnt lgkmcnt(0)
	v_mfma_f32_16x16x32_bf16 v[26:29], v[10:13], v[168:171], v[62:65]
	v_mfma_f32_16x16x32_bf16 v[62:65], v[14:17], v[140:143], v[26:29]
	v_mfma_f32_16x16x32_bf16 v[26:29], v[180:183], v[168:171], v[58:61]
	v_mfma_f32_16x16x32_bf16 v[58:61], v[144:147], v[140:143], v[26:29]
	v_mfma_f32_16x16x32_bf16 v[26:29], v[10:13], v[172:175], v[54:57]
	v_mfma_f32_16x16x32_bf16 v[46:49], v[14:17], v[176:179], v[26:29]
	v_mfma_f32_16x16x32_bf16 v[26:29], v[180:183], v[172:175], v[50:53]
	v_mfma_f32_16x16x32_bf16 v[42:45], v[144:147], v[176:179], v[26:29]
	v_mfma_f32_16x16x32_bf16 v[26:29], v[10:13], v[184:187], v[200:203]
	v_mfma_f32_16x16x32_bf16 v[10:13], v[10:13], v[188:191], v[38:41]
	v_mfma_f32_16x16x32_bf16 v[30:33], v[14:17], v[136:139], v[26:29]
	v_mfma_f32_16x16x32_bf16 v[26:29], v[180:183], v[184:187], v[216:219]
	v_mfma_f32_16x16x32_bf16 v[14:17], v[14:17], v[196:199], v[10:13]
	v_mfma_f32_16x16x32_bf16 v[10:13], v[180:183], v[188:191], v[34:37]
	v_mfma_f32_16x16x32_bf16 v[26:29], v[144:147], v[136:139], v[26:29]
	v_mfma_f32_16x16x32_bf16 v[10:13], v[144:147], v[196:199], v[10:13]
	s_setprio 0
	s_setprio 1
	v_mfma_f32_16x16x32_bf16 v[34:37], v[130:133], v[168:171], v[152:155]
	v_mfma_f32_16x16x32_bf16 v[54:57], v[148:151], v[140:143], v[34:37]
	v_mfma_f32_16x16x32_bf16 v[34:37], v[204:207], v[168:171], v[156:159]
	v_mfma_f32_16x16x32_bf16 v[18:21], v[204:207], v[172:175], v[18:21]
	v_mfma_f32_16x16x32_bf16 v[50:53], v[220:223], v[140:143], v[34:37]
	v_mfma_f32_16x16x32_bf16 v[22:25], v[130:133], v[172:175], v[22:25]
	v_mfma_f32_16x16x32_bf16 v[34:37], v[220:223], v[176:179], v[18:21]
	v_mfma_f32_16x16x32_bf16 v[18:21], v[130:133], v[184:187], v[160:163]
	v_mfma_f32_16x16x32_bf16 v[38:41], v[148:151], v[176:179], v[22:25]
	v_mfma_f32_16x16x32_bf16 v[22:25], v[148:151], v[136:139], v[18:21]
	v_mfma_f32_16x16x32_bf16 v[18:21], v[204:207], v[184:187], v[164:167]
	v_mfma_f32_16x16x32_bf16 v[6:9], v[130:133], v[188:191], v[6:9]
	v_mfma_f32_16x16x32_bf16 v[2:5], v[204:207], v[188:191], v[2:5]
	v_mfma_f32_16x16x32_bf16 v[18:21], v[220:223], v[136:139], v[18:21]
	v_mfma_f32_16x16x32_bf16 v[6:9], v[148:151], v[196:199], v[6:9]
	v_mfma_f32_16x16x32_bf16 v[2:5], v[220:223], v[196:199], v[2:5]
	s_setprio 0
	v_cmp_gt_u32_e32 vcc, s30, v1
	s_barrier
	s_and_saveexec_b64 s[4:5], vcc
	s_cbranch_execz .LBB0_565
	s_barrier

;   #define LDA(dst,b,h) for(int m=0;m<4;++m)for(int k=0;k<2;++k) \
;     dst[m][k]=*reinterpret_cast<const bf16x8*>((char*)SA(b,h)+lds_byte(wr*64+m*16+fr,k*32+fq*8))
;   #define LDB(dst,b,h) for(int n=0;n<2;++n)for(int k=0;k<2;++k) \
;     dst[n][k]=*reinterpret_cast<const bf16x8*>((char*)SB(b,h)+lds_byte(wc*32+n*16+fr,k*32+fq*8))
;   #define MMA(ai,bj,At,Bt_) do{__builtin_amdgcn_s_setprio(1); \
;     for(int m=0;m<4;++m)for(int n=0;n<2;++n)for(int k=0;k<2;++k) \
;       acc[ai][bj][m][n]=__builtin_amdgcn_mfma_f32_16x16x32_bf16(Bt_[n][k],At[m][k],acc[ai][bj][m][n],0,0,0); \
;     __builtin_amdgcn_s_setprio(0);}while(0)
;   #define WAIT_V(n) asm volatile("s_waitcnt vmcnt(" #n ")":::"memory")
;   #define WAIT_L(n) asm volatile("s_waitcnt lgkmcnt(" #n ")":::"memory")
;   #define BAR __builtin_amdgcn_s_barrier()
;   #define SCHED __builtin_amdgcn_sched_barrier(0)
; template <bool TWO, class MID> ...
;     ...
;     LDB(B0,0,0); SCHED; LDA(At,0,0); STAGE_A(SA(1,1),1,t+1);
;     WAIT_L(8); BAR; WAIT_L(0); MMA(0,0,At,B0); BAR; SCHED;
;     LDB(B1,0,1); STAGE_B(SB(0,0),0,t+2);
;     BAR; WAIT_L(0); MMA(0,1,At,B1); BAR;
;     LDA(At,0,1); STAGE_A(SA(0,0),0,t+2);
;     BAR; WAIT_L(0); MMA(1,0,At,B0); BAR; SCHED;
;     STAGE_B(SB(0,1),1,t+2);
;     WAIT_V(6); BAR; MMA(1,1,At,B1); BAR;
.LBB0_620:
	ds_read_b128 v[166:169], v149
	ds_read_b128 v[170:173], v149 offset:1024
	ds_read_b128 v[174:177], v149 offset:2048
	ds_read_b128 v[178:181], v149 offset:3072
	ds_read_b128 v[182:185], v141
	ds_read_b128 v[186:189], v141 offset:1024
	ds_read_b128 v[190:193], v139
	ds_read_b128 v[196:199], v139 offset:1024
	ds_read_b128 v[200:203], v137
	ds_read_b128 v[204:207], v137 offset:1024
	ds_read_b128 v[208:211], v135
	ds_read_b128 v[212:215], v135 offset:1024
	s_add_u32 s15, s0, s16
	s_addc_u32 s18, s1, s17
	s_add_u32 s24, s15, 0x10200080
	s_addc_u32 s25, s18, 0
	v_lshl_add_u64 v[216:217], s[24:25], 0, v[132:133]
	v_readfirstlane_b32 s19, v148
	s_mov_b32 m0, s19
	global_load_lds_dwordx4 v[216:217], off
	v_lshl_add_u64 v[216:217], s[24:25], 0, v[130:131]
	v_readfirstlane_b32 s19, v150
	s_mov_b32 m0, s19
	global_load_lds_dwordx4 v[216:217], off
	s_waitcnt lgkmcnt(8)
	s_setprio 1
	s_barrier
	s_waitcnt lgkmcnt(0)
	v_mfma_f32_16x16x32_bf16 v[126:129], v[166:169], v[182:185], v[126:129]
	v_mfma_f32_16x16x32_bf16 v[122:125], v[174:177], v[182:185], v[122:125]
	v_mfma_f32_16x16x32_bf16 v[118:121], v[166:169], v[190:193], v[118:121]
	v_mfma_f32_16x16x32_bf16 v[114:117], v[174:177], v[190:193], v[114:117]
	v_mfma_f32_16x16x32_bf16 v[110:113], v[166:169], v[200:203], v[110:113]
	v_mfma_f32_16x16x32_bf16 v[106:109], v[174:177], v[200:203], v[106:109]
	v_mfma_f32_16x16x32_bf16 v[102:105], v[166:169], v[208:211], v[102:105]
	v_mfma_f32_16x16x32_bf16 v[98:101], v[174:177], v[208:211], v[98:101]
	v_mfma_f32_16x16x32_bf16 v[126:129], v[170:173], v[186:189], v[126:129]
	v_mfma_f32_16x16x32_bf16 v[122:125], v[178:181], v[186:189], v[122:125]
	v_mfma_f32_16x16x32_bf16 v[118:121], v[170:173], v[196:199], v[118:121]
	v_mfma_f32_16x16x32_bf16 v[114:117], v[178:181], v[196:199], v[114:117]
	v_mfma_f32_16x16x32_bf16 v[110:113], v[170:173], v[204:207], v[110:113]
	v_mfma_f32_16x16x32_bf16 v[106:109], v[178:181], v[204:207], v[106:109]
	v_mfma_f32_16x16x32_bf16 v[102:105], v[170:173], v[212:215], v[102:105]
	v_mfma_f32_16x16x32_bf16 v[98:101], v[178:181], v[212:215], v[98:101]
	s_barrier
	s_setprio 0
	s_add_u32 s19, s0, s4
	ds_read_b128 v[216:219], v147
	ds_read_b128 v[220:223], v147 offset:1024
	ds_read_b128 v[224:227], v147 offset:2048
	ds_read_b128 v[228:231], v147 offset:3072
	s_addc_u32 s24, s1, s5
	s_add_u32 s26, s19, 0x5c00100
	s_addc_u32 s27, s24, 0
	v_lshl_add_u64 v[232:233], s[26:27], 0, v[132:133]
	v_readfirstlane_b32 s25, v152
	s_mov_b32 m0, s25
	global_load_lds_dwordx4 v[232:233], off
	v_lshl_add_u64 v[232:233], s[26:27], 0, v[130:131]
	v_readfirstlane_b32 s25, v154
	s_mov_b32 m0, s25
	global_load_lds_dwordx4 v[232:233], off
	s_setprio 1
	s_barrier
	s_waitcnt lgkmcnt(0)
	v_mfma_f32_16x16x32_bf16 v[94:97], v[216:219], v[182:185], v[94:97]
	v_mfma_f32_16x16x32_bf16 v[90:93], v[224:227], v[182:185], v[90:93]
	v_mfma_f32_16x16x32_bf16 v[86:89], v[216:219], v[190:193], v[86:89]
	v_mfma_f32_16x16x32_bf16 v[82:85], v[224:227], v[190:193], v[82:85]
	v_mfma_f32_16x16x32_bf16 v[78:81], v[216:219], v[200:203], v[78:81]
	v_mfma_f32_16x16x32_bf16 v[74:77], v[224:227], v[200:203], v[74:77]
	v_mfma_f32_16x16x32_bf16 v[70:73], v[216:219], v[208:211], v[70:73]
	v_mfma_f32_16x16x32_bf16 v[66:69], v[224:227], v[208:211], v[66:69]
	v_mfma_f32_16x16x32_bf16 v[94:97], v[220:223], v[186:189], v[94:97]
	v_mfma_f32_16x16x32_bf16 v[90:93], v[228:231], v[186:189], v[90:93]
	v_mfma_f32_16x16x32_bf16 v[86:89], v[220:223], v[196:199], v[86:89]
	v_mfma_f32_16x16x32_bf16 v[82:85], v[228:231], v[196:199], v[82:85]
	v_mfma_f32_16x16x32_bf16 v[78:81], v[220:223], v[204:207], v[78:81]
	v_mfma_f32_16x16x32_bf16 v[74:77], v[228:231], v[204:207], v[74:77]
	v_mfma_f32_16x16x32_bf16 v[70:73], v[220:223], v[212:215], v[70:73]
	v_mfma_f32_16x16x32_bf16 v[66:69], v[228:231], v[212:215], v[66:69]
	s_barrier
	s_setprio 0
	ds_read_b128 v[182:185], v141 offset:16384
	ds_read_b128 v[186:189], v141 offset:17408
	ds_read_b128 v[190:193], v139 offset:16384
	ds_read_b128 v[196:199], v139 offset:17408
	ds_read_b128 v[200:203], v137 offset:16384
	ds_read_b128 v[204:207], v137 offset:17408
	ds_read_b128 v[208:211], v135 offset:16384
	ds_read_b128 v[212:215], v135 offset:17408
	s_add_u32 s26, s15, 0x10000100
	s_addc_u32 s27, s18, 0
	v_lshl_add_u64 v[232:233], s[26:27], 0, v[132:133]
	v_readfirstlane_b32 s25, v138
	s_mov_b32 m0, s25
	global_load_lds_dwordx4 v[232:233], off
	v_lshl_add_u64 v[232:233], s[26:27], 0, v[130:131]
	v_readfirstlane_b32 s25, v156
	s_mov_b32 m0, s25
	global_load_lds_dwordx4 v[232:233], off
	s_setprio 1
	s_barrier
	s_waitcnt lgkmcnt(0)
	v_mfma_f32_16x16x32_bf16 v[62:65], v[166:169], v[182:185], v[62:65]
	v_mfma_f32_16x16x32_bf16 v[58:61], v[174:177], v[182:185], v[58:61]
	v_mfma_f32_16x16x32_bf16 v[54:57], v[166:169], v[190:193], v[54:57]
	v_mfma_f32_16x16x32_bf16 v[50:53], v[174:177], v[190:193], v[50:53]
	v_mfma_f32_16x16x32_bf16 v[46:49], v[166:169], v[200:203], v[46:49]
	v_mfma_f32_16x16x32_bf16 v[42:45], v[174:177], v[200:203], v[42:45]
	v_mfma_f32_16x16x32_bf16 v[38:41], v[166:169], v[208:211], v[38:41]
	v_mfma_f32_16x16x32_bf16 v[34:37], v[174:177], v[208:211], v[34:37]
	v_mfma_f32_16x16x32_bf16 v[62:65], v[170:173], v[186:189], v[62:65]
	v_mfma_f32_16x16x32_bf16 v[58:61], v[178:181], v[186:189], v[58:61]
	v_mfma_f32_16x16x32_bf16 v[54:57], v[170:173], v[196:199], v[54:57]
	v_mfma_f32_16x16x32_bf16 v[50:53], v[178:181], v[196:199], v[50:53]
	v_mfma_f32_16x16x32_bf16 v[46:49], v[170:173], v[204:207], v[46:49]
	v_mfma_f32_16x16x32_bf16 v[42:45], v[178:181], v[204:207], v[42:45]
	v_mfma_f32_16x16x32_bf16 v[38:41], v[170:173], v[212:215], v[38:41]
	v_mfma_f32_16x16x32_bf16 v[34:37], v[178:181], v[212:215], v[34:37]
	s_barrier
;   #define LDA(dst,b,h) for(int m=0;m<4;++m)for(int k=0;k<2;++k) \
;     dst[m][k]=*reinterpret_cast<const bf16x8*>((char*)SA(b,h)+lds_byte(wr*64+m*16+fr,k*32+fq*8))
;   #define LDB(dst,b,h) for(int n=0;n<2;++n)for(int k=0;k<2;++k) \
;     dst[n][k]=*reinterpret_cast<const bf16x8*>((char*)SB(b,h)+lds_byte(wc*32+n*16+fr,k*32+fq*8))
;   #define MMA(ai,bj,At,Bt_) do{__builtin_amdgcn_s_setprio(1); \
;     for(int m=0;m<4;++m)for(int n=0;n<2;++n)for(int k=0;k<2;++k) \
;       acc[ai][bj][m][n]=__builtin_amdgcn_mfma_f32_16x16x32_bf16(Bt_[n][k],At[m][k],acc[ai][bj][m][n],0,0,0); \
;     __builtin_amdgcn_s_setprio(0);}while(0)
;   #define WAIT_V(n) asm volatile("s_waitcnt vmcnt(" #n ")":::"memory")
;   #define WAIT_L(n) asm volatile("s_waitcnt lgkmcnt(" #n ")":::"memory")
;   #define BAR __builtin_amdgcn_s_barrier()
;   #define SCHED __builtin_amdgcn_sched_barrier(0)
; template <bool TWO, class MID> ...
;     ...
;     WAIT_V(6); BAR; MMA(1,1,At,B1); BAR;
;     LDB(B0,1,0); SCHED; LDA(At,1,0); STAGE_A(SA(0,1),1,t+2);
;     WAIT_L(8); BAR; WAIT_L(0); MMA(0,0,At,B0); BAR; SCHED;
;     LDB(B1,1,1); STAGE_B(SB(1,0),0,t+3);
;     BAR; WAIT_L(0); MMA(0,1,At,B1); BAR;
	s_setprio 0
	s_add_u32 s26, s19, 0x5e00100
	s_addc_u32 s27, s24, 0
	v_lshl_add_u64 v[166:167], s[26:27], 0, v[132:133]
	v_readfirstlane_b32 s25, v158
	s_mov_b32 m0, s25
	global_load_lds_dwordx4 v[166:167], off
	v_lshl_add_u64 v[166:167], s[26:27], 0, v[130:131]
	v_readfirstlane_b32 s25, v160
	s_mov_b32 m0, s25
	global_load_lds_dwordx4 v[166:167], off
	s_waitcnt vmcnt(6)
	s_setprio 1
	s_barrier
	v_mfma_f32_16x16x32_bf16 v[30:33], v[216:219], v[182:185], v[30:33]
	v_mfma_f32_16x16x32_bf16 v[26:29], v[224:227], v[182:185], v[26:29]
	v_mfma_f32_16x16x32_bf16 v[22:25], v[216:219], v[190:193], v[22:25]
	v_mfma_f32_16x16x32_bf16 v[18:21], v[224:227], v[190:193], v[18:21]
	v_mfma_f32_16x16x32_bf16 v[14:17], v[216:219], v[200:203], v[14:17]
	v_mfma_f32_16x16x32_bf16 v[10:13], v[224:227], v[200:203], v[10:13]
	v_mfma_f32_16x16x32_bf16 v[6:9], v[216:219], v[208:211], v[6:9]
	v_mfma_f32_16x16x32_bf16 v[2:5], v[224:227], v[208:211], v[2:5]
	v_mfma_f32_16x16x32_bf16 v[30:33], v[220:223], v[186:189], v[30:33]
	v_mfma_f32_16x16x32_bf16 v[26:29], v[228:231], v[186:189], v[26:29]
	v_mfma_f32_16x16x32_bf16 v[22:25], v[220:223], v[196:199], v[22:25]
	v_mfma_f32_16x16x32_bf16 v[18:21], v[228:231], v[196:199], v[18:21]
	v_mfma_f32_16x16x32_bf16 v[14:17], v[220:223], v[204:207], v[14:17]
	v_mfma_f32_16x16x32_bf16 v[10:13], v[228:231], v[204:207], v[10:13]
	v_mfma_f32_16x16x32_bf16 v[6:9], v[220:223], v[212:215], v[6:9]
	v_mfma_f32_16x16x32_bf16 v[2:5], v[228:231], v[212:215], v[2:5]
	s_barrier
	s_setprio 0
	ds_read_b128 v[166:169], v145
	ds_read_b128 v[170:173], v145 offset:1024
	ds_read_b128 v[174:177], v145 offset:2048
	ds_read_b128 v[178:181], v145 offset:3072
	ds_read_b128 v[182:185], v141 offset:32768
	ds_read_b128 v[186:189], v141 offset:33792
	ds_read_b128 v[190:193], v139 offset:32768
	ds_read_b128 v[196:199], v139 offset:33792
	ds_read_b128 v[200:203], v137 offset:32768
	ds_read_b128 v[204:207], v137 offset:33792
	ds_read_b128 v[208:211], v135 offset:32768
	ds_read_b128 v[212:215], v135 offset:33792
	s_add_u32 s26, s15, 0x10200100
	s_addc_u32 s27, s18, 0
	v_lshl_add_u64 v[216:217], s[26:27], 0, v[132:133]
	v_readfirstlane_b32 s25, v162
	s_mov_b32 m0, s25
	global_load_lds_dwordx4 v[216:217], off
	v_lshl_add_u64 v[216:217], s[26:27], 0, v[130:131]
	v_readfirstlane_b32 s25, v164
	s_mov_b32 m0, s25
	global_load_lds_dwordx4 v[216:217], off
	s_waitcnt lgkmcnt(8)
	s_setprio 1
	s_barrier
	s_waitcnt lgkmcnt(0)
	v_mfma_f32_16x16x32_bf16 v[126:129], v[166:169], v[182:185], v[126:129]
	v_mfma_f32_16x16x32_bf16 v[122:125], v[174:177], v[182:185], v[122:125]
	v_mfma_f32_16x16x32_bf16 v[118:121], v[166:169], v[190:193], v[118:121]
	v_mfma_f32_16x16x32_bf16 v[114:117], v[174:177], v[190:193], v[114:117]
	v_mfma_f32_16x16x32_bf16 v[110:113], v[166:169], v[200:203], v[110:113]
	v_mfma_f32_16x16x32_bf16 v[106:109], v[174:177], v[200:203], v[106:109]
	v_mfma_f32_16x16x32_bf16 v[102:105], v[166:169], v[208:211], v[102:105]
	v_mfma_f32_16x16x32_bf16 v[98:101], v[174:177], v[208:211], v[98:101]
	v_mfma_f32_16x16x32_bf16 v[126:129], v[170:173], v[186:189], v[126:129]
	v_mfma_f32_16x16x32_bf16 v[122:125], v[178:181], v[186:189], v[122:125]
	v_mfma_f32_16x16x32_bf16 v[118:121], v[170:173], v[196:199], v[118:121]
	v_mfma_f32_16x16x32_bf16 v[114:117], v[178:181], v[196:199], v[114:117]
	v_mfma_f32_16x16x32_bf16 v[110:113], v[170:173], v[204:207], v[110:113]
	v_mfma_f32_16x16x32_bf16 v[106:109], v[178:181], v[204:207], v[106:109]
	v_mfma_f32_16x16x32_bf16 v[102:105], v[170:173], v[212:215], v[102:105]
	v_mfma_f32_16x16x32_bf16 v[98:101], v[178:181], v[212:215], v[98:101]
	s_barrier
	s_setprio 0
	ds_read_b128 v[216:219], v143
	ds_read_b128 v[220:223], v143 offset:1024
	ds_read_b128 v[224:227], v143 offset:2048
	ds_read_b128 v[228:231], v143 offset:3072
	s_add_u32 s26, s19, 0x5c00180
	s_addc_u32 s27, s24, 0
	v_lshl_add_u64 v[232:233], s[26:27], 0, v[132:133]
	v_readfirstlane_b32 s25, v134
	s_mov_b32 m0, s25
	global_load_lds_dwordx4 v[232:233], off
	v_lshl_add_u64 v[232:233], s[26:27], 0, v[130:131]
	v_readfirstlane_b32 s25, v136
	s_mov_b32 m0, s25
	global_load_lds_dwordx4 v[232:233], off
	s_setprio 1
	s_barrier
	s_waitcnt lgkmcnt(0)
	v_mfma_f32_16x16x32_bf16 v[94:97], v[216:219], v[182:185], v[94:97]
	v_mfma_f32_16x16x32_bf16 v[90:93], v[224:227], v[182:185], v[90:93]
	v_mfma_f32_16x16x32_bf16 v[86:89], v[216:219], v[190:193], v[86:89]
	v_mfma_f32_16x16x32_bf16 v[82:85], v[224:227], v[190:193], v[82:85]
	v_mfma_f32_16x16x32_bf16 v[78:81], v[216:219], v[200:203], v[78:81]
	v_mfma_f32_16x16x32_bf16 v[74:77], v[224:227], v[200:203], v[74:77]
	v_mfma_f32_16x16x32_bf16 v[70:73], v[216:219], v[208:211], v[70:73]
	v_mfma_f32_16x16x32_bf16 v[66:69], v[224:227], v[208:211], v[66:69]
	v_mfma_f32_16x16x32_bf16 v[94:97], v[220:223], v[186:189], v[94:97]
	v_mfma_f32_16x16x32_bf16 v[90:93], v[228:231], v[186:189], v[90:93]
	v_mfma_f32_16x16x32_bf16 v[86:89], v[220:223], v[196:199], v[86:89]
	v_mfma_f32_16x16x32_bf16 v[82:85], v[228:231], v[196:199], v[82:85]
	v_mfma_f32_16x16x32_bf16 v[78:81], v[220:223], v[204:207], v[78:81]
	v_mfma_f32_16x16x32_bf16 v[74:77], v[228:231], v[204:207], v[74:77]
	v_mfma_f32_16x16x32_bf16 v[70:73], v[220:223], v[212:215], v[70:73]
	v_mfma_f32_16x16x32_bf16 v[66:69], v[228:231], v[212:215], v[66:69]
	s_barrier
;   #define LDA(dst,b,h) for(int m=0;m<4;++m)for(int k=0;k<2;++k) \
;     dst[m][k]=*reinterpret_cast<const bf16x8*>((char*)SA(b,h)+lds_byte(wr*64+m*16+fr,k*32+fq*8))
;   #define LDB(dst,b,h) for(int n=0;n<2;++n)for(int k=0;k<2;++k) \
;     dst[n][k]=*reinterpret_cast<const bf16x8*>((char*)SB(b,h)+lds_byte(wc*32+n*16+fr,k*32+fq*8))
;   #define MMA(ai,bj,At,Bt_) do{__builtin_amdgcn_s_setprio(1); \
;     for(int m=0;m<4;++m)for(int n=0;n<2;++n)for(int k=0;k<2;++k) \
;       acc[ai][bj][m][n]=__builtin_amdgcn_mfma_f32_16x16x32_bf16(Bt_[n][k],At[m][k],acc[ai][bj][m][n],0,0,0); \
;     __builtin_amdgcn_s_setprio(0);}while(0)
;   #define WAIT_V(n) asm volatile("s_waitcnt vmcnt(" #n ")":::"memory")
;   #define WAIT_L(n) asm volatile("s_waitcnt lgkmcnt(" #n ")":::"memory")
;   #define BAR __builtin_amdgcn_s_barrier()
;   #define SCHED __builtin_amdgcn_sched_barrier(0)
; template <bool TWO, class MID> ...
;     ...
;     LDA(At,1,1); STAGE_A(SA(1,0),0,t+3);
;     BAR; WAIT_L(0); MMA(1,0,At,B0); BAR; SCHED;
;     STAGE_B(SB(1,1),1,t+3);
;     WAIT_V(6); BAR; MMA(1,1,At,B1); BAR;
;   }
;   { LDB(B0,0,0); LDA(At,0,0); STAGE_A(SA(1,1),1,nt-1);
;     BAR; WAIT_L(0); MMA(0,0,At,B0); BAR;
;     LDB(B1,0,1); BAR; WAIT_L(0); MMA(0,1,At,B1); BAR;
	s_setprio 0
	ds_read_b128 v[182:185], v141 offset:49152
	ds_read_b128 v[186:189], v141 offset:50176
	ds_read_b128 v[190:193], v139 offset:49152
	ds_read_b128 v[196:199], v139 offset:50176
	ds_read_b128 v[200:203], v137 offset:49152
	ds_read_b128 v[204:207], v137 offset:50176
	ds_read_b128 v[208:211], v135 offset:49152
	ds_read_b128 v[212:215], v135 offset:50176
	s_add_u32 s26, s15, 0x10000180
	s_addc_u32 s27, s18, 0
	v_lshl_add_u64 v[232:233], s[26:27], 0, v[132:133]
	v_readfirstlane_b32 s15, v140
	s_mov_b32 m0, s15
	global_load_lds_dwordx4 v[232:233], off
	v_lshl_add_u64 v[232:233], s[26:27], 0, v[130:131]
	v_readfirstlane_b32 s15, v142
	s_mov_b32 m0, s15
	global_load_lds_dwordx4 v[232:233], off
	s_setprio 1
	s_barrier
	s_waitcnt lgkmcnt(0)
	v_mfma_f32_16x16x32_bf16 v[62:65], v[166:169], v[182:185], v[62:65]
	v_mfma_f32_16x16x32_bf16 v[58:61], v[174:177], v[182:185], v[58:61]
	v_mfma_f32_16x16x32_bf16 v[54:57], v[166:169], v[190:193], v[54:57]
	v_mfma_f32_16x16x32_bf16 v[50:53], v[174:177], v[190:193], v[50:53]
	v_mfma_f32_16x16x32_bf16 v[46:49], v[166:169], v[200:203], v[46:49]
	v_mfma_f32_16x16x32_bf16 v[42:45], v[174:177], v[200:203], v[42:45]
	v_mfma_f32_16x16x32_bf16 v[38:41], v[166:169], v[208:211], v[38:41]
	v_mfma_f32_16x16x32_bf16 v[34:37], v[174:177], v[208:211], v[34:37]
	v_mfma_f32_16x16x32_bf16 v[62:65], v[170:173], v[186:189], v[62:65]
	v_mfma_f32_16x16x32_bf16 v[58:61], v[178:181], v[186:189], v[58:61]
	v_mfma_f32_16x16x32_bf16 v[54:57], v[170:173], v[196:199], v[54:57]
	v_mfma_f32_16x16x32_bf16 v[50:53], v[178:181], v[196:199], v[50:53]
	v_mfma_f32_16x16x32_bf16 v[46:49], v[170:173], v[204:207], v[46:49]
	v_mfma_f32_16x16x32_bf16 v[42:45], v[178:181], v[204:207], v[42:45]
	v_mfma_f32_16x16x32_bf16 v[38:41], v[170:173], v[212:215], v[38:41]
	v_mfma_f32_16x16x32_bf16 v[34:37], v[178:181], v[212:215], v[34:37]
	s_barrier
	s_setprio 0
	s_add_u32 s18, s19, 0x5e00180
	s_addc_u32 s19, s24, 0
	v_lshl_add_u64 v[166:167], s[18:19], 0, v[132:133]
	v_readfirstlane_b32 s15, v144
	s_mov_b32 m0, s15
	global_load_lds_dwordx4 v[166:167], off
	v_lshl_add_u64 v[166:167], s[18:19], 0, v[130:131]
	v_readfirstlane_b32 s15, v146
	s_mov_b32 m0, s15
	global_load_lds_dwordx4 v[166:167], off
	s_waitcnt vmcnt(6)
	s_setprio 1
	s_barrier
	v_mfma_f32_16x16x32_bf16 v[30:33], v[216:219], v[182:185], v[30:33]
	v_mfma_f32_16x16x32_bf16 v[26:29], v[224:227], v[182:185], v[26:29]
	v_mfma_f32_16x16x32_bf16 v[22:25], v[216:219], v[190:193], v[22:25]
	v_mfma_f32_16x16x32_bf16 v[18:21], v[224:227], v[190:193], v[18:21]
	v_mfma_f32_16x16x32_bf16 v[14:17], v[216:219], v[200:203], v[14:17]
	v_mfma_f32_16x16x32_bf16 v[10:13], v[224:227], v[200:203], v[10:13]
	v_mfma_f32_16x16x32_bf16 v[6:9], v[216:219], v[208:211], v[6:9]
	v_mfma_f32_16x16x32_bf16 v[2:5], v[224:227], v[208:211], v[2:5]
	v_mfma_f32_16x16x32_bf16 v[30:33], v[220:223], v[186:189], v[30:33]
	v_mfma_f32_16x16x32_bf16 v[26:29], v[228:231], v[186:189], v[26:29]
	v_mfma_f32_16x16x32_bf16 v[22:25], v[220:223], v[196:199], v[22:25]
	v_mfma_f32_16x16x32_bf16 v[18:21], v[228:231], v[196:199], v[18:21]
	v_mfma_f32_16x16x32_bf16 v[14:17], v[220:223], v[204:207], v[14:17]
	v_mfma_f32_16x16x32_bf16 v[10:13], v[228:231], v[204:207], v[10:13]
	v_mfma_f32_16x16x32_bf16 v[6:9], v[220:223], v[212:215], v[6:9]
	v_mfma_f32_16x16x32_bf16 v[2:5], v[228:231], v[212:215], v[2:5]
	s_setprio 0
	s_add_i32 s14, s14, 2
	s_add_u32 s0, s0, 0x100
	s_addc_u32 s1, s1, 0
	s_cmpk_lt_u32 s14, 0x7c
	s_barrier
	s_cbranch_scc1 .LBB0_620
	ds_read_b128 v[152:155], v149
	ds_read_b128 v[156:159], v149 offset:1024
	ds_read_b128 v[160:163], v149 offset:2048
	ds_read_b128 v[164:167], v149 offset:3072
	ds_read_b128 v[168:171], v141
	ds_read_b128 v[172:175], v141 offset:1024
	ds_read_b128 v[176:179], v139
	ds_read_b128 v[180:183], v139 offset:1024
	ds_read_b128 v[184:187], v137
	ds_read_b128 v[188:191], v137 offset:1024
	ds_read_b128 v[196:199], v135
	ds_read_b128 v[200:203], v135 offset:1024
	s_add_u32 s0, s12, 0x203f80
	s_addc_u32 s1, s13, 0
	v_lshl_add_u64 v[132:133], s[0:1], 0, v[132:133]
	v_readfirstlane_b32 s12, v148
	s_mov_b32 m0, s12
	global_load_lds_dwordx4 v[132:133], off
	v_lshl_add_u64 v[130:131], s[0:1], 0, v[130:131]
	v_readfirstlane_b32 s0, v150
	s_mov_b32 m0, s0
	global_load_lds_dwordx4 v[130:131], off
	s_setprio 1
	s_barrier
	s_waitcnt lgkmcnt(0)
	v_mfma_f32_16x16x32_bf16 v[126:129], v[152:155], v[168:171], v[126:129]
	v_mfma_f32_16x16x32_bf16 v[122:125], v[160:163], v[168:171], v[122:125]
	v_mfma_f32_16x16x32_bf16 v[118:121], v[152:155], v[176:179], v[118:121]
	v_mfma_f32_16x16x32_bf16 v[114:117], v[160:163], v[176:179], v[114:117]
	v_mfma_f32_16x16x32_bf16 v[102:105], v[152:155], v[196:199], v[102:105]
	v_mfma_f32_16x16x32_bf16 v[98:101], v[160:163], v[196:199], v[98:101]
	v_mfma_f32_16x16x32_bf16 v[126:129], v[156:159], v[172:175], v[126:129]
	v_mfma_f32_16x16x32_bf16 v[122:125], v[164:167], v[172:175], v[122:125]
	v_mfma_f32_16x16x32_bf16 v[118:121], v[156:159], v[180:183], v[118:121]
	v_mfma_f32_16x16x32_bf16 v[114:117], v[164:167], v[180:183], v[114:117]
	v_mfma_f32_16x16x32_bf16 v[110:113], v[152:155], v[184:187], v[110:113]
	v_mfma_f32_16x16x32_bf16 v[106:109], v[160:163], v[184:187], v[106:109]
	v_mfma_f32_16x16x32_bf16 v[102:105], v[156:159], v[200:203], v[102:105]
	v_mfma_f32_16x16x32_bf16 v[98:101], v[164:167], v[200:203], v[98:101]
	v_mfma_f32_16x16x32_bf16 v[130:133], v[156:159], v[188:191], v[110:113]
	v_mfma_f32_16x16x32_bf16 v[148:151], v[164:167], v[188:191], v[106:109]
	s_barrier
	s_setprio 0
	s_nop 0
	ds_read_b128 v[106:109], v147
	ds_read_b128 v[110:113], v147 offset:1024
	ds_read_b128 v[204:207], v147 offset:2048
	ds_read_b128 v[208:211], v147 offset:3072
	s_setprio 1
	s_barrier
;   #define LDA(dst,b,h) for(int m=0;m<4;++m)for(int k=0;k<2;++k) \
;     dst[m][k]=*reinterpret_cast<const bf16x8*>((char*)SA(b,h)+lds_byte(wr*64+m*16+fr,k*32+fq*8))
;   #define LDB(dst,b,h) for(int n=0;n<2;++n)for(int k=0;k<2;++k) \
;     dst[n][k]=*reinterpret_cast<const bf16x8*>((char*)SB(b,h)+lds_byte(wc*32+n*16+fr,k*32+fq*8))
;   #define MMA(ai,bj,At,Bt_) do{__builtin_amdgcn_s_setprio(1); \
;     for(int m=0;m<4;++m)for(int n=0;n<2;++n)for(int k=0;k<2;++k) \
;       acc[ai][bj][m][n]=__builtin_amdgcn_mfma_f32_16x16x32_bf16(Bt_[n][k],At[m][k],acc[ai][bj][m][n],0,0,0); \
;     __builtin_amdgcn_s_setprio(0);}while(0)
;   #define WAIT_V(n) asm volatile("s_waitcnt vmcnt(" #n ")":::"memory")
;   #define WAIT_L(n) asm volatile("s_waitcnt lgkmcnt(" #n ")":::"memory")
;   #define BAR __builtin_amdgcn_s_barrier()
; template <bool TWO, class MID> ...
;     ...
;     LDB(B1,0,1); BAR; WAIT_L(0); MMA(0,1,At,B1); BAR;
;     LDA(At,0,1); WAIT_V(4); BAR; WAIT_L(0); MMA(1,0,At,B0); MMA(1,1,At,B1); BAR; }
;   { LDB(B0,1,0); LDA(At,1,0); WAIT_V(2); BAR; WAIT_L(0); MMA(0,0,At,B0); BAR;
	s_waitcnt lgkmcnt(0)
	v_mfma_f32_16x16x32_bf16 v[86:89], v[106:109], v[176:179], v[86:89]
	v_mfma_f32_16x16x32_bf16 v[82:85], v[204:207], v[176:179], v[82:85]
	v_mfma_f32_16x16x32_bf16 v[70:73], v[106:109], v[196:199], v[70:73]
	v_mfma_f32_16x16x32_bf16 v[66:69], v[204:207], v[196:199], v[66:69]
	v_mfma_f32_16x16x32_bf16 v[94:97], v[106:109], v[168:171], v[94:97]
	v_mfma_f32_16x16x32_bf16 v[90:93], v[204:207], v[168:171], v[90:93]
	v_mfma_f32_16x16x32_bf16 v[86:89], v[110:113], v[180:183], v[86:89]
	v_mfma_f32_16x16x32_bf16 v[82:85], v[208:211], v[180:183], v[82:85]
	v_mfma_f32_16x16x32_bf16 v[78:81], v[106:109], v[184:187], v[78:81]
	v_mfma_f32_16x16x32_bf16 v[74:77], v[204:207], v[184:187], v[74:77]
	v_mfma_f32_16x16x32_bf16 v[70:73], v[110:113], v[200:203], v[70:73]
	v_mfma_f32_16x16x32_bf16 v[66:69], v[208:211], v[200:203], v[66:69]
	v_mfma_f32_16x16x32_bf16 v[212:215], v[110:113], v[172:175], v[94:97]
	v_mfma_f32_16x16x32_bf16 v[168:171], v[208:211], v[172:175], v[90:93]
	v_mfma_f32_16x16x32_bf16 v[172:175], v[110:113], v[188:191], v[78:81]
	v_mfma_f32_16x16x32_bf16 v[176:179], v[208:211], v[188:191], v[74:77]
	s_barrier
	s_setprio 0
	s_nop 0
	ds_read_b128 v[74:77], v141 offset:16384
	ds_read_b128 v[78:81], v141 offset:17408
	ds_read_b128 v[90:93], v139 offset:16384
	ds_read_b128 v[94:97], v139 offset:17408
	ds_read_b128 v[180:183], v137 offset:16384
	ds_read_b128 v[184:187], v137 offset:17408
	ds_read_b128 v[188:191], v135 offset:16384
	ds_read_b128 v[196:199], v135 offset:17408
	s_waitcnt vmcnt(4)
	s_setprio 1
	s_barrier
	s_waitcnt lgkmcnt(0)
	v_mfma_f32_16x16x32_bf16 v[62:65], v[152:155], v[74:77], v[62:65]
	v_mfma_f32_16x16x32_bf16 v[58:61], v[160:163], v[74:77], v[58:61]
	v_mfma_f32_16x16x32_bf16 v[54:57], v[152:155], v[90:93], v[54:57]
	v_mfma_f32_16x16x32_bf16 v[50:53], v[160:163], v[90:93], v[50:53]
	v_mfma_f32_16x16x32_bf16 v[38:41], v[152:155], v[188:191], v[38:41]
	v_mfma_f32_16x16x32_bf16 v[34:37], v[160:163], v[188:191], v[34:37]
	v_mfma_f32_16x16x32_bf16 v[62:65], v[156:159], v[78:81], v[62:65]
	v_mfma_f32_16x16x32_bf16 v[58:61], v[164:167], v[78:81], v[58:61]
	v_mfma_f32_16x16x32_bf16 v[54:57], v[156:159], v[94:97], v[54:57]
	v_mfma_f32_16x16x32_bf16 v[50:53], v[164:167], v[94:97], v[50:53]
	v_mfma_f32_16x16x32_bf16 v[46:49], v[152:155], v[180:183], v[46:49]
	v_mfma_f32_16x16x32_bf16 v[42:45], v[160:163], v[180:183], v[42:45]
	v_mfma_f32_16x16x32_bf16 v[38:41], v[156:159], v[196:199], v[38:41]
	v_mfma_f32_16x16x32_bf16 v[34:37], v[164:167], v[196:199], v[34:37]
	v_mfma_f32_16x16x32_bf16 v[200:203], v[156:159], v[184:187], v[46:49]
	v_mfma_f32_16x16x32_bf16 v[216:219], v[164:167], v[184:187], v[42:45]
	s_setprio 0
	s_setprio 1
	v_mfma_f32_16x16x32_bf16 v[22:25], v[106:109], v[90:93], v[22:25]
	v_mfma_f32_16x16x32_bf16 v[18:21], v[204:207], v[90:93], v[18:21]
	v_mfma_f32_16x16x32_bf16 v[6:9], v[106:109], v[188:191], v[6:9]
	v_mfma_f32_16x16x32_bf16 v[2:5], v[204:207], v[188:191], v[2:5]
	v_mfma_f32_16x16x32_bf16 v[30:33], v[106:109], v[74:77], v[30:33]
	v_mfma_f32_16x16x32_bf16 v[26:29], v[204:207], v[74:77], v[26:29]
	v_mfma_f32_16x16x32_bf16 v[22:25], v[110:113], v[94:97], v[22:25]
	v_mfma_f32_16x16x32_bf16 v[18:21], v[208:211], v[94:97], v[18:21]
	v_mfma_f32_16x16x32_bf16 v[14:17], v[106:109], v[180:183], v[14:17]
	v_mfma_f32_16x16x32_bf16 v[10:13], v[204:207], v[180:183], v[10:13]
	v_mfma_f32_16x16x32_bf16 v[6:9], v[110:113], v[196:199], v[6:9]
	v_mfma_f32_16x16x32_bf16 v[2:5], v[208:211], v[196:199], v[2:5]
	v_mfma_f32_16x16x32_bf16 v[152:155], v[110:113], v[78:81], v[30:33]
	v_mfma_f32_16x16x32_bf16 v[156:159], v[208:211], v[78:81], v[26:29]
	v_mfma_f32_16x16x32_bf16 v[160:163], v[110:113], v[184:187], v[14:17]
	v_mfma_f32_16x16x32_bf16 v[164:167], v[208:211], v[184:187], v[10:13]
	s_barrier
	s_setprio 0
	s_nop 0
	ds_read_b128 v[10:13], v145
	ds_read_b128 v[14:17], v145 offset:1024
	ds_read_b128 v[180:183], v145 offset:2048
	ds_read_b128 v[144:147], v145 offset:3072
	ds_read_b128 v[26:29], v141 offset:32768
	ds_read_b128 v[30:33], v141 offset:33792
	ds_read_b128 v[42:45], v139 offset:32768
	ds_read_b128 v[46:49], v139 offset:33792
	ds_read_b128 v[184:187], v137 offset:32768
	ds_read_b128 v[188:191], v137 offset:33792
	ds_read_b128 v[196:199], v135 offset:32768
	ds_read_b128 v[204:207], v135 offset:33792
	s_waitcnt vmcnt(2)
	s_setprio 1
	s_barrier
;   #define LDA(dst,b,h) for(int m=0;m<4;++m)for(int k=0;k<2;++k) \
;     dst[m][k]=*reinterpret_cast<const bf16x8*>((char*)SA(b,h)+lds_byte(wr*64+m*16+fr,k*32+fq*8))
;   #define LDB(dst,b,h) for(int n=0;n<2;++n)for(int k=0;k<2;++k) \
;     dst[n][k]=*reinterpret_cast<const bf16x8*>((char*)SB(b,h)+lds_byte(wc*32+n*16+fr,k*32+fq*8))
;   #define MMA(ai,bj,At,Bt_) do{__builtin_amdgcn_s_setprio(1); \
;     for(int m=0;m<4;++m)for(int n=0;n<2;++n)for(int k=0;k<2;++k) \
;       acc[ai][bj][m][n]=__builtin_amdgcn_mfma_f32_16x16x32_bf16(Bt_[n][k],At[m][k],acc[ai][bj][m][n],0,0,0); \
;     __builtin_amdgcn_s_setprio(0);}while(0)
;   #define WAIT_V(n) asm volatile("s_waitcnt vmcnt(" #n ")":::"memory")
;   #define WAIT_L(n) asm volatile("s_waitcnt lgkmcnt(" #n ")":::"memory")
;   #define BAR __builtin_amdgcn_s_barrier()
; template <bool TWO, class MID> ...
;     ...
;   { LDB(B0,1,0); LDA(At,1,0); WAIT_V(2); BAR; WAIT_L(0); MMA(0,0,At,B0); BAR;
;     LDB(B1,1,1); WAIT_V(0); BAR; WAIT_L(0); MMA(0,1,At,B1); BAR;
;     LDA(At,1,1); BAR; WAIT_L(0); MMA(1,0,At,B0); MMA(1,1,At,B1); BAR; }
;   if(wr==0)BAR;
	s_waitcnt lgkmcnt(0)
	v_mfma_f32_16x16x32_bf16 v[74:77], v[10:13], v[26:29], v[126:129]
	v_mfma_f32_16x16x32_bf16 v[126:129], v[14:17], v[30:33], v[74:77]
	v_mfma_f32_16x16x32_bf16 v[74:77], v[180:183], v[26:29], v[122:125]
	v_mfma_f32_16x16x32_bf16 v[122:125], v[144:147], v[30:33], v[74:77]
	v_mfma_f32_16x16x32_bf16 v[74:77], v[10:13], v[42:45], v[118:121]
	v_mfma_f32_16x16x32_bf16 v[110:113], v[14:17], v[46:49], v[74:77]
	v_mfma_f32_16x16x32_bf16 v[74:77], v[180:183], v[42:45], v[114:117]
	v_mfma_f32_16x16x32_bf16 v[106:109], v[144:147], v[46:49], v[74:77]
	v_mfma_f32_16x16x32_bf16 v[74:77], v[10:13], v[184:187], v[130:133]
	v_mfma_f32_16x16x32_bf16 v[94:97], v[14:17], v[188:191], v[74:77]
	v_mfma_f32_16x16x32_bf16 v[74:77], v[180:183], v[184:187], v[148:151]
	v_mfma_f32_16x16x32_bf16 v[90:93], v[144:147], v[188:191], v[74:77]
	v_mfma_f32_16x16x32_bf16 v[74:77], v[10:13], v[196:199], v[102:105]
	v_mfma_f32_16x16x32_bf16 v[78:81], v[14:17], v[204:207], v[74:77]
	v_mfma_f32_16x16x32_bf16 v[74:77], v[180:183], v[196:199], v[98:101]
	v_mfma_f32_16x16x32_bf16 v[74:77], v[144:147], v[204:207], v[74:77]
	s_barrier
	s_setprio 0
	ds_read_b128 v[130:133], v143
	ds_read_b128 v[148:151], v143 offset:1024
	ds_read_b128 v[208:211], v143 offset:2048
	ds_read_b128 v[220:223], v143 offset:3072
	s_waitcnt vmcnt(0)
	s_setprio 1
	s_barrier
	s_waitcnt lgkmcnt(0)
	v_mfma_f32_16x16x32_bf16 v[98:101], v[130:133], v[26:29], v[212:215]
	v_mfma_f32_16x16x32_bf16 v[26:29], v[208:211], v[26:29], v[168:171]
	v_mfma_f32_16x16x32_bf16 v[114:117], v[220:223], v[30:33], v[26:29]
	v_mfma_f32_16x16x32_bf16 v[26:29], v[130:133], v[42:45], v[86:89]
	v_mfma_f32_16x16x32_bf16 v[102:105], v[148:151], v[46:49], v[26:29]
	v_mfma_f32_16x16x32_bf16 v[26:29], v[208:211], v[42:45], v[82:85]
	v_mfma_f32_16x16x32_bf16 v[118:121], v[148:151], v[30:33], v[98:101]
	v_mfma_f32_16x16x32_bf16 v[98:101], v[220:223], v[46:49], v[26:29]
	v_mfma_f32_16x16x32_bf16 v[26:29], v[130:133], v[184:187], v[172:175]
	v_mfma_f32_16x16x32_bf16 v[86:89], v[148:151], v[188:191], v[26:29]
	v_mfma_f32_16x16x32_bf16 v[26:29], v[208:211], v[184:187], v[176:179]
	v_mfma_f32_16x16x32_bf16 v[82:85], v[220:223], v[188:191], v[26:29]
	v_mfma_f32_16x16x32_bf16 v[26:29], v[130:133], v[196:199], v[70:73]
	v_mfma_f32_16x16x32_bf16 v[70:73], v[148:151], v[204:207], v[26:29]
	v_mfma_f32_16x16x32_bf16 v[26:29], v[208:211], v[196:199], v[66:69]
	v_mfma_f32_16x16x32_bf16 v[66:69], v[220:223], v[204:207], v[26:29]
	s_barrier
	s_setprio 0
	ds_read_b128 v[168:171], v141 offset:49152
	ds_read_b128 v[140:143], v141 offset:50176
	ds_read_b128 v[172:175], v139 offset:49152
	ds_read_b128 v[176:179], v139 offset:50176
	ds_read_b128 v[184:187], v137 offset:49152
	ds_read_b128 v[136:139], v137 offset:50176
	ds_read_b128 v[188:191], v135 offset:49152
	ds_read_b128 v[196:199], v135 offset:50176
	s_setprio 1
	s_barrier
	s_waitcnt lgkmcnt(0)
	v_mfma_f32_16x16x32_bf16 v[26:29], v[10:13], v[168:171], v[62:65]
	v_mfma_f32_16x16x32_bf16 v[62:65], v[14:17], v[140:143], v[26:29]
	v_mfma_f32_16x16x32_bf16 v[26:29], v[180:183], v[168:171], v[58:61]
	v_mfma_f32_16x16x32_bf16 v[58:61], v[144:147], v[140:143], v[26:29]
	v_mfma_f32_16x16x32_bf16 v[26:29], v[10:13], v[172:175], v[54:57]
	v_mfma_f32_16x16x32_bf16 v[46:49], v[14:17], v[176:179], v[26:29]
	v_mfma_f32_16x16x32_bf16 v[26:29], v[180:183], v[172:175], v[50:53]
	v_mfma_f32_16x16x32_bf16 v[42:45], v[144:147], v[176:179], v[26:29]
	v_mfma_f32_16x16x32_bf16 v[26:29], v[10:13], v[184:187], v[200:203]
	v_mfma_f32_16x16x32_bf16 v[10:13], v[10:13], v[188:191], v[38:41]
	v_mfma_f32_16x16x32_bf16 v[30:33], v[14:17], v[136:139], v[26:29]
	v_mfma_f32_16x16x32_bf16 v[26:29], v[180:183], v[184:187], v[216:219]
	v_mfma_f32_16x16x32_bf16 v[14:17], v[14:17], v[196:199], v[10:13]
	v_mfma_f32_16x16x32_bf16 v[10:13], v[180:183], v[188:191], v[34:37]
	v_mfma_f32_16x16x32_bf16 v[26:29], v[144:147], v[136:139], v[26:29]
	v_mfma_f32_16x16x32_bf16 v[10:13], v[144:147], v[196:199], v[10:13]
	s_setprio 0
	s_setprio 1
	v_mfma_f32_16x16x32_bf16 v[34:37], v[130:133], v[168:171], v[152:155]
	v_mfma_f32_16x16x32_bf16 v[54:57], v[148:151], v[140:143], v[34:37]
	v_mfma_f32_16x16x32_bf16 v[34:37], v[208:211], v[168:171], v[156:159]
	v_mfma_f32_16x16x32_bf16 v[18:21], v[208:211], v[172:175], v[18:21]
	v_mfma_f32_16x16x32_bf16 v[50:53], v[220:223], v[140:143], v[34:37]
	v_mfma_f32_16x16x32_bf16 v[22:25], v[130:133], v[172:175], v[22:25]
	v_mfma_f32_16x16x32_bf16 v[34:37], v[220:223], v[176:179], v[18:21]
	v_mfma_f32_16x16x32_bf16 v[18:21], v[130:133], v[184:187], v[160:163]
	v_mfma_f32_16x16x32_bf16 v[38:41], v[148:151], v[176:179], v[22:25]
	v_mfma_f32_16x16x32_bf16 v[22:25], v[148:151], v[136:139], v[18:21]
	v_mfma_f32_16x16x32_bf16 v[18:21], v[208:211], v[184:187], v[164:167]
	v_mfma_f32_16x16x32_bf16 v[6:9], v[130:133], v[188:191], v[6:9]
	v_mfma_f32_16x16x32_bf16 v[2:5], v[208:211], v[188:191], v[2:5]
	v_mfma_f32_16x16x32_bf16 v[18:21], v[220:223], v[136:139], v[18:21]
	v_mfma_f32_16x16x32_bf16 v[6:9], v[148:151], v[196:199], v[6:9]
	v_mfma_f32_16x16x32_bf16 v[2:5], v[220:223], v[196:199], v[2:5]
	s_setprio 0
	v_cmp_gt_u32_e32 vcc, s30, v1
	s_barrier
	s_and_saveexec_b64 s[0:1], vcc
	s_cbranch_execz .LBB0_623
	s_barrier
